# prologue: adaLN GEMV loads batched+prefetched (silu staging 16 in flight, weight rows 8-row double-buffered), posb dot loop 16 loads in flight; plus conv tap batching
# speedup vs baseline: 1.0030x; 1.0030x over previous
; DI int TIDX() { int t = (int)threadIdx.x; asm volatile("" : "+v"(t)); return t; }
; DI void posb_item(const KP& p, int kv, float* lds) {
;   const int tid = TIDX(); const float* pos = p.in[kv ? 18 : 17]; const float* w1 = p.in[kv ? 21 : 19];
;   const int e = tid & 63, seg = tid >> 6; float s = 0.f;
;   for (int f = seg * 256; f < seg * 256 + 256; ++f) s += pos[f] * w1[(size_t)f * 64 + e];
;   lds[seg * 64 + e] = s; __syncthreads();
;   if (tid < 64) { float t = 0.f; for (int g = 0; g < 8; ++g) t += lds[g * 64 + tid]; ((float*)(p.ws + WS_POSB))[kv * 64 + tid] = t; }
;   __syncthreads();
.LBB0_14:
	s_cmpk_gt_i32 s15, 0x17f
	s_mov_b64 s[4:5], -1
	s_cbranch_scc0 .LBB0_20
	s_add_i32 s8, s15, 0xfffffe80
	s_cmp_eq_u32 s8, 0
	s_movk_i32 s4, 0x88
	s_cselect_b32 s4, s4, 0x90
	s_movk_i32 s5, 0x98
	s_cselect_b32 s9, s5, 0xa8
	s_add_u32 s4, s0, s4
	s_addc_u32 s5, s1, 0
	s_add_u32 s10, s0, s9
	v_mov_b32_e32 v4, v185
	s_addc_u32 s11, s1, 0
	s_load_dwordx2 s[4:5], s[4:5], 0x0
	s_nop 0
	s_load_dwordx2 s[10:11], s[10:11], 0x0
	v_lshlrev_b32_e32 v0, 2, v4
	v_and_b32_e32 v2, 0xffffff00, v0
	v_ashrrev_i32_e32 v3, 31, v2
	v_and_b32_e32 v7, 63, v4
	v_or_b32_e32 v5, 0xff, v0
	v_lshlrev_b64 v[0:1], 8, v[2:3]
	v_lshl_or_b32 v0, v7, 2, v0
	v_add_u32_e32 v6, -1, v2
	s_waitcnt lgkmcnt(0)
	v_lshl_add_u64 v[0:1], s[10:11], 0, v[0:1]
	v_lshl_add_u64 v[2:3], v[2:3], 2, s[4:5]
	v_mov_b32_e32 v7, 0
	s_mov_b64 s[4:5], 0
	s_mov_b64 s[10:11], 0x800
	s_movk_i32 s9, 32
.Lposb_loop:
	global_load_dword v10, v[2:3], off
	global_load_dword v11, v[0:1], off
	global_load_dword v12, v[2:3], off offset:4
	global_load_dword v13, v[0:1], off offset:256
	global_load_dword v14, v[2:3], off offset:8
	global_load_dword v15, v[0:1], off offset:512
	global_load_dword v16, v[2:3], off offset:12
	global_load_dword v17, v[0:1], off offset:768
	global_load_dword v18, v[2:3], off offset:16
	global_load_dword v19, v[0:1], off offset:1024
	global_load_dword v20, v[2:3], off offset:20
	global_load_dword v21, v[0:1], off offset:1280
	global_load_dword v22, v[2:3], off offset:24
	global_load_dword v23, v[0:1], off offset:1536
	global_load_dword v24, v[2:3], off offset:28
	global_load_dword v25, v[0:1], off offset:1792
	v_lshl_add_u64 v[0:1], v[0:1], 0, s[10:11]
	v_lshl_add_u64 v[2:3], v[2:3], 0, 32
	s_waitcnt vmcnt(14)
	v_fmac_f32_e32 v7, v10, v11
	s_waitcnt vmcnt(12)
	v_fmac_f32_e32 v7, v12, v13
	s_waitcnt vmcnt(10)
	v_fmac_f32_e32 v7, v14, v15
	s_waitcnt vmcnt(8)
	v_fmac_f32_e32 v7, v16, v17
	s_waitcnt vmcnt(6)
	v_fmac_f32_e32 v7, v18, v19
	s_waitcnt vmcnt(4)
	v_fmac_f32_e32 v7, v20, v21
	s_waitcnt vmcnt(2)
	v_fmac_f32_e32 v7, v22, v23
	s_waitcnt vmcnt(0)
	v_fmac_f32_e32 v7, v24, v25
	s_add_i32 s9, s9, -1
	s_cmp_lg_u32 s9, 0
	s_cbranch_scc1 .Lposb_loop
	s_or_b64 exec, exec, s[4:5]
	v_lshl_add_u32 v0, v4, 2, 32
	v_cmp_gt_i32_e32 vcc, 64, v4
	ds_write_b32 v0, v7
	s_waitcnt lgkmcnt(0)
	s_barrier
	s_and_saveexec_b64 s[4:5], vcc
	s_cbranch_execz .LBB0_19
	ds_read2st64_b32 v[2:3], v0 offset1:1
	ds_read2st64_b32 v[6:7], v0 offset0:2 offset1:3
	ds_read2st64_b32 v[8:9], v0 offset0:4 offset1:5
	ds_read2st64_b32 v[0:1], v0 offset0:6 offset1:7
	v_lshl_add_u32 v4, s8, 6, v4
	s_waitcnt lgkmcnt(3)
	v_add_f32_e32 v2, 0, v2
	v_add_f32_e32 v2, v2, v3
	s_waitcnt lgkmcnt(2)
	v_add_f32_e32 v2, v2, v6
	v_add_f32_e32 v2, v2, v7
	s_waitcnt lgkmcnt(1)
	v_add_f32_e32 v2, v2, v8
	v_add_f32_e32 v2, v2, v9
	s_waitcnt lgkmcnt(0)
	v_add_f32_e32 v0, v2, v0
	v_ashrrev_i32_e32 v5, 31, v4
	v_add_f32_e32 v2, v0, v1
	v_lshl_add_u64 v[0:1], v[4:5], 2, s[2:3]
	global_store_dword v[0:1], v2, off

; DI float siluf(float x) { return x / (1.f + __expf(-x)); }
; DI void ada_item(const KP& p, int item, float* lds) {
;     ...
;   for (int i = tid; i < 32768; i += 512) { const int d = i >> 4, b = i & 15; lds[i] = siluf(c[b * 2048 + d]); }
.LBB0_20:
	s_and_b64 vcc, exec, s[4:5]
	s_cbranch_vccz .LBB0_13
	s_mul_hi_i32 s4, s15, 0x2aaaaaab
	s_lshr_b32 s5, s4, 31
	s_ashr_i32 s18, s4, 4
	s_add_i32 s18, s18, s5
	s_bitcmp0_b32 s18, 0
	s_cselect_b32 s4, 24, 48
	s_cselect_b32 s8, 32, 56
	s_add_u32 s4, s0, s4
	s_addc_u32 s5, s1, 0
	v_mov_b32_e32 v105, v185
	s_add_u32 s8, s0, s8
	s_movk_i32 s10, 0x7fff
	s_addc_u32 s9, s1, 0
	v_cmp_lt_i32_e32 vcc, s10, v105
	v_lshlrev_b32_e32 v0, 2, v105
	s_and_saveexec_b64 s[10:11], vcc
	s_xor_b64 s[10:11], exec, s[10:11]
	v_lshlrev_b32_e32 v0, 2, v105
	s_or_saveexec_b64 s[10:11], s[10:11]
	s_load_dwordx2 s[4:5], s[4:5], 0x0
	s_nop 0
	s_load_dwordx2 s[8:9], s[8:9], 0x0
	s_xor_b64 exec, exec, s[10:11]
	s_cbranch_execz .LBB0_27
	s_load_dwordx2 s[22:23], s[0:1], 0x8
	v_add_u32_e32 v1, 32, v0
	v_and_b32_e32 v2, 15, v105
	v_lshlrev_b32_e32 v2, 11, v2
	v_lshrrev_b32_e32 v3, 4, v105
	v_add_u32_e32 v2, v2, v3
	v_lshlrev_b32_e32 v2, 2, v2
	s_waitcnt lgkmcnt(0)
	global_load_dword v12, v2, s[22:23]
	global_load_dword v13, v2, s[22:23] offset:128
	global_load_dword v14, v2, s[22:23] offset:256
	global_load_dword v15, v2, s[22:23] offset:384
	global_load_dword v16, v2, s[22:23] offset:512
	global_load_dword v17, v2, s[22:23] offset:640
	global_load_dword v18, v2, s[22:23] offset:768
	global_load_dword v19, v2, s[22:23] offset:896
	global_load_dword v20, v2, s[22:23] offset:1024
	global_load_dword v21, v2, s[22:23] offset:1152
	global_load_dword v22, v2, s[22:23] offset:1280
	global_load_dword v23, v2, s[22:23] offset:1408
	global_load_dword v24, v2, s[22:23] offset:1536
	global_load_dword v25, v2, s[22:23] offset:1664
	global_load_dword v26, v2, s[22:23] offset:1792
	global_load_dword v27, v2, s[22:23] offset:1920
	s_waitcnt vmcnt(15)
	v_mov_b32_e32 v4, v12
	v_mul_f32_e32 v5, 0xbfb8aa3b, v4
	v_exp_f32_e32 v5, v5
	s_nop 0
	v_add_f32_e32 v5, 1.0, v5
	v_div_scale_f32 v6, s[20:21], v5, v5, v4
	v_rcp_f32_e32 v7, v6
	v_div_scale_f32 v8, vcc, v4, v5, v4
	v_fma_f32 v9, -v6, v7, 1.0
	v_fmac_f32_e32 v7, v9, v7
	v_mul_f32_e32 v9, v8, v7
	v_fma_f32 v10, -v6, v9, v8
	v_fmac_f32_e32 v9, v10, v7
	v_fma_f32 v6, -v6, v9, v8
	v_div_fmas_f32 v6, v6, v7, v9
	v_div_fixup_f32 v4, v6, v5, v4
	ds_write_b32 v1, v4
	s_waitcnt vmcnt(14)
	v_mov_b32_e32 v4, v13
	v_mul_f32_e32 v5, 0xbfb8aa3b, v4
	v_exp_f32_e32 v5, v5
	s_nop 0
	v_add_f32_e32 v5, 1.0, v5
	v_div_scale_f32 v6, s[20:21], v5, v5, v4
	v_rcp_f32_e32 v7, v6
	v_div_scale_f32 v8, vcc, v4, v5, v4
	v_fma_f32 v9, -v6, v7, 1.0
	v_fmac_f32_e32 v7, v9, v7
	v_mul_f32_e32 v9, v8, v7
	v_fma_f32 v10, -v6, v9, v8
	v_fmac_f32_e32 v9, v10, v7
	v_fma_f32 v6, -v6, v9, v8
	v_div_fmas_f32 v6, v6, v7, v9
	v_div_fixup_f32 v4, v6, v5, v4
	ds_write_b32 v1, v4 offset:2048
	s_waitcnt vmcnt(13)
	v_mov_b32_e32 v4, v14
	v_mul_f32_e32 v5, 0xbfb8aa3b, v4
	v_exp_f32_e32 v5, v5
	s_nop 0
	v_add_f32_e32 v5, 1.0, v5
	v_div_scale_f32 v6, s[20:21], v5, v5, v4
	v_rcp_f32_e32 v7, v6
	v_div_scale_f32 v8, vcc, v4, v5, v4
	v_fma_f32 v9, -v6, v7, 1.0
	v_fmac_f32_e32 v7, v9, v7
	v_mul_f32_e32 v9, v8, v7
	v_fma_f32 v10, -v6, v9, v8
	v_fmac_f32_e32 v9, v10, v7
	v_fma_f32 v6, -v6, v9, v8
	v_div_fmas_f32 v6, v6, v7, v9
	v_div_fixup_f32 v4, v6, v5, v4
	ds_write_b32 v1, v4 offset:4096
	s_waitcnt vmcnt(12)
	v_mov_b32_e32 v4, v15
	v_mul_f32_e32 v5, 0xbfb8aa3b, v4
	v_exp_f32_e32 v5, v5
	s_nop 0
	v_add_f32_e32 v5, 1.0, v5
	v_div_scale_f32 v6, s[20:21], v5, v5, v4
	v_rcp_f32_e32 v7, v6
	v_div_scale_f32 v8, vcc, v4, v5, v4
	v_fma_f32 v9, -v6, v7, 1.0
	v_fmac_f32_e32 v7, v9, v7
	v_mul_f32_e32 v9, v8, v7
	v_fma_f32 v10, -v6, v9, v8
	v_fmac_f32_e32 v9, v10, v7
	v_fma_f32 v6, -v6, v9, v8
	v_div_fmas_f32 v6, v6, v7, v9
	v_div_fixup_f32 v4, v6, v5, v4
	ds_write_b32 v1, v4 offset:6144
	s_waitcnt vmcnt(11)
	v_mov_b32_e32 v4, v16
	v_mul_f32_e32 v5, 0xbfb8aa3b, v4
	v_exp_f32_e32 v5, v5
	s_nop 0
	v_add_f32_e32 v5, 1.0, v5
	v_div_scale_f32 v6, s[20:21], v5, v5, v4
	v_rcp_f32_e32 v7, v6
	v_div_scale_f32 v8, vcc, v4, v5, v4
	v_fma_f32 v9, -v6, v7, 1.0
	v_fmac_f32_e32 v7, v9, v7
	v_mul_f32_e32 v9, v8, v7
	v_fma_f32 v10, -v6, v9, v8
	v_fmac_f32_e32 v9, v10, v7
	v_fma_f32 v6, -v6, v9, v8
	v_div_fmas_f32 v6, v6, v7, v9
	v_div_fixup_f32 v4, v6, v5, v4
	ds_write_b32 v1, v4 offset:8192
	s_waitcnt vmcnt(10)
	v_mov_b32_e32 v4, v17
	v_mul_f32_e32 v5, 0xbfb8aa3b, v4
	v_exp_f32_e32 v5, v5
	s_nop 0
	v_add_f32_e32 v5, 1.0, v5
	v_div_scale_f32 v6, s[20:21], v5, v5, v4
	v_rcp_f32_e32 v7, v6
	v_div_scale_f32 v8, vcc, v4, v5, v4
	v_fma_f32 v9, -v6, v7, 1.0
	v_fmac_f32_e32 v7, v9, v7
	v_mul_f32_e32 v9, v8, v7
	v_fma_f32 v10, -v6, v9, v8
	v_fmac_f32_e32 v9, v10, v7
	v_fma_f32 v6, -v6, v9, v8
	v_div_fmas_f32 v6, v6, v7, v9
	v_div_fixup_f32 v4, v6, v5, v4
	ds_write_b32 v1, v4 offset:10240
	s_waitcnt vmcnt(9)
	v_mov_b32_e32 v4, v18
	v_mul_f32_e32 v5, 0xbfb8aa3b, v4
	v_exp_f32_e32 v5, v5
	s_nop 0
	v_add_f32_e32 v5, 1.0, v5
	v_div_scale_f32 v6, s[20:21], v5, v5, v4
	v_rcp_f32_e32 v7, v6
	v_div_scale_f32 v8, vcc, v4, v5, v4
	v_fma_f32 v9, -v6, v7, 1.0
	v_fmac_f32_e32 v7, v9, v7
	v_mul_f32_e32 v9, v8, v7
	v_fma_f32 v10, -v6, v9, v8
	v_fmac_f32_e32 v9, v10, v7
	v_fma_f32 v6, -v6, v9, v8
	v_div_fmas_f32 v6, v6, v7, v9
	v_div_fixup_f32 v4, v6, v5, v4
	ds_write_b32 v1, v4 offset:12288
	s_waitcnt vmcnt(8)
	v_mov_b32_e32 v4, v19
	v_mul_f32_e32 v5, 0xbfb8aa3b, v4
	v_exp_f32_e32 v5, v5
	s_nop 0
	v_add_f32_e32 v5, 1.0, v5
	v_div_scale_f32 v6, s[20:21], v5, v5, v4
	v_rcp_f32_e32 v7, v6
	v_div_scale_f32 v8, vcc, v4, v5, v4
	v_fma_f32 v9, -v6, v7, 1.0
	v_fmac_f32_e32 v7, v9, v7
	v_mul_f32_e32 v9, v8, v7
	v_fma_f32 v10, -v6, v9, v8
	v_fmac_f32_e32 v9, v10, v7
	v_fma_f32 v6, -v6, v9, v8
	v_div_fmas_f32 v6, v6, v7, v9
	v_div_fixup_f32 v4, v6, v5, v4
	ds_write_b32 v1, v4 offset:14336
	s_waitcnt vmcnt(7)
; DI float siluf(float x) { return x / (1.f + __expf(-x)); }
; DI void ada_item(const KP& p, int item, float* lds) {
;     ...
;   for (int i = tid; i < 32768; i += 512) { const int d = i >> 4, b = i & 15; lds[i] = siluf(c[b * 2048 + d]); }
	v_mov_b32_e32 v4, v20
	v_mul_f32_e32 v5, 0xbfb8aa3b, v4
	v_exp_f32_e32 v5, v5
	s_nop 0
	v_add_f32_e32 v5, 1.0, v5
	v_div_scale_f32 v6, s[20:21], v5, v5, v4
	v_rcp_f32_e32 v7, v6
	v_div_scale_f32 v8, vcc, v4, v5, v4
	v_fma_f32 v9, -v6, v7, 1.0
	v_fmac_f32_e32 v7, v9, v7
	v_mul_f32_e32 v9, v8, v7
	v_fma_f32 v10, -v6, v9, v8
	v_fmac_f32_e32 v9, v10, v7
	v_fma_f32 v6, -v6, v9, v8
	v_div_fmas_f32 v6, v6, v7, v9
	v_div_fixup_f32 v4, v6, v5, v4
	ds_write_b32 v1, v4 offset:16384
	s_waitcnt vmcnt(6)
	v_mov_b32_e32 v4, v21
	v_mul_f32_e32 v5, 0xbfb8aa3b, v4
	v_exp_f32_e32 v5, v5
	s_nop 0
	v_add_f32_e32 v5, 1.0, v5
	v_div_scale_f32 v6, s[20:21], v5, v5, v4
	v_rcp_f32_e32 v7, v6
	v_div_scale_f32 v8, vcc, v4, v5, v4
	v_fma_f32 v9, -v6, v7, 1.0
	v_fmac_f32_e32 v7, v9, v7
	v_mul_f32_e32 v9, v8, v7
	v_fma_f32 v10, -v6, v9, v8
	v_fmac_f32_e32 v9, v10, v7
	v_fma_f32 v6, -v6, v9, v8
	v_div_fmas_f32 v6, v6, v7, v9
	v_div_fixup_f32 v4, v6, v5, v4
	ds_write_b32 v1, v4 offset:18432
	s_waitcnt vmcnt(5)
	v_mov_b32_e32 v4, v22
	v_mul_f32_e32 v5, 0xbfb8aa3b, v4
	v_exp_f32_e32 v5, v5
	s_nop 0
	v_add_f32_e32 v5, 1.0, v5
	v_div_scale_f32 v6, s[20:21], v5, v5, v4
	v_rcp_f32_e32 v7, v6
	v_div_scale_f32 v8, vcc, v4, v5, v4
	v_fma_f32 v9, -v6, v7, 1.0
	v_fmac_f32_e32 v7, v9, v7
	v_mul_f32_e32 v9, v8, v7
	v_fma_f32 v10, -v6, v9, v8
	v_fmac_f32_e32 v9, v10, v7
	v_fma_f32 v6, -v6, v9, v8
	v_div_fmas_f32 v6, v6, v7, v9
	v_div_fixup_f32 v4, v6, v5, v4
	ds_write_b32 v1, v4 offset:20480
	s_waitcnt vmcnt(4)
	v_mov_b32_e32 v4, v23
	v_mul_f32_e32 v5, 0xbfb8aa3b, v4
	v_exp_f32_e32 v5, v5
	s_nop 0
	v_add_f32_e32 v5, 1.0, v5
	v_div_scale_f32 v6, s[20:21], v5, v5, v4
	v_rcp_f32_e32 v7, v6
	v_div_scale_f32 v8, vcc, v4, v5, v4
	v_fma_f32 v9, -v6, v7, 1.0
	v_fmac_f32_e32 v7, v9, v7
	v_mul_f32_e32 v9, v8, v7
	v_fma_f32 v10, -v6, v9, v8
	v_fmac_f32_e32 v9, v10, v7
	v_fma_f32 v6, -v6, v9, v8
	v_div_fmas_f32 v6, v6, v7, v9
	v_div_fixup_f32 v4, v6, v5, v4
	ds_write_b32 v1, v4 offset:22528
	s_waitcnt vmcnt(3)
	v_mov_b32_e32 v4, v24
	v_mul_f32_e32 v5, 0xbfb8aa3b, v4
	v_exp_f32_e32 v5, v5
	s_nop 0
	v_add_f32_e32 v5, 1.0, v5
	v_div_scale_f32 v6, s[20:21], v5, v5, v4
	v_rcp_f32_e32 v7, v6
	v_div_scale_f32 v8, vcc, v4, v5, v4
	v_fma_f32 v9, -v6, v7, 1.0
	v_fmac_f32_e32 v7, v9, v7
	v_mul_f32_e32 v9, v8, v7
	v_fma_f32 v10, -v6, v9, v8
	v_fmac_f32_e32 v9, v10, v7
	v_fma_f32 v6, -v6, v9, v8
	v_div_fmas_f32 v6, v6, v7, v9
	v_div_fixup_f32 v4, v6, v5, v4
	ds_write_b32 v1, v4 offset:24576
	s_waitcnt vmcnt(2)
	v_mov_b32_e32 v4, v25
	v_mul_f32_e32 v5, 0xbfb8aa3b, v4
	v_exp_f32_e32 v5, v5
	s_nop 0
	v_add_f32_e32 v5, 1.0, v5
	v_div_scale_f32 v6, s[20:21], v5, v5, v4
	v_rcp_f32_e32 v7, v6
	v_div_scale_f32 v8, vcc, v4, v5, v4
	v_fma_f32 v9, -v6, v7, 1.0
	v_fmac_f32_e32 v7, v9, v7
	v_mul_f32_e32 v9, v8, v7
	v_fma_f32 v10, -v6, v9, v8
	v_fmac_f32_e32 v9, v10, v7
	v_fma_f32 v6, -v6, v9, v8
	v_div_fmas_f32 v6, v6, v7, v9
	v_div_fixup_f32 v4, v6, v5, v4
	ds_write_b32 v1, v4 offset:26624
	s_waitcnt vmcnt(1)
	v_mov_b32_e32 v4, v26
	v_mul_f32_e32 v5, 0xbfb8aa3b, v4
	v_exp_f32_e32 v5, v5
	s_nop 0
	v_add_f32_e32 v5, 1.0, v5
	v_div_scale_f32 v6, s[20:21], v5, v5, v4
	v_rcp_f32_e32 v7, v6
	v_div_scale_f32 v8, vcc, v4, v5, v4
	v_fma_f32 v9, -v6, v7, 1.0
	v_fmac_f32_e32 v7, v9, v7
	v_mul_f32_e32 v9, v8, v7
	v_fma_f32 v10, -v6, v9, v8
	v_fmac_f32_e32 v9, v10, v7
	v_fma_f32 v6, -v6, v9, v8
	v_div_fmas_f32 v6, v6, v7, v9
	v_div_fixup_f32 v4, v6, v5, v4
	ds_write_b32 v1, v4 offset:28672
	s_waitcnt vmcnt(0)
	v_mov_b32_e32 v4, v27
	v_mul_f32_e32 v5, 0xbfb8aa3b, v4
	v_exp_f32_e32 v5, v5
	s_nop 0
	v_add_f32_e32 v5, 1.0, v5
	v_div_scale_f32 v6, s[20:21], v5, v5, v4
	v_rcp_f32_e32 v7, v6
	v_div_scale_f32 v8, vcc, v4, v5, v4
	v_fma_f32 v9, -v6, v7, 1.0
	v_fmac_f32_e32 v7, v9, v7
	v_mul_f32_e32 v9, v8, v7
	v_fma_f32 v10, -v6, v9, v8
	v_fmac_f32_e32 v9, v10, v7
	v_fma_f32 v6, -v6, v9, v8
	v_div_fmas_f32 v6, v6, v7, v9
	v_div_fixup_f32 v4, v6, v5, v4
	ds_write_b32 v1, v4 offset:30720
	global_load_dword v12, v2, s[22:23] offset:2048
	global_load_dword v13, v2, s[22:23] offset:2176
	global_load_dword v14, v2, s[22:23] offset:2304
	global_load_dword v15, v2, s[22:23] offset:2432
	global_load_dword v16, v2, s[22:23] offset:2560
	global_load_dword v17, v2, s[22:23] offset:2688
	global_load_dword v18, v2, s[22:23] offset:2816
	global_load_dword v19, v2, s[22:23] offset:2944
	global_load_dword v20, v2, s[22:23] offset:3072
	global_load_dword v21, v2, s[22:23] offset:3200
	global_load_dword v22, v2, s[22:23] offset:3328
	global_load_dword v23, v2, s[22:23] offset:3456
	global_load_dword v24, v2, s[22:23] offset:3584
	global_load_dword v25, v2, s[22:23] offset:3712
	global_load_dword v26, v2, s[22:23] offset:3840
	global_load_dword v27, v2, s[22:23] offset:3968
	s_waitcnt vmcnt(15)
	v_mov_b32_e32 v4, v12
	v_mul_f32_e32 v5, 0xbfb8aa3b, v4
	v_exp_f32_e32 v5, v5
	s_nop 0
	v_add_f32_e32 v5, 1.0, v5
	v_div_scale_f32 v6, s[20:21], v5, v5, v4
	v_rcp_f32_e32 v7, v6
	v_div_scale_f32 v8, vcc, v4, v5, v4
	v_fma_f32 v9, -v6, v7, 1.0
	v_fmac_f32_e32 v7, v9, v7
	v_mul_f32_e32 v9, v8, v7
	v_fma_f32 v10, -v6, v9, v8
	v_fmac_f32_e32 v9, v10, v7
	v_fma_f32 v6, -v6, v9, v8
	v_div_fmas_f32 v6, v6, v7, v9
	v_div_fixup_f32 v4, v6, v5, v4
	ds_write_b32 v1, v4 offset:32768
	s_waitcnt vmcnt(14)
	v_mov_b32_e32 v4, v13
	v_mul_f32_e32 v5, 0xbfb8aa3b, v4
	v_exp_f32_e32 v5, v5
	s_nop 0
	v_add_f32_e32 v5, 1.0, v5
	v_div_scale_f32 v6, s[20:21], v5, v5, v4
	v_rcp_f32_e32 v7, v6
	v_div_scale_f32 v8, vcc, v4, v5, v4
	v_fma_f32 v9, -v6, v7, 1.0
	v_fmac_f32_e32 v7, v9, v7
	v_mul_f32_e32 v9, v8, v7
	v_fma_f32 v10, -v6, v9, v8
	v_fmac_f32_e32 v9, v10, v7
	v_fma_f32 v6, -v6, v9, v8
	v_div_fmas_f32 v6, v6, v7, v9
	v_div_fixup_f32 v4, v6, v5, v4
	ds_write_b32 v1, v4 offset:34816
	s_waitcnt vmcnt(13)
; DI float siluf(float x) { return x / (1.f + __expf(-x)); }
; DI void ada_item(const KP& p, int item, float* lds) {
;     ...
;   for (int i = tid; i < 32768; i += 512) { const int d = i >> 4, b = i & 15; lds[i] = siluf(c[b * 2048 + d]); }
	v_mov_b32_e32 v4, v14
	v_mul_f32_e32 v5, 0xbfb8aa3b, v4
	v_exp_f32_e32 v5, v5
	s_nop 0
	v_add_f32_e32 v5, 1.0, v5
	v_div_scale_f32 v6, s[20:21], v5, v5, v4
	v_rcp_f32_e32 v7, v6
	v_div_scale_f32 v8, vcc, v4, v5, v4
	v_fma_f32 v9, -v6, v7, 1.0
	v_fmac_f32_e32 v7, v9, v7
	v_mul_f32_e32 v9, v8, v7
	v_fma_f32 v10, -v6, v9, v8
	v_fmac_f32_e32 v9, v10, v7
	v_fma_f32 v6, -v6, v9, v8
	v_div_fmas_f32 v6, v6, v7, v9
	v_div_fixup_f32 v4, v6, v5, v4
	ds_write_b32 v1, v4 offset:36864
	s_waitcnt vmcnt(12)
	v_mov_b32_e32 v4, v15
	v_mul_f32_e32 v5, 0xbfb8aa3b, v4
	v_exp_f32_e32 v5, v5
	s_nop 0
	v_add_f32_e32 v5, 1.0, v5
	v_div_scale_f32 v6, s[20:21], v5, v5, v4
	v_rcp_f32_e32 v7, v6
	v_div_scale_f32 v8, vcc, v4, v5, v4
	v_fma_f32 v9, -v6, v7, 1.0
	v_fmac_f32_e32 v7, v9, v7
	v_mul_f32_e32 v9, v8, v7
	v_fma_f32 v10, -v6, v9, v8
	v_fmac_f32_e32 v9, v10, v7
	v_fma_f32 v6, -v6, v9, v8
	v_div_fmas_f32 v6, v6, v7, v9
	v_div_fixup_f32 v4, v6, v5, v4
	ds_write_b32 v1, v4 offset:38912
	s_waitcnt vmcnt(11)
	v_mov_b32_e32 v4, v16
	v_mul_f32_e32 v5, 0xbfb8aa3b, v4
	v_exp_f32_e32 v5, v5
	s_nop 0
	v_add_f32_e32 v5, 1.0, v5
	v_div_scale_f32 v6, s[20:21], v5, v5, v4
	v_rcp_f32_e32 v7, v6
	v_div_scale_f32 v8, vcc, v4, v5, v4
	v_fma_f32 v9, -v6, v7, 1.0
	v_fmac_f32_e32 v7, v9, v7
	v_mul_f32_e32 v9, v8, v7
	v_fma_f32 v10, -v6, v9, v8
	v_fmac_f32_e32 v9, v10, v7
	v_fma_f32 v6, -v6, v9, v8
	v_div_fmas_f32 v6, v6, v7, v9
	v_div_fixup_f32 v4, v6, v5, v4
	ds_write_b32 v1, v4 offset:40960
	s_waitcnt vmcnt(10)
	v_mov_b32_e32 v4, v17
	v_mul_f32_e32 v5, 0xbfb8aa3b, v4
	v_exp_f32_e32 v5, v5
	s_nop 0
	v_add_f32_e32 v5, 1.0, v5
	v_div_scale_f32 v6, s[20:21], v5, v5, v4
	v_rcp_f32_e32 v7, v6
	v_div_scale_f32 v8, vcc, v4, v5, v4
	v_fma_f32 v9, -v6, v7, 1.0
	v_fmac_f32_e32 v7, v9, v7
	v_mul_f32_e32 v9, v8, v7
	v_fma_f32 v10, -v6, v9, v8
	v_fmac_f32_e32 v9, v10, v7
	v_fma_f32 v6, -v6, v9, v8
	v_div_fmas_f32 v6, v6, v7, v9
	v_div_fixup_f32 v4, v6, v5, v4
	ds_write_b32 v1, v4 offset:43008
	s_waitcnt vmcnt(9)
	v_mov_b32_e32 v4, v18
	v_mul_f32_e32 v5, 0xbfb8aa3b, v4
	v_exp_f32_e32 v5, v5
	s_nop 0
	v_add_f32_e32 v5, 1.0, v5
	v_div_scale_f32 v6, s[20:21], v5, v5, v4
	v_rcp_f32_e32 v7, v6
	v_div_scale_f32 v8, vcc, v4, v5, v4
	v_fma_f32 v9, -v6, v7, 1.0
	v_fmac_f32_e32 v7, v9, v7
	v_mul_f32_e32 v9, v8, v7
	v_fma_f32 v10, -v6, v9, v8
	v_fmac_f32_e32 v9, v10, v7
	v_fma_f32 v6, -v6, v9, v8
	v_div_fmas_f32 v6, v6, v7, v9
	v_div_fixup_f32 v4, v6, v5, v4
	ds_write_b32 v1, v4 offset:45056
	s_waitcnt vmcnt(8)
	v_mov_b32_e32 v4, v19
	v_mul_f32_e32 v5, 0xbfb8aa3b, v4
	v_exp_f32_e32 v5, v5
	s_nop 0
	v_add_f32_e32 v5, 1.0, v5
	v_div_scale_f32 v6, s[20:21], v5, v5, v4
	v_rcp_f32_e32 v7, v6
	v_div_scale_f32 v8, vcc, v4, v5, v4
	v_fma_f32 v9, -v6, v7, 1.0
	v_fmac_f32_e32 v7, v9, v7
	v_mul_f32_e32 v9, v8, v7
	v_fma_f32 v10, -v6, v9, v8
	v_fmac_f32_e32 v9, v10, v7
	v_fma_f32 v6, -v6, v9, v8
	v_div_fmas_f32 v6, v6, v7, v9
	v_div_fixup_f32 v4, v6, v5, v4
	ds_write_b32 v1, v4 offset:47104
	s_waitcnt vmcnt(7)
	v_mov_b32_e32 v4, v20
	v_mul_f32_e32 v5, 0xbfb8aa3b, v4
	v_exp_f32_e32 v5, v5
	s_nop 0
	v_add_f32_e32 v5, 1.0, v5
	v_div_scale_f32 v6, s[20:21], v5, v5, v4
	v_rcp_f32_e32 v7, v6
	v_div_scale_f32 v8, vcc, v4, v5, v4
	v_fma_f32 v9, -v6, v7, 1.0
	v_fmac_f32_e32 v7, v9, v7
	v_mul_f32_e32 v9, v8, v7
	v_fma_f32 v10, -v6, v9, v8
	v_fmac_f32_e32 v9, v10, v7
	v_fma_f32 v6, -v6, v9, v8
	v_div_fmas_f32 v6, v6, v7, v9
	v_div_fixup_f32 v4, v6, v5, v4
	ds_write_b32 v1, v4 offset:49152
	s_waitcnt vmcnt(6)
	v_mov_b32_e32 v4, v21
	v_mul_f32_e32 v5, 0xbfb8aa3b, v4
	v_exp_f32_e32 v5, v5
	s_nop 0
	v_add_f32_e32 v5, 1.0, v5
	v_div_scale_f32 v6, s[20:21], v5, v5, v4
	v_rcp_f32_e32 v7, v6
	v_div_scale_f32 v8, vcc, v4, v5, v4
	v_fma_f32 v9, -v6, v7, 1.0
	v_fmac_f32_e32 v7, v9, v7
	v_mul_f32_e32 v9, v8, v7
	v_fma_f32 v10, -v6, v9, v8
	v_fmac_f32_e32 v9, v10, v7
	v_fma_f32 v6, -v6, v9, v8
	v_div_fmas_f32 v6, v6, v7, v9
	v_div_fixup_f32 v4, v6, v5, v4
	ds_write_b32 v1, v4 offset:51200
	s_waitcnt vmcnt(5)
	v_mov_b32_e32 v4, v22
	v_mul_f32_e32 v5, 0xbfb8aa3b, v4
	v_exp_f32_e32 v5, v5
	s_nop 0
	v_add_f32_e32 v5, 1.0, v5
	v_div_scale_f32 v6, s[20:21], v5, v5, v4
	v_rcp_f32_e32 v7, v6
	v_div_scale_f32 v8, vcc, v4, v5, v4
	v_fma_f32 v9, -v6, v7, 1.0
	v_fmac_f32_e32 v7, v9, v7
	v_mul_f32_e32 v9, v8, v7
	v_fma_f32 v10, -v6, v9, v8
	v_fmac_f32_e32 v9, v10, v7
	v_fma_f32 v6, -v6, v9, v8
	v_div_fmas_f32 v6, v6, v7, v9
	v_div_fixup_f32 v4, v6, v5, v4
	ds_write_b32 v1, v4 offset:53248
	s_waitcnt vmcnt(4)
	v_mov_b32_e32 v4, v23
	v_mul_f32_e32 v5, 0xbfb8aa3b, v4
	v_exp_f32_e32 v5, v5
	s_nop 0
	v_add_f32_e32 v5, 1.0, v5
	v_div_scale_f32 v6, s[20:21], v5, v5, v4
	v_rcp_f32_e32 v7, v6
	v_div_scale_f32 v8, vcc, v4, v5, v4
	v_fma_f32 v9, -v6, v7, 1.0
	v_fmac_f32_e32 v7, v9, v7
	v_mul_f32_e32 v9, v8, v7
	v_fma_f32 v10, -v6, v9, v8
	v_fmac_f32_e32 v9, v10, v7
	v_fma_f32 v6, -v6, v9, v8
	v_div_fmas_f32 v6, v6, v7, v9
	v_div_fixup_f32 v4, v6, v5, v4
	ds_write_b32 v1, v4 offset:55296
	s_waitcnt vmcnt(3)
	v_mov_b32_e32 v4, v24
	v_mul_f32_e32 v5, 0xbfb8aa3b, v4
	v_exp_f32_e32 v5, v5
	s_nop 0
	v_add_f32_e32 v5, 1.0, v5
	v_div_scale_f32 v6, s[20:21], v5, v5, v4
	v_rcp_f32_e32 v7, v6
	v_div_scale_f32 v8, vcc, v4, v5, v4
	v_fma_f32 v9, -v6, v7, 1.0
	v_fmac_f32_e32 v7, v9, v7
	v_mul_f32_e32 v9, v8, v7
	v_fma_f32 v10, -v6, v9, v8
	v_fmac_f32_e32 v9, v10, v7
	v_fma_f32 v6, -v6, v9, v8
	v_div_fmas_f32 v6, v6, v7, v9
	v_div_fixup_f32 v4, v6, v5, v4
	ds_write_b32 v1, v4 offset:57344
	s_waitcnt vmcnt(2)
; DI float siluf(float x) { return x / (1.f + __expf(-x)); }
; DI void ada_item(const KP& p, int item, float* lds) {
;     ...
;   for (int i = tid; i < 32768; i += 512) { const int d = i >> 4, b = i & 15; lds[i] = siluf(c[b * 2048 + d]); }
	v_mov_b32_e32 v4, v25
	v_mul_f32_e32 v5, 0xbfb8aa3b, v4
	v_exp_f32_e32 v5, v5
	s_nop 0
	v_add_f32_e32 v5, 1.0, v5
	v_div_scale_f32 v6, s[20:21], v5, v5, v4
	v_rcp_f32_e32 v7, v6
	v_div_scale_f32 v8, vcc, v4, v5, v4
	v_fma_f32 v9, -v6, v7, 1.0
	v_fmac_f32_e32 v7, v9, v7
	v_mul_f32_e32 v9, v8, v7
	v_fma_f32 v10, -v6, v9, v8
	v_fmac_f32_e32 v9, v10, v7
	v_fma_f32 v6, -v6, v9, v8
	v_div_fmas_f32 v6, v6, v7, v9
	v_div_fixup_f32 v4, v6, v5, v4
	ds_write_b32 v1, v4 offset:59392
	s_waitcnt vmcnt(1)
	v_mov_b32_e32 v4, v26
	v_mul_f32_e32 v5, 0xbfb8aa3b, v4
	v_exp_f32_e32 v5, v5
	s_nop 0
	v_add_f32_e32 v5, 1.0, v5
	v_div_scale_f32 v6, s[20:21], v5, v5, v4
	v_rcp_f32_e32 v7, v6
	v_div_scale_f32 v8, vcc, v4, v5, v4
	v_fma_f32 v9, -v6, v7, 1.0
	v_fmac_f32_e32 v7, v9, v7
	v_mul_f32_e32 v9, v8, v7
	v_fma_f32 v10, -v6, v9, v8
	v_fmac_f32_e32 v9, v10, v7
	v_fma_f32 v6, -v6, v9, v8
	v_div_fmas_f32 v6, v6, v7, v9
	v_div_fixup_f32 v4, v6, v5, v4
	ds_write_b32 v1, v4 offset:61440
	s_waitcnt vmcnt(0)
	v_mov_b32_e32 v4, v27
	v_mul_f32_e32 v5, 0xbfb8aa3b, v4
	v_exp_f32_e32 v5, v5
	s_nop 0
	v_add_f32_e32 v5, 1.0, v5
	v_div_scale_f32 v6, s[20:21], v5, v5, v4
	v_rcp_f32_e32 v7, v6
	v_div_scale_f32 v8, vcc, v4, v5, v4
	v_fma_f32 v9, -v6, v7, 1.0
	v_fmac_f32_e32 v7, v9, v7
	v_mul_f32_e32 v9, v8, v7
	v_fma_f32 v10, -v6, v9, v8
	v_fmac_f32_e32 v9, v10, v7
	v_fma_f32 v6, -v6, v9, v8
	v_div_fmas_f32 v6, v6, v7, v9
	v_div_fixup_f32 v4, v6, v5, v4
	ds_write_b32 v1, v4 offset:63488
	v_add_u32_e32 v2, 0x1000, v2
	v_add_u32_e32 v1, 0x10000, v1
	global_load_dword v12, v2, s[22:23]
	global_load_dword v13, v2, s[22:23] offset:128
	global_load_dword v14, v2, s[22:23] offset:256
	global_load_dword v15, v2, s[22:23] offset:384
	global_load_dword v16, v2, s[22:23] offset:512
	global_load_dword v17, v2, s[22:23] offset:640
	global_load_dword v18, v2, s[22:23] offset:768
	global_load_dword v19, v2, s[22:23] offset:896
	global_load_dword v20, v2, s[22:23] offset:1024
	global_load_dword v21, v2, s[22:23] offset:1152
	global_load_dword v22, v2, s[22:23] offset:1280
	global_load_dword v23, v2, s[22:23] offset:1408
	global_load_dword v24, v2, s[22:23] offset:1536
	global_load_dword v25, v2, s[22:23] offset:1664
	global_load_dword v26, v2, s[22:23] offset:1792
	global_load_dword v27, v2, s[22:23] offset:1920
	s_waitcnt vmcnt(15)
	v_mov_b32_e32 v4, v12
	v_mul_f32_e32 v5, 0xbfb8aa3b, v4
	v_exp_f32_e32 v5, v5
	s_nop 0
	v_add_f32_e32 v5, 1.0, v5
	v_div_scale_f32 v6, s[20:21], v5, v5, v4
	v_rcp_f32_e32 v7, v6
	v_div_scale_f32 v8, vcc, v4, v5, v4
	v_fma_f32 v9, -v6, v7, 1.0
	v_fmac_f32_e32 v7, v9, v7
	v_mul_f32_e32 v9, v8, v7
	v_fma_f32 v10, -v6, v9, v8
	v_fmac_f32_e32 v9, v10, v7
	v_fma_f32 v6, -v6, v9, v8
	v_div_fmas_f32 v6, v6, v7, v9
	v_div_fixup_f32 v4, v6, v5, v4
	ds_write_b32 v1, v4
	s_waitcnt vmcnt(14)
	v_mov_b32_e32 v4, v13
	v_mul_f32_e32 v5, 0xbfb8aa3b, v4
	v_exp_f32_e32 v5, v5
	s_nop 0
	v_add_f32_e32 v5, 1.0, v5
	v_div_scale_f32 v6, s[20:21], v5, v5, v4
	v_rcp_f32_e32 v7, v6
	v_div_scale_f32 v8, vcc, v4, v5, v4
	v_fma_f32 v9, -v6, v7, 1.0
	v_fmac_f32_e32 v7, v9, v7
	v_mul_f32_e32 v9, v8, v7
	v_fma_f32 v10, -v6, v9, v8
	v_fmac_f32_e32 v9, v10, v7
	v_fma_f32 v6, -v6, v9, v8
	v_div_fmas_f32 v6, v6, v7, v9
	v_div_fixup_f32 v4, v6, v5, v4
	ds_write_b32 v1, v4 offset:2048
	s_waitcnt vmcnt(13)
	v_mov_b32_e32 v4, v14
	v_mul_f32_e32 v5, 0xbfb8aa3b, v4
	v_exp_f32_e32 v5, v5
	s_nop 0
	v_add_f32_e32 v5, 1.0, v5
	v_div_scale_f32 v6, s[20:21], v5, v5, v4
	v_rcp_f32_e32 v7, v6
	v_div_scale_f32 v8, vcc, v4, v5, v4
	v_fma_f32 v9, -v6, v7, 1.0
	v_fmac_f32_e32 v7, v9, v7
	v_mul_f32_e32 v9, v8, v7
	v_fma_f32 v10, -v6, v9, v8
	v_fmac_f32_e32 v9, v10, v7
	v_fma_f32 v6, -v6, v9, v8
	v_div_fmas_f32 v6, v6, v7, v9
	v_div_fixup_f32 v4, v6, v5, v4
	ds_write_b32 v1, v4 offset:4096
	s_waitcnt vmcnt(12)
	v_mov_b32_e32 v4, v15
	v_mul_f32_e32 v5, 0xbfb8aa3b, v4
	v_exp_f32_e32 v5, v5
	s_nop 0
	v_add_f32_e32 v5, 1.0, v5
	v_div_scale_f32 v6, s[20:21], v5, v5, v4
	v_rcp_f32_e32 v7, v6
	v_div_scale_f32 v8, vcc, v4, v5, v4
	v_fma_f32 v9, -v6, v7, 1.0
	v_fmac_f32_e32 v7, v9, v7
	v_mul_f32_e32 v9, v8, v7
	v_fma_f32 v10, -v6, v9, v8
	v_fmac_f32_e32 v9, v10, v7
	v_fma_f32 v6, -v6, v9, v8
	v_div_fmas_f32 v6, v6, v7, v9
	v_div_fixup_f32 v4, v6, v5, v4
	ds_write_b32 v1, v4 offset:6144
	s_waitcnt vmcnt(11)
	v_mov_b32_e32 v4, v16
	v_mul_f32_e32 v5, 0xbfb8aa3b, v4
	v_exp_f32_e32 v5, v5
	s_nop 0
	v_add_f32_e32 v5, 1.0, v5
	v_div_scale_f32 v6, s[20:21], v5, v5, v4
	v_rcp_f32_e32 v7, v6
	v_div_scale_f32 v8, vcc, v4, v5, v4
	v_fma_f32 v9, -v6, v7, 1.0
	v_fmac_f32_e32 v7, v9, v7
	v_mul_f32_e32 v9, v8, v7
	v_fma_f32 v10, -v6, v9, v8
	v_fmac_f32_e32 v9, v10, v7
	v_fma_f32 v6, -v6, v9, v8
	v_div_fmas_f32 v6, v6, v7, v9
	v_div_fixup_f32 v4, v6, v5, v4
	ds_write_b32 v1, v4 offset:8192
	s_waitcnt vmcnt(10)
	v_mov_b32_e32 v4, v17
	v_mul_f32_e32 v5, 0xbfb8aa3b, v4
	v_exp_f32_e32 v5, v5
	s_nop 0
	v_add_f32_e32 v5, 1.0, v5
	v_div_scale_f32 v6, s[20:21], v5, v5, v4
	v_rcp_f32_e32 v7, v6
	v_div_scale_f32 v8, vcc, v4, v5, v4
	v_fma_f32 v9, -v6, v7, 1.0
	v_fmac_f32_e32 v7, v9, v7
	v_mul_f32_e32 v9, v8, v7
	v_fma_f32 v10, -v6, v9, v8
	v_fmac_f32_e32 v9, v10, v7
	v_fma_f32 v6, -v6, v9, v8
	v_div_fmas_f32 v6, v6, v7, v9
	v_div_fixup_f32 v4, v6, v5, v4
	ds_write_b32 v1, v4 offset:10240
	s_waitcnt vmcnt(9)
	v_mov_b32_e32 v4, v18
	v_mul_f32_e32 v5, 0xbfb8aa3b, v4
	v_exp_f32_e32 v5, v5
	s_nop 0
	v_add_f32_e32 v5, 1.0, v5
	v_div_scale_f32 v6, s[20:21], v5, v5, v4
	v_rcp_f32_e32 v7, v6
	v_div_scale_f32 v8, vcc, v4, v5, v4
	v_fma_f32 v9, -v6, v7, 1.0
	v_fmac_f32_e32 v7, v9, v7
	v_mul_f32_e32 v9, v8, v7
	v_fma_f32 v10, -v6, v9, v8
	v_fmac_f32_e32 v9, v10, v7
	v_fma_f32 v6, -v6, v9, v8
	v_div_fmas_f32 v6, v6, v7, v9
	v_div_fixup_f32 v4, v6, v5, v4
	ds_write_b32 v1, v4 offset:12288
	s_waitcnt vmcnt(8)
; DI float siluf(float x) { return x / (1.f + __expf(-x)); }
; DI void ada_item(const KP& p, int item, float* lds) {
;     ...
;   for (int i = tid; i < 32768; i += 512) { const int d = i >> 4, b = i & 15; lds[i] = siluf(c[b * 2048 + d]); }
	v_mov_b32_e32 v4, v19
	v_mul_f32_e32 v5, 0xbfb8aa3b, v4
	v_exp_f32_e32 v5, v5
	s_nop 0
	v_add_f32_e32 v5, 1.0, v5
	v_div_scale_f32 v6, s[20:21], v5, v5, v4
	v_rcp_f32_e32 v7, v6
	v_div_scale_f32 v8, vcc, v4, v5, v4
	v_fma_f32 v9, -v6, v7, 1.0
	v_fmac_f32_e32 v7, v9, v7
	v_mul_f32_e32 v9, v8, v7
	v_fma_f32 v10, -v6, v9, v8
	v_fmac_f32_e32 v9, v10, v7
	v_fma_f32 v6, -v6, v9, v8
	v_div_fmas_f32 v6, v6, v7, v9
	v_div_fixup_f32 v4, v6, v5, v4
	ds_write_b32 v1, v4 offset:14336
	s_waitcnt vmcnt(7)
	v_mov_b32_e32 v4, v20
	v_mul_f32_e32 v5, 0xbfb8aa3b, v4
	v_exp_f32_e32 v5, v5
	s_nop 0
	v_add_f32_e32 v5, 1.0, v5
	v_div_scale_f32 v6, s[20:21], v5, v5, v4
	v_rcp_f32_e32 v7, v6
	v_div_scale_f32 v8, vcc, v4, v5, v4
	v_fma_f32 v9, -v6, v7, 1.0
	v_fmac_f32_e32 v7, v9, v7
	v_mul_f32_e32 v9, v8, v7
	v_fma_f32 v10, -v6, v9, v8
	v_fmac_f32_e32 v9, v10, v7
	v_fma_f32 v6, -v6, v9, v8
	v_div_fmas_f32 v6, v6, v7, v9
	v_div_fixup_f32 v4, v6, v5, v4
	ds_write_b32 v1, v4 offset:16384
	s_waitcnt vmcnt(6)
	v_mov_b32_e32 v4, v21
	v_mul_f32_e32 v5, 0xbfb8aa3b, v4
	v_exp_f32_e32 v5, v5
	s_nop 0
	v_add_f32_e32 v5, 1.0, v5
	v_div_scale_f32 v6, s[20:21], v5, v5, v4
	v_rcp_f32_e32 v7, v6
	v_div_scale_f32 v8, vcc, v4, v5, v4
	v_fma_f32 v9, -v6, v7, 1.0
	v_fmac_f32_e32 v7, v9, v7
	v_mul_f32_e32 v9, v8, v7
	v_fma_f32 v10, -v6, v9, v8
	v_fmac_f32_e32 v9, v10, v7
	v_fma_f32 v6, -v6, v9, v8
	v_div_fmas_f32 v6, v6, v7, v9
	v_div_fixup_f32 v4, v6, v5, v4
	ds_write_b32 v1, v4 offset:18432
	s_waitcnt vmcnt(5)
	v_mov_b32_e32 v4, v22
	v_mul_f32_e32 v5, 0xbfb8aa3b, v4
	v_exp_f32_e32 v5, v5
	s_nop 0
	v_add_f32_e32 v5, 1.0, v5
	v_div_scale_f32 v6, s[20:21], v5, v5, v4
	v_rcp_f32_e32 v7, v6
	v_div_scale_f32 v8, vcc, v4, v5, v4
	v_fma_f32 v9, -v6, v7, 1.0
	v_fmac_f32_e32 v7, v9, v7
	v_mul_f32_e32 v9, v8, v7
	v_fma_f32 v10, -v6, v9, v8
	v_fmac_f32_e32 v9, v10, v7
	v_fma_f32 v6, -v6, v9, v8
	v_div_fmas_f32 v6, v6, v7, v9
	v_div_fixup_f32 v4, v6, v5, v4
	ds_write_b32 v1, v4 offset:20480
	s_waitcnt vmcnt(4)
	v_mov_b32_e32 v4, v23
	v_mul_f32_e32 v5, 0xbfb8aa3b, v4
	v_exp_f32_e32 v5, v5
	s_nop 0
	v_add_f32_e32 v5, 1.0, v5
	v_div_scale_f32 v6, s[20:21], v5, v5, v4
	v_rcp_f32_e32 v7, v6
	v_div_scale_f32 v8, vcc, v4, v5, v4
	v_fma_f32 v9, -v6, v7, 1.0
	v_fmac_f32_e32 v7, v9, v7
	v_mul_f32_e32 v9, v8, v7
	v_fma_f32 v10, -v6, v9, v8
	v_fmac_f32_e32 v9, v10, v7
	v_fma_f32 v6, -v6, v9, v8
	v_div_fmas_f32 v6, v6, v7, v9
	v_div_fixup_f32 v4, v6, v5, v4
	ds_write_b32 v1, v4 offset:22528
	s_waitcnt vmcnt(3)
	v_mov_b32_e32 v4, v24
	v_mul_f32_e32 v5, 0xbfb8aa3b, v4
	v_exp_f32_e32 v5, v5
	s_nop 0
	v_add_f32_e32 v5, 1.0, v5
	v_div_scale_f32 v6, s[20:21], v5, v5, v4
	v_rcp_f32_e32 v7, v6
	v_div_scale_f32 v8, vcc, v4, v5, v4
	v_fma_f32 v9, -v6, v7, 1.0
	v_fmac_f32_e32 v7, v9, v7
	v_mul_f32_e32 v9, v8, v7
	v_fma_f32 v10, -v6, v9, v8
	v_fmac_f32_e32 v9, v10, v7
	v_fma_f32 v6, -v6, v9, v8
	v_div_fmas_f32 v6, v6, v7, v9
	v_div_fixup_f32 v4, v6, v5, v4
	ds_write_b32 v1, v4 offset:24576
	s_waitcnt vmcnt(2)
	v_mov_b32_e32 v4, v25
	v_mul_f32_e32 v5, 0xbfb8aa3b, v4
	v_exp_f32_e32 v5, v5
	s_nop 0
	v_add_f32_e32 v5, 1.0, v5
	v_div_scale_f32 v6, s[20:21], v5, v5, v4
	v_rcp_f32_e32 v7, v6
	v_div_scale_f32 v8, vcc, v4, v5, v4
	v_fma_f32 v9, -v6, v7, 1.0
	v_fmac_f32_e32 v7, v9, v7
	v_mul_f32_e32 v9, v8, v7
	v_fma_f32 v10, -v6, v9, v8
	v_fmac_f32_e32 v9, v10, v7
	v_fma_f32 v6, -v6, v9, v8
	v_div_fmas_f32 v6, v6, v7, v9
	v_div_fixup_f32 v4, v6, v5, v4
	ds_write_b32 v1, v4 offset:26624
	s_waitcnt vmcnt(1)
	v_mov_b32_e32 v4, v26
	v_mul_f32_e32 v5, 0xbfb8aa3b, v4
	v_exp_f32_e32 v5, v5
	s_nop 0
	v_add_f32_e32 v5, 1.0, v5
	v_div_scale_f32 v6, s[20:21], v5, v5, v4
	v_rcp_f32_e32 v7, v6
	v_div_scale_f32 v8, vcc, v4, v5, v4
	v_fma_f32 v9, -v6, v7, 1.0
	v_fmac_f32_e32 v7, v9, v7
	v_mul_f32_e32 v9, v8, v7
	v_fma_f32 v10, -v6, v9, v8
	v_fmac_f32_e32 v9, v10, v7
	v_fma_f32 v6, -v6, v9, v8
	v_div_fmas_f32 v6, v6, v7, v9
	v_div_fixup_f32 v4, v6, v5, v4
	ds_write_b32 v1, v4 offset:28672
	s_waitcnt vmcnt(0)
	v_mov_b32_e32 v4, v27
	v_mul_f32_e32 v5, 0xbfb8aa3b, v4
	v_exp_f32_e32 v5, v5
	s_nop 0
	v_add_f32_e32 v5, 1.0, v5
	v_div_scale_f32 v6, s[20:21], v5, v5, v4
	v_rcp_f32_e32 v7, v6
	v_div_scale_f32 v8, vcc, v4, v5, v4
	v_fma_f32 v9, -v6, v7, 1.0
	v_fmac_f32_e32 v7, v9, v7
	v_mul_f32_e32 v9, v8, v7
	v_fma_f32 v10, -v6, v9, v8
	v_fmac_f32_e32 v9, v10, v7
	v_fma_f32 v6, -v6, v9, v8
	v_div_fmas_f32 v6, v6, v7, v9
	v_div_fixup_f32 v4, v6, v5, v4
	ds_write_b32 v1, v4 offset:30720
	global_load_dword v12, v2, s[22:23] offset:2048
	global_load_dword v13, v2, s[22:23] offset:2176
	global_load_dword v14, v2, s[22:23] offset:2304
	global_load_dword v15, v2, s[22:23] offset:2432
	global_load_dword v16, v2, s[22:23] offset:2560
	global_load_dword v17, v2, s[22:23] offset:2688
	global_load_dword v18, v2, s[22:23] offset:2816
	global_load_dword v19, v2, s[22:23] offset:2944
	global_load_dword v20, v2, s[22:23] offset:3072
	global_load_dword v21, v2, s[22:23] offset:3200
	global_load_dword v22, v2, s[22:23] offset:3328
	global_load_dword v23, v2, s[22:23] offset:3456
	global_load_dword v24, v2, s[22:23] offset:3584
	global_load_dword v25, v2, s[22:23] offset:3712
	global_load_dword v26, v2, s[22:23] offset:3840
	global_load_dword v27, v2, s[22:23] offset:3968
	s_waitcnt vmcnt(15)
	v_mov_b32_e32 v4, v12
	v_mul_f32_e32 v5, 0xbfb8aa3b, v4
	v_exp_f32_e32 v5, v5
	s_nop 0
	v_add_f32_e32 v5, 1.0, v5
	v_div_scale_f32 v6, s[20:21], v5, v5, v4
	v_rcp_f32_e32 v7, v6
	v_div_scale_f32 v8, vcc, v4, v5, v4
	v_fma_f32 v9, -v6, v7, 1.0
	v_fmac_f32_e32 v7, v9, v7
	v_mul_f32_e32 v9, v8, v7
	v_fma_f32 v10, -v6, v9, v8
	v_fmac_f32_e32 v9, v10, v7
	v_fma_f32 v6, -v6, v9, v8
	v_div_fmas_f32 v6, v6, v7, v9
	v_div_fixup_f32 v4, v6, v5, v4
	ds_write_b32 v1, v4 offset:32768
	s_waitcnt vmcnt(14)
; DI float siluf(float x) { return x / (1.f + __expf(-x)); }
; DI void ada_item(const KP& p, int item, float* lds) {
;     ...
;   for (int i = tid; i < 32768; i += 512) { const int d = i >> 4, b = i & 15; lds[i] = siluf(c[b * 2048 + d]); }
	v_mov_b32_e32 v4, v13
	v_mul_f32_e32 v5, 0xbfb8aa3b, v4
	v_exp_f32_e32 v5, v5
	s_nop 0
	v_add_f32_e32 v5, 1.0, v5
	v_div_scale_f32 v6, s[20:21], v5, v5, v4
	v_rcp_f32_e32 v7, v6
	v_div_scale_f32 v8, vcc, v4, v5, v4
	v_fma_f32 v9, -v6, v7, 1.0
	v_fmac_f32_e32 v7, v9, v7
	v_mul_f32_e32 v9, v8, v7
	v_fma_f32 v10, -v6, v9, v8
	v_fmac_f32_e32 v9, v10, v7
	v_fma_f32 v6, -v6, v9, v8
	v_div_fmas_f32 v6, v6, v7, v9
	v_div_fixup_f32 v4, v6, v5, v4
	ds_write_b32 v1, v4 offset:34816
	s_waitcnt vmcnt(13)
	v_mov_b32_e32 v4, v14
	v_mul_f32_e32 v5, 0xbfb8aa3b, v4
	v_exp_f32_e32 v5, v5
	s_nop 0
	v_add_f32_e32 v5, 1.0, v5
	v_div_scale_f32 v6, s[20:21], v5, v5, v4
	v_rcp_f32_e32 v7, v6
	v_div_scale_f32 v8, vcc, v4, v5, v4
	v_fma_f32 v9, -v6, v7, 1.0
	v_fmac_f32_e32 v7, v9, v7
	v_mul_f32_e32 v9, v8, v7
	v_fma_f32 v10, -v6, v9, v8
	v_fmac_f32_e32 v9, v10, v7
	v_fma_f32 v6, -v6, v9, v8
	v_div_fmas_f32 v6, v6, v7, v9
	v_div_fixup_f32 v4, v6, v5, v4
	ds_write_b32 v1, v4 offset:36864
	s_waitcnt vmcnt(12)
	v_mov_b32_e32 v4, v15
	v_mul_f32_e32 v5, 0xbfb8aa3b, v4
	v_exp_f32_e32 v5, v5
	s_nop 0
	v_add_f32_e32 v5, 1.0, v5
	v_div_scale_f32 v6, s[20:21], v5, v5, v4
	v_rcp_f32_e32 v7, v6
	v_div_scale_f32 v8, vcc, v4, v5, v4
	v_fma_f32 v9, -v6, v7, 1.0
	v_fmac_f32_e32 v7, v9, v7
	v_mul_f32_e32 v9, v8, v7
	v_fma_f32 v10, -v6, v9, v8
	v_fmac_f32_e32 v9, v10, v7
	v_fma_f32 v6, -v6, v9, v8
	v_div_fmas_f32 v6, v6, v7, v9
	v_div_fixup_f32 v4, v6, v5, v4
	ds_write_b32 v1, v4 offset:38912
	s_waitcnt vmcnt(11)
	v_mov_b32_e32 v4, v16
	v_mul_f32_e32 v5, 0xbfb8aa3b, v4
	v_exp_f32_e32 v5, v5
	s_nop 0
	v_add_f32_e32 v5, 1.0, v5
	v_div_scale_f32 v6, s[20:21], v5, v5, v4
	v_rcp_f32_e32 v7, v6
	v_div_scale_f32 v8, vcc, v4, v5, v4
	v_fma_f32 v9, -v6, v7, 1.0
	v_fmac_f32_e32 v7, v9, v7
	v_mul_f32_e32 v9, v8, v7
	v_fma_f32 v10, -v6, v9, v8
	v_fmac_f32_e32 v9, v10, v7
	v_fma_f32 v6, -v6, v9, v8
	v_div_fmas_f32 v6, v6, v7, v9
	v_div_fixup_f32 v4, v6, v5, v4
	ds_write_b32 v1, v4 offset:40960
	s_waitcnt vmcnt(10)
	v_mov_b32_e32 v4, v17
	v_mul_f32_e32 v5, 0xbfb8aa3b, v4
	v_exp_f32_e32 v5, v5
	s_nop 0
	v_add_f32_e32 v5, 1.0, v5
	v_div_scale_f32 v6, s[20:21], v5, v5, v4
	v_rcp_f32_e32 v7, v6
	v_div_scale_f32 v8, vcc, v4, v5, v4
	v_fma_f32 v9, -v6, v7, 1.0
	v_fmac_f32_e32 v7, v9, v7
	v_mul_f32_e32 v9, v8, v7
	v_fma_f32 v10, -v6, v9, v8
	v_fmac_f32_e32 v9, v10, v7
	v_fma_f32 v6, -v6, v9, v8
	v_div_fmas_f32 v6, v6, v7, v9
	v_div_fixup_f32 v4, v6, v5, v4
	ds_write_b32 v1, v4 offset:43008
	s_waitcnt vmcnt(9)
	v_mov_b32_e32 v4, v18
	v_mul_f32_e32 v5, 0xbfb8aa3b, v4
	v_exp_f32_e32 v5, v5
	s_nop 0
	v_add_f32_e32 v5, 1.0, v5
	v_div_scale_f32 v6, s[20:21], v5, v5, v4
	v_rcp_f32_e32 v7, v6
	v_div_scale_f32 v8, vcc, v4, v5, v4
	v_fma_f32 v9, -v6, v7, 1.0
	v_fmac_f32_e32 v7, v9, v7
	v_mul_f32_e32 v9, v8, v7
	v_fma_f32 v10, -v6, v9, v8
	v_fmac_f32_e32 v9, v10, v7
	v_fma_f32 v6, -v6, v9, v8
	v_div_fmas_f32 v6, v6, v7, v9
	v_div_fixup_f32 v4, v6, v5, v4
	ds_write_b32 v1, v4 offset:45056
	s_waitcnt vmcnt(8)
	v_mov_b32_e32 v4, v19
	v_mul_f32_e32 v5, 0xbfb8aa3b, v4
	v_exp_f32_e32 v5, v5
	s_nop 0
	v_add_f32_e32 v5, 1.0, v5
	v_div_scale_f32 v6, s[20:21], v5, v5, v4
	v_rcp_f32_e32 v7, v6
	v_div_scale_f32 v8, vcc, v4, v5, v4
	v_fma_f32 v9, -v6, v7, 1.0
	v_fmac_f32_e32 v7, v9, v7
	v_mul_f32_e32 v9, v8, v7
	v_fma_f32 v10, -v6, v9, v8
	v_fmac_f32_e32 v9, v10, v7
	v_fma_f32 v6, -v6, v9, v8
	v_div_fmas_f32 v6, v6, v7, v9
	v_div_fixup_f32 v4, v6, v5, v4
	ds_write_b32 v1, v4 offset:47104
	s_waitcnt vmcnt(7)
	v_mov_b32_e32 v4, v20
	v_mul_f32_e32 v5, 0xbfb8aa3b, v4
	v_exp_f32_e32 v5, v5
	s_nop 0
	v_add_f32_e32 v5, 1.0, v5
	v_div_scale_f32 v6, s[20:21], v5, v5, v4
	v_rcp_f32_e32 v7, v6
	v_div_scale_f32 v8, vcc, v4, v5, v4
	v_fma_f32 v9, -v6, v7, 1.0
	v_fmac_f32_e32 v7, v9, v7
	v_mul_f32_e32 v9, v8, v7
	v_fma_f32 v10, -v6, v9, v8
	v_fmac_f32_e32 v9, v10, v7
	v_fma_f32 v6, -v6, v9, v8
	v_div_fmas_f32 v6, v6, v7, v9
	v_div_fixup_f32 v4, v6, v5, v4
	ds_write_b32 v1, v4 offset:49152
	s_waitcnt vmcnt(6)
	v_mov_b32_e32 v4, v21
	v_mul_f32_e32 v5, 0xbfb8aa3b, v4
	v_exp_f32_e32 v5, v5
	s_nop 0
	v_add_f32_e32 v5, 1.0, v5
	v_div_scale_f32 v6, s[20:21], v5, v5, v4
	v_rcp_f32_e32 v7, v6
	v_div_scale_f32 v8, vcc, v4, v5, v4
	v_fma_f32 v9, -v6, v7, 1.0
	v_fmac_f32_e32 v7, v9, v7
	v_mul_f32_e32 v9, v8, v7
	v_fma_f32 v10, -v6, v9, v8
	v_fmac_f32_e32 v9, v10, v7
	v_fma_f32 v6, -v6, v9, v8
	v_div_fmas_f32 v6, v6, v7, v9
	v_div_fixup_f32 v4, v6, v5, v4
	ds_write_b32 v1, v4 offset:51200
	s_waitcnt vmcnt(5)
	v_mov_b32_e32 v4, v22
	v_mul_f32_e32 v5, 0xbfb8aa3b, v4
	v_exp_f32_e32 v5, v5
	s_nop 0
	v_add_f32_e32 v5, 1.0, v5
	v_div_scale_f32 v6, s[20:21], v5, v5, v4
	v_rcp_f32_e32 v7, v6
	v_div_scale_f32 v8, vcc, v4, v5, v4
	v_fma_f32 v9, -v6, v7, 1.0
	v_fmac_f32_e32 v7, v9, v7
	v_mul_f32_e32 v9, v8, v7
	v_fma_f32 v10, -v6, v9, v8
	v_fmac_f32_e32 v9, v10, v7
	v_fma_f32 v6, -v6, v9, v8
	v_div_fmas_f32 v6, v6, v7, v9
	v_div_fixup_f32 v4, v6, v5, v4
	ds_write_b32 v1, v4 offset:53248
	s_waitcnt vmcnt(4)
	v_mov_b32_e32 v4, v23
	v_mul_f32_e32 v5, 0xbfb8aa3b, v4
	v_exp_f32_e32 v5, v5
	s_nop 0
	v_add_f32_e32 v5, 1.0, v5
	v_div_scale_f32 v6, s[20:21], v5, v5, v4
	v_rcp_f32_e32 v7, v6
	v_div_scale_f32 v8, vcc, v4, v5, v4
	v_fma_f32 v9, -v6, v7, 1.0
	v_fmac_f32_e32 v7, v9, v7
	v_mul_f32_e32 v9, v8, v7
	v_fma_f32 v10, -v6, v9, v8
	v_fmac_f32_e32 v9, v10, v7
	v_fma_f32 v6, -v6, v9, v8
	v_div_fmas_f32 v6, v6, v7, v9
	v_div_fixup_f32 v4, v6, v5, v4
	ds_write_b32 v1, v4 offset:55296
	s_waitcnt vmcnt(3)
; DI float siluf(float x) { return x / (1.f + __expf(-x)); }
; DI void ada_item(const KP& p, int item, float* lds) {
;     ...
;   for (int i = tid; i < 32768; i += 512) { const int d = i >> 4, b = i & 15; lds[i] = siluf(c[b * 2048 + d]); }
;   __syncthreads();
;   const int cq = tid & 15, dg = tid >> 4, d0 = dg * 64;
;   f32x4 acc[16];
; #pragma unroll
;   for (int b = 0; b < 16; ++b) acc[b] = (f32x4){0.f, 0.f, 0.f, 0.f};
; #pragma unroll 1
;   for (int dd0 = 0; dd0 < 64; dd0 += 16) {
;     f32x4 wv[16];
; #pragma unroll
;     for (int u = 0; u < 16; ++u) wv[u] = *(const f32x4*)(W + (size_t)(d0 + dd0 + u) * 6144 + e0 + cq * 4);
	v_mov_b32_e32 v4, v24
	v_mul_f32_e32 v5, 0xbfb8aa3b, v4
	v_exp_f32_e32 v5, v5
	s_nop 0
	v_add_f32_e32 v5, 1.0, v5
	v_div_scale_f32 v6, s[20:21], v5, v5, v4
	v_rcp_f32_e32 v7, v6
	v_div_scale_f32 v8, vcc, v4, v5, v4
	v_fma_f32 v9, -v6, v7, 1.0
	v_fmac_f32_e32 v7, v9, v7
	v_mul_f32_e32 v9, v8, v7
	v_fma_f32 v10, -v6, v9, v8
	v_fmac_f32_e32 v9, v10, v7
	v_fma_f32 v6, -v6, v9, v8
	v_div_fmas_f32 v6, v6, v7, v9
	v_div_fixup_f32 v4, v6, v5, v4
	ds_write_b32 v1, v4 offset:57344
	s_waitcnt vmcnt(2)
	v_mov_b32_e32 v4, v25
	v_mul_f32_e32 v5, 0xbfb8aa3b, v4
	v_exp_f32_e32 v5, v5
	s_nop 0
	v_add_f32_e32 v5, 1.0, v5
	v_div_scale_f32 v6, s[20:21], v5, v5, v4
	v_rcp_f32_e32 v7, v6
	v_div_scale_f32 v8, vcc, v4, v5, v4
	v_fma_f32 v9, -v6, v7, 1.0
	v_fmac_f32_e32 v7, v9, v7
	v_mul_f32_e32 v9, v8, v7
	v_fma_f32 v10, -v6, v9, v8
	v_fmac_f32_e32 v9, v10, v7
	v_fma_f32 v6, -v6, v9, v8
	v_div_fmas_f32 v6, v6, v7, v9
	v_div_fixup_f32 v4, v6, v5, v4
	ds_write_b32 v1, v4 offset:59392
	s_waitcnt vmcnt(1)
	v_mov_b32_e32 v4, v26
	v_mul_f32_e32 v5, 0xbfb8aa3b, v4
	v_exp_f32_e32 v5, v5
	s_nop 0
	v_add_f32_e32 v5, 1.0, v5
	v_div_scale_f32 v6, s[20:21], v5, v5, v4
	v_rcp_f32_e32 v7, v6
	v_div_scale_f32 v8, vcc, v4, v5, v4
	v_fma_f32 v9, -v6, v7, 1.0
	v_fmac_f32_e32 v7, v9, v7
	v_mul_f32_e32 v9, v8, v7
	v_fma_f32 v10, -v6, v9, v8
	v_fmac_f32_e32 v9, v10, v7
	v_fma_f32 v6, -v6, v9, v8
	v_div_fmas_f32 v6, v6, v7, v9
	v_div_fixup_f32 v4, v6, v5, v4
	ds_write_b32 v1, v4 offset:61440
	s_waitcnt vmcnt(0)
	v_mov_b32_e32 v4, v27
	v_mul_f32_e32 v5, 0xbfb8aa3b, v4
	v_exp_f32_e32 v5, v5
	s_nop 0
	v_add_f32_e32 v5, 1.0, v5
	v_div_scale_f32 v6, s[20:21], v5, v5, v4
	v_rcp_f32_e32 v7, v6
	v_div_scale_f32 v8, vcc, v4, v5, v4
	v_fma_f32 v9, -v6, v7, 1.0
	v_fmac_f32_e32 v7, v9, v7
	v_mul_f32_e32 v9, v8, v7
	v_fma_f32 v10, -v6, v9, v8
	v_fmac_f32_e32 v9, v10, v7
	v_fma_f32 v6, -v6, v9, v8
	v_div_fmas_f32 v6, v6, v7, v9
	v_div_fixup_f32 v4, v6, v5, v4
	ds_write_b32 v1, v4 offset:63488
	s_or_b64 exec, exec, s[12:13]
.LBB0_27:
	s_or_b64 exec, exec, s[10:11]
	s_mul_i32 s10, s18, 0x60
	s_movk_i32 s12, 0x6000
	s_sub_i32 s10, s15, s10
	v_and_b32_e32 v0, 0xffffffc0, v0
	s_lshl_b32 s10, s10, 6
	s_ashr_i32 s19, s18, 1
	v_mad_i64_i32 v[0:1], s[12:13], v0, s12, 0
	v_mov_b32_e32 v2, 0x3000000
	s_ashr_i32 s11, s10, 31
	v_mad_i64_i32 v[0:1], s[12:13], s19, v2, v[0:1]
	s_lshl_b64 s[12:13], s[10:11], 2
	v_and_b32_e32 v108, 15, v105
	s_waitcnt lgkmcnt(0)
	s_add_u32 s4, s4, s12
	v_lshlrev_b32_e32 v106, 8, v105
	v_lshl_or_b32 v0, v108, 4, v0
	s_addc_u32 s5, s5, s13
	v_and_b32_e32 v107, 0xfffff000, v106
	v_lshl_add_u64 v[0:1], s[4:5], 0, v[0:1]
	v_mov_b32_e32 v158, v0
	v_mov_b32_e32 v159, v1
	v_add_u32_e32 v109, 32, v107
	s_mov_b64 s[20:21], 0x6000
	s_mov_b32 s4, 0
	v_mov_b32_e32 v0, 0
	v_mov_b32_e32 v1, 0
	v_mov_b32_e32 v2, 0
	v_mov_b32_e32 v3, 0
	v_mov_b32_e32 v4, 0
	v_mov_b32_e32 v5, 0
	v_mov_b32_e32 v6, 0
	v_mov_b32_e32 v7, 0
	v_mov_b32_e32 v8, 0
	v_mov_b32_e32 v9, 0
	v_mov_b32_e32 v10, 0
	v_mov_b32_e32 v11, 0
	v_mov_b32_e32 v12, 0
	v_mov_b32_e32 v13, 0
	v_mov_b32_e32 v14, 0
	v_mov_b32_e32 v15, 0
	v_mov_b32_e32 v16, 0
	v_mov_b32_e32 v17, 0
	v_mov_b32_e32 v18, 0
	v_mov_b32_e32 v19, 0
	v_mov_b32_e32 v20, 0
	v_mov_b32_e32 v21, 0
	v_mov_b32_e32 v22, 0
	v_mov_b32_e32 v23, 0
	v_mov_b32_e32 v24, 0
	v_mov_b32_e32 v25, 0
	v_mov_b32_e32 v26, 0
	v_mov_b32_e32 v27, 0
	v_mov_b32_e32 v28, 0
	v_mov_b32_e32 v29, 0
	v_mov_b32_e32 v30, 0
	v_mov_b32_e32 v31, 0
	v_mov_b32_e32 v32, 0
	v_mov_b32_e32 v33, 0
	v_mov_b32_e32 v34, 0
	v_mov_b32_e32 v35, 0
	v_mov_b32_e32 v36, 0
	v_mov_b32_e32 v37, 0
	v_mov_b32_e32 v38, 0
	v_mov_b32_e32 v39, 0
	v_mov_b32_e32 v40, 0
	v_mov_b32_e32 v41, 0
	v_mov_b32_e32 v42, 0
	v_mov_b32_e32 v43, 0
	v_mov_b32_e32 v44, 0
	v_mov_b32_e32 v45, 0
	v_mov_b32_e32 v46, 0
	v_mov_b32_e32 v47, 0
	v_mov_b32_e32 v48, 0
	v_mov_b32_e32 v49, 0
	v_mov_b32_e32 v50, 0
	v_mov_b32_e32 v51, 0
	v_mov_b32_e32 v52, 0
	v_mov_b32_e32 v53, 0
	v_mov_b32_e32 v54, 0
	v_mov_b32_e32 v55, 0
	v_mov_b32_e32 v56, 0
	v_mov_b32_e32 v57, 0
	v_mov_b32_e32 v58, 0
	v_mov_b32_e32 v59, 0
	v_mov_b32_e32 v60, 0
	v_mov_b32_e32 v61, 0
	v_mov_b32_e32 v62, 0
	v_mov_b32_e32 v63, 0
	s_barrier
	global_load_dwordx4 v[70:73], v[158:159], off
	v_lshl_add_u64 v[64:65], v[158:159], 0, s[20:21]
	global_load_dwordx4 v[74:77], v[64:65], off
	v_lshl_add_u64 v[66:67], v[64:65], 0, s[20:21]
	global_load_dwordx4 v[78:81], v[66:67], off
	v_lshl_add_u64 v[64:65], v[66:67], 0, s[20:21]
	global_load_dwordx4 v[82:85], v[64:65], off
	v_lshl_add_u64 v[66:67], v[64:65], 0, s[20:21]
	global_load_dwordx4 v[86:89], v[66:67], off
	v_lshl_add_u64 v[64:65], v[66:67], 0, s[20:21]
	global_load_dwordx4 v[90:93], v[64:65], off
	v_lshl_add_u64 v[66:67], v[64:65], 0, s[20:21]
	global_load_dwordx4 v[94:97], v[66:67], off
	v_lshl_add_u64 v[64:65], v[66:67], 0, s[20:21]
	global_load_dwordx4 v[98:101], v[64:65], off
	v_lshl_add_u64 v[158:159], v[64:65], 0, s[20:21]
; DI void ada_item(const KP& p, int item, float* lds) {
;     ...
; #pragma unroll 1
;   for (int dd0 = 0; dd0 < 64; dd0 += 16) {
;     f32x4 wv[16];
; #pragma unroll
;     for (int u = 0; u < 16; ++u) wv[u] = *(const f32x4*)(W + (size_t)(d0 + dd0 + u) * 6144 + e0 + cq * 4);
; #pragma unroll
;     for (int u = 0; u < 16; ++u) { const f32x4 w = wv[u]; const f32x4* sp = (const f32x4*)(lds + (d0 + dd0 + u) * 16);
; #pragma unroll
;       for (int q = 0; q < 4; ++q) { const f32x4 s = sp[q];
;         acc[4 * q + 0] += w * s[0]; acc[4 * q + 1] += w * s[1]; acc[4 * q + 2] += w * s[2]; acc[4 * q + 3] += w * s[3]; } } }
.Lada_loop:
	global_load_dwordx4 v[110:113], v[158:159], off
	v_lshl_add_u64 v[64:65], v[158:159], 0, s[20:21]
	global_load_dwordx4 v[114:117], v[64:65], off
	v_lshl_add_u64 v[66:67], v[64:65], 0, s[20:21]
	global_load_dwordx4 v[118:121], v[66:67], off
	v_lshl_add_u64 v[64:65], v[66:67], 0, s[20:21]
	global_load_dwordx4 v[122:125], v[64:65], off
	v_lshl_add_u64 v[66:67], v[64:65], 0, s[20:21]
	global_load_dwordx4 v[126:129], v[66:67], off
	v_lshl_add_u64 v[64:65], v[66:67], 0, s[20:21]
	global_load_dwordx4 v[130:133], v[64:65], off
	v_lshl_add_u64 v[66:67], v[64:65], 0, s[20:21]
	global_load_dwordx4 v[134:137], v[66:67], off
	v_lshl_add_u64 v[64:65], v[66:67], 0, s[20:21]
	global_load_dwordx4 v[138:141], v[64:65], off
	v_lshl_add_u64 v[158:159], v[64:65], 0, s[20:21]
	ds_read_b128 v[142:145], v109 offset:0
	ds_read_b128 v[146:149], v109 offset:16
	ds_read_b128 v[150:153], v109 offset:32
	ds_read_b128 v[154:157], v109 offset:48
	ds_read_b128 v[160:163], v109 offset:64
	s_waitcnt vmcnt(15)
	s_waitcnt lgkmcnt(4)
	v_pk_fma_f32 v[0:1], v[70:71], v[142:143], v[0:1] op_sel_hi:[1,0,1]
	v_pk_fma_f32 v[2:3], v[72:73], v[142:143], v[2:3] op_sel_hi:[1,0,1]
	v_pk_fma_f32 v[4:5], v[70:71], v[142:143], v[4:5] op_sel:[0,1,0]
	v_pk_fma_f32 v[6:7], v[72:73], v[142:143], v[6:7] op_sel:[0,1,0]
	v_pk_fma_f32 v[8:9], v[70:71], v[144:145], v[8:9] op_sel_hi:[1,0,1]
	v_pk_fma_f32 v[10:11], v[72:73], v[144:145], v[10:11] op_sel_hi:[1,0,1]
	v_pk_fma_f32 v[12:13], v[70:71], v[144:145], v[12:13] op_sel:[0,1,0]
	v_pk_fma_f32 v[14:15], v[72:73], v[144:145], v[14:15] op_sel:[0,1,0]
	ds_read_b128 v[164:167], v109 offset:80
	s_waitcnt lgkmcnt(4)
	v_pk_fma_f32 v[16:17], v[70:71], v[146:147], v[16:17] op_sel_hi:[1,0,1]
	v_pk_fma_f32 v[18:19], v[72:73], v[146:147], v[18:19] op_sel_hi:[1,0,1]
	v_pk_fma_f32 v[20:21], v[70:71], v[146:147], v[20:21] op_sel:[0,1,0]
	v_pk_fma_f32 v[22:23], v[72:73], v[146:147], v[22:23] op_sel:[0,1,0]
	v_pk_fma_f32 v[24:25], v[70:71], v[148:149], v[24:25] op_sel_hi:[1,0,1]
	v_pk_fma_f32 v[26:27], v[72:73], v[148:149], v[26:27] op_sel_hi:[1,0,1]
	v_pk_fma_f32 v[28:29], v[70:71], v[148:149], v[28:29] op_sel:[0,1,0]
	v_pk_fma_f32 v[30:31], v[72:73], v[148:149], v[30:31] op_sel:[0,1,0]
	ds_read_b128 v[142:145], v109 offset:96
	s_waitcnt lgkmcnt(4)
	v_pk_fma_f32 v[32:33], v[70:71], v[150:151], v[32:33] op_sel_hi:[1,0,1]
	v_pk_fma_f32 v[34:35], v[72:73], v[150:151], v[34:35] op_sel_hi:[1,0,1]
	v_pk_fma_f32 v[36:37], v[70:71], v[150:151], v[36:37] op_sel:[0,1,0]
	v_pk_fma_f32 v[38:39], v[72:73], v[150:151], v[38:39] op_sel:[0,1,0]
	v_pk_fma_f32 v[40:41], v[70:71], v[152:153], v[40:41] op_sel_hi:[1,0,1]
	v_pk_fma_f32 v[42:43], v[72:73], v[152:153], v[42:43] op_sel_hi:[1,0,1]
	v_pk_fma_f32 v[44:45], v[70:71], v[152:153], v[44:45] op_sel:[0,1,0]
	v_pk_fma_f32 v[46:47], v[72:73], v[152:153], v[46:47] op_sel:[0,1,0]
	ds_read_b128 v[146:149], v109 offset:112
	s_waitcnt lgkmcnt(4)
	v_pk_fma_f32 v[48:49], v[70:71], v[154:155], v[48:49] op_sel_hi:[1,0,1]
	v_pk_fma_f32 v[50:51], v[72:73], v[154:155], v[50:51] op_sel_hi:[1,0,1]
	v_pk_fma_f32 v[52:53], v[70:71], v[154:155], v[52:53] op_sel:[0,1,0]
	v_pk_fma_f32 v[54:55], v[72:73], v[154:155], v[54:55] op_sel:[0,1,0]
	v_pk_fma_f32 v[56:57], v[70:71], v[156:157], v[56:57] op_sel_hi:[1,0,1]
	v_pk_fma_f32 v[58:59], v[72:73], v[156:157], v[58:59] op_sel_hi:[1,0,1]
	v_pk_fma_f32 v[60:61], v[70:71], v[156:157], v[60:61] op_sel:[0,1,0]
	v_pk_fma_f32 v[62:63], v[72:73], v[156:157], v[62:63] op_sel:[0,1,0]
	ds_read_b128 v[150:153], v109 offset:128
	s_waitcnt vmcnt(14)
	s_waitcnt lgkmcnt(4)
	v_pk_fma_f32 v[0:1], v[74:75], v[160:161], v[0:1] op_sel_hi:[1,0,1]
	v_pk_fma_f32 v[2:3], v[76:77], v[160:161], v[2:3] op_sel_hi:[1,0,1]
	v_pk_fma_f32 v[4:5], v[74:75], v[160:161], v[4:5] op_sel:[0,1,0]
	v_pk_fma_f32 v[6:7], v[76:77], v[160:161], v[6:7] op_sel:[0,1,0]
	v_pk_fma_f32 v[8:9], v[74:75], v[162:163], v[8:9] op_sel_hi:[1,0,1]
	v_pk_fma_f32 v[10:11], v[76:77], v[162:163], v[10:11] op_sel_hi:[1,0,1]
	v_pk_fma_f32 v[12:13], v[74:75], v[162:163], v[12:13] op_sel:[0,1,0]
	v_pk_fma_f32 v[14:15], v[76:77], v[162:163], v[14:15] op_sel:[0,1,0]
	ds_read_b128 v[154:157], v109 offset:144
	s_waitcnt lgkmcnt(4)
	v_pk_fma_f32 v[16:17], v[74:75], v[164:165], v[16:17] op_sel_hi:[1,0,1]
	v_pk_fma_f32 v[18:19], v[76:77], v[164:165], v[18:19] op_sel_hi:[1,0,1]
	v_pk_fma_f32 v[20:21], v[74:75], v[164:165], v[20:21] op_sel:[0,1,0]
	v_pk_fma_f32 v[22:23], v[76:77], v[164:165], v[22:23] op_sel:[0,1,0]
	v_pk_fma_f32 v[24:25], v[74:75], v[166:167], v[24:25] op_sel_hi:[1,0,1]
	v_pk_fma_f32 v[26:27], v[76:77], v[166:167], v[26:27] op_sel_hi:[1,0,1]
	v_pk_fma_f32 v[28:29], v[74:75], v[166:167], v[28:29] op_sel:[0,1,0]
	v_pk_fma_f32 v[30:31], v[76:77], v[166:167], v[30:31] op_sel:[0,1,0]
	ds_read_b128 v[160:163], v109 offset:160
	s_waitcnt lgkmcnt(4)
	v_pk_fma_f32 v[32:33], v[74:75], v[142:143], v[32:33] op_sel_hi:[1,0,1]
	v_pk_fma_f32 v[34:35], v[76:77], v[142:143], v[34:35] op_sel_hi:[1,0,1]
	v_pk_fma_f32 v[36:37], v[74:75], v[142:143], v[36:37] op_sel:[0,1,0]
	v_pk_fma_f32 v[38:39], v[76:77], v[142:143], v[38:39] op_sel:[0,1,0]
	v_pk_fma_f32 v[40:41], v[74:75], v[144:145], v[40:41] op_sel_hi:[1,0,1]
	v_pk_fma_f32 v[42:43], v[76:77], v[144:145], v[42:43] op_sel_hi:[1,0,1]
	v_pk_fma_f32 v[44:45], v[74:75], v[144:145], v[44:45] op_sel:[0,1,0]
	v_pk_fma_f32 v[46:47], v[76:77], v[144:145], v[46:47] op_sel:[0,1,0]
	ds_read_b128 v[164:167], v109 offset:176
	s_waitcnt lgkmcnt(4)
; DI void ada_item(const KP& p, int item, float* lds) {
;     ...
;     for (int u = 0; u < 16; ++u) { const f32x4 w = wv[u]; const f32x4* sp = (const f32x4*)(lds + (d0 + dd0 + u) * 16);
; #pragma unroll
;       for (int q = 0; q < 4; ++q) { const f32x4 s = sp[q];
;         acc[4 * q + 0] += w * s[0]; acc[4 * q + 1] += w * s[1]; acc[4 * q + 2] += w * s[2]; acc[4 * q + 3] += w * s[3]; } } }
	v_pk_fma_f32 v[48:49], v[74:75], v[146:147], v[48:49] op_sel_hi:[1,0,1]
	v_pk_fma_f32 v[50:51], v[76:77], v[146:147], v[50:51] op_sel_hi:[1,0,1]
	v_pk_fma_f32 v[52:53], v[74:75], v[146:147], v[52:53] op_sel:[0,1,0]
	v_pk_fma_f32 v[54:55], v[76:77], v[146:147], v[54:55] op_sel:[0,1,0]
	v_pk_fma_f32 v[56:57], v[74:75], v[148:149], v[56:57] op_sel_hi:[1,0,1]
	v_pk_fma_f32 v[58:59], v[76:77], v[148:149], v[58:59] op_sel_hi:[1,0,1]
	v_pk_fma_f32 v[60:61], v[74:75], v[148:149], v[60:61] op_sel:[0,1,0]
	v_pk_fma_f32 v[62:63], v[76:77], v[148:149], v[62:63] op_sel:[0,1,0]
	ds_read_b128 v[142:145], v109 offset:192
	s_waitcnt vmcnt(13)
	s_waitcnt lgkmcnt(4)
	v_pk_fma_f32 v[0:1], v[78:79], v[150:151], v[0:1] op_sel_hi:[1,0,1]
	v_pk_fma_f32 v[2:3], v[80:81], v[150:151], v[2:3] op_sel_hi:[1,0,1]
	v_pk_fma_f32 v[4:5], v[78:79], v[150:151], v[4:5] op_sel:[0,1,0]
	v_pk_fma_f32 v[6:7], v[80:81], v[150:151], v[6:7] op_sel:[0,1,0]
	v_pk_fma_f32 v[8:9], v[78:79], v[152:153], v[8:9] op_sel_hi:[1,0,1]
	v_pk_fma_f32 v[10:11], v[80:81], v[152:153], v[10:11] op_sel_hi:[1,0,1]
	v_pk_fma_f32 v[12:13], v[78:79], v[152:153], v[12:13] op_sel:[0,1,0]
	v_pk_fma_f32 v[14:15], v[80:81], v[152:153], v[14:15] op_sel:[0,1,0]
	ds_read_b128 v[146:149], v109 offset:208
	s_waitcnt lgkmcnt(4)
	v_pk_fma_f32 v[16:17], v[78:79], v[154:155], v[16:17] op_sel_hi:[1,0,1]
	v_pk_fma_f32 v[18:19], v[80:81], v[154:155], v[18:19] op_sel_hi:[1,0,1]
	v_pk_fma_f32 v[20:21], v[78:79], v[154:155], v[20:21] op_sel:[0,1,0]
	v_pk_fma_f32 v[22:23], v[80:81], v[154:155], v[22:23] op_sel:[0,1,0]
	v_pk_fma_f32 v[24:25], v[78:79], v[156:157], v[24:25] op_sel_hi:[1,0,1]
	v_pk_fma_f32 v[26:27], v[80:81], v[156:157], v[26:27] op_sel_hi:[1,0,1]
	v_pk_fma_f32 v[28:29], v[78:79], v[156:157], v[28:29] op_sel:[0,1,0]
	v_pk_fma_f32 v[30:31], v[80:81], v[156:157], v[30:31] op_sel:[0,1,0]
	ds_read_b128 v[150:153], v109 offset:224
	s_waitcnt lgkmcnt(4)
	v_pk_fma_f32 v[32:33], v[78:79], v[160:161], v[32:33] op_sel_hi:[1,0,1]
	v_pk_fma_f32 v[34:35], v[80:81], v[160:161], v[34:35] op_sel_hi:[1,0,1]
	v_pk_fma_f32 v[36:37], v[78:79], v[160:161], v[36:37] op_sel:[0,1,0]
	v_pk_fma_f32 v[38:39], v[80:81], v[160:161], v[38:39] op_sel:[0,1,0]
	v_pk_fma_f32 v[40:41], v[78:79], v[162:163], v[40:41] op_sel_hi:[1,0,1]
	v_pk_fma_f32 v[42:43], v[80:81], v[162:163], v[42:43] op_sel_hi:[1,0,1]
	v_pk_fma_f32 v[44:45], v[78:79], v[162:163], v[44:45] op_sel:[0,1,0]
	v_pk_fma_f32 v[46:47], v[80:81], v[162:163], v[46:47] op_sel:[0,1,0]
	ds_read_b128 v[154:157], v109 offset:240
	s_waitcnt lgkmcnt(4)
	v_pk_fma_f32 v[48:49], v[78:79], v[164:165], v[48:49] op_sel_hi:[1,0,1]
	v_pk_fma_f32 v[50:51], v[80:81], v[164:165], v[50:51] op_sel_hi:[1,0,1]
	v_pk_fma_f32 v[52:53], v[78:79], v[164:165], v[52:53] op_sel:[0,1,0]
	v_pk_fma_f32 v[54:55], v[80:81], v[164:165], v[54:55] op_sel:[0,1,0]
	v_pk_fma_f32 v[56:57], v[78:79], v[166:167], v[56:57] op_sel_hi:[1,0,1]
	v_pk_fma_f32 v[58:59], v[80:81], v[166:167], v[58:59] op_sel_hi:[1,0,1]
	v_pk_fma_f32 v[60:61], v[78:79], v[166:167], v[60:61] op_sel:[0,1,0]
	v_pk_fma_f32 v[62:63], v[80:81], v[166:167], v[62:63] op_sel:[0,1,0]
	ds_read_b128 v[160:163], v109 offset:256
	s_waitcnt vmcnt(12)
	s_waitcnt lgkmcnt(4)
	v_pk_fma_f32 v[0:1], v[82:83], v[142:143], v[0:1] op_sel_hi:[1,0,1]
	v_pk_fma_f32 v[2:3], v[84:85], v[142:143], v[2:3] op_sel_hi:[1,0,1]
	v_pk_fma_f32 v[4:5], v[82:83], v[142:143], v[4:5] op_sel:[0,1,0]
	v_pk_fma_f32 v[6:7], v[84:85], v[142:143], v[6:7] op_sel:[0,1,0]
	v_pk_fma_f32 v[8:9], v[82:83], v[144:145], v[8:9] op_sel_hi:[1,0,1]
	v_pk_fma_f32 v[10:11], v[84:85], v[144:145], v[10:11] op_sel_hi:[1,0,1]
	v_pk_fma_f32 v[12:13], v[82:83], v[144:145], v[12:13] op_sel:[0,1,0]
	v_pk_fma_f32 v[14:15], v[84:85], v[144:145], v[14:15] op_sel:[0,1,0]
	ds_read_b128 v[164:167], v109 offset:272
	s_waitcnt lgkmcnt(4)
	v_pk_fma_f32 v[16:17], v[82:83], v[146:147], v[16:17] op_sel_hi:[1,0,1]
	v_pk_fma_f32 v[18:19], v[84:85], v[146:147], v[18:19] op_sel_hi:[1,0,1]
	v_pk_fma_f32 v[20:21], v[82:83], v[146:147], v[20:21] op_sel:[0,1,0]
	v_pk_fma_f32 v[22:23], v[84:85], v[146:147], v[22:23] op_sel:[0,1,0]
	v_pk_fma_f32 v[24:25], v[82:83], v[148:149], v[24:25] op_sel_hi:[1,0,1]
	v_pk_fma_f32 v[26:27], v[84:85], v[148:149], v[26:27] op_sel_hi:[1,0,1]
	v_pk_fma_f32 v[28:29], v[82:83], v[148:149], v[28:29] op_sel:[0,1,0]
	v_pk_fma_f32 v[30:31], v[84:85], v[148:149], v[30:31] op_sel:[0,1,0]
	ds_read_b128 v[142:145], v109 offset:288
	s_waitcnt lgkmcnt(4)
	v_pk_fma_f32 v[32:33], v[82:83], v[150:151], v[32:33] op_sel_hi:[1,0,1]
	v_pk_fma_f32 v[34:35], v[84:85], v[150:151], v[34:35] op_sel_hi:[1,0,1]
	v_pk_fma_f32 v[36:37], v[82:83], v[150:151], v[36:37] op_sel:[0,1,0]
	v_pk_fma_f32 v[38:39], v[84:85], v[150:151], v[38:39] op_sel:[0,1,0]
	v_pk_fma_f32 v[40:41], v[82:83], v[152:153], v[40:41] op_sel_hi:[1,0,1]
	v_pk_fma_f32 v[42:43], v[84:85], v[152:153], v[42:43] op_sel_hi:[1,0,1]
	v_pk_fma_f32 v[44:45], v[82:83], v[152:153], v[44:45] op_sel:[0,1,0]
	v_pk_fma_f32 v[46:47], v[84:85], v[152:153], v[46:47] op_sel:[0,1,0]
	ds_read_b128 v[146:149], v109 offset:304
	s_waitcnt lgkmcnt(4)
	v_pk_fma_f32 v[48:49], v[82:83], v[154:155], v[48:49] op_sel_hi:[1,0,1]
	v_pk_fma_f32 v[50:51], v[84:85], v[154:155], v[50:51] op_sel_hi:[1,0,1]
	v_pk_fma_f32 v[52:53], v[82:83], v[154:155], v[52:53] op_sel:[0,1,0]
	v_pk_fma_f32 v[54:55], v[84:85], v[154:155], v[54:55] op_sel:[0,1,0]
	v_pk_fma_f32 v[56:57], v[82:83], v[156:157], v[56:57] op_sel_hi:[1,0,1]
	v_pk_fma_f32 v[58:59], v[84:85], v[156:157], v[58:59] op_sel_hi:[1,0,1]
	v_pk_fma_f32 v[60:61], v[82:83], v[156:157], v[60:61] op_sel:[0,1,0]
	v_pk_fma_f32 v[62:63], v[84:85], v[156:157], v[62:63] op_sel:[0,1,0]
	ds_read_b128 v[150:153], v109 offset:320
	s_waitcnt vmcnt(11)
; DI void ada_item(const KP& p, int item, float* lds) {
;     ...
;     for (int u = 0; u < 16; ++u) { const f32x4 w = wv[u]; const f32x4* sp = (const f32x4*)(lds + (d0 + dd0 + u) * 16);
; #pragma unroll
;       for (int q = 0; q < 4; ++q) { const f32x4 s = sp[q];
;         acc[4 * q + 0] += w * s[0]; acc[4 * q + 1] += w * s[1]; acc[4 * q + 2] += w * s[2]; acc[4 * q + 3] += w * s[3]; } } }
	s_waitcnt lgkmcnt(4)
	v_pk_fma_f32 v[0:1], v[86:87], v[160:161], v[0:1] op_sel_hi:[1,0,1]
	v_pk_fma_f32 v[2:3], v[88:89], v[160:161], v[2:3] op_sel_hi:[1,0,1]
	v_pk_fma_f32 v[4:5], v[86:87], v[160:161], v[4:5] op_sel:[0,1,0]
	v_pk_fma_f32 v[6:7], v[88:89], v[160:161], v[6:7] op_sel:[0,1,0]
	v_pk_fma_f32 v[8:9], v[86:87], v[162:163], v[8:9] op_sel_hi:[1,0,1]
	v_pk_fma_f32 v[10:11], v[88:89], v[162:163], v[10:11] op_sel_hi:[1,0,1]
	v_pk_fma_f32 v[12:13], v[86:87], v[162:163], v[12:13] op_sel:[0,1,0]
	v_pk_fma_f32 v[14:15], v[88:89], v[162:163], v[14:15] op_sel:[0,1,0]
	ds_read_b128 v[154:157], v109 offset:336
	s_waitcnt lgkmcnt(4)
	v_pk_fma_f32 v[16:17], v[86:87], v[164:165], v[16:17] op_sel_hi:[1,0,1]
	v_pk_fma_f32 v[18:19], v[88:89], v[164:165], v[18:19] op_sel_hi:[1,0,1]
	v_pk_fma_f32 v[20:21], v[86:87], v[164:165], v[20:21] op_sel:[0,1,0]
	v_pk_fma_f32 v[22:23], v[88:89], v[164:165], v[22:23] op_sel:[0,1,0]
	v_pk_fma_f32 v[24:25], v[86:87], v[166:167], v[24:25] op_sel_hi:[1,0,1]
	v_pk_fma_f32 v[26:27], v[88:89], v[166:167], v[26:27] op_sel_hi:[1,0,1]
	v_pk_fma_f32 v[28:29], v[86:87], v[166:167], v[28:29] op_sel:[0,1,0]
	v_pk_fma_f32 v[30:31], v[88:89], v[166:167], v[30:31] op_sel:[0,1,0]
	ds_read_b128 v[160:163], v109 offset:352
	s_waitcnt lgkmcnt(4)
	v_pk_fma_f32 v[32:33], v[86:87], v[142:143], v[32:33] op_sel_hi:[1,0,1]
	v_pk_fma_f32 v[34:35], v[88:89], v[142:143], v[34:35] op_sel_hi:[1,0,1]
	v_pk_fma_f32 v[36:37], v[86:87], v[142:143], v[36:37] op_sel:[0,1,0]
	v_pk_fma_f32 v[38:39], v[88:89], v[142:143], v[38:39] op_sel:[0,1,0]
	v_pk_fma_f32 v[40:41], v[86:87], v[144:145], v[40:41] op_sel_hi:[1,0,1]
	v_pk_fma_f32 v[42:43], v[88:89], v[144:145], v[42:43] op_sel_hi:[1,0,1]
	v_pk_fma_f32 v[44:45], v[86:87], v[144:145], v[44:45] op_sel:[0,1,0]
	v_pk_fma_f32 v[46:47], v[88:89], v[144:145], v[46:47] op_sel:[0,1,0]
	ds_read_b128 v[164:167], v109 offset:368
	s_waitcnt lgkmcnt(4)
	v_pk_fma_f32 v[48:49], v[86:87], v[146:147], v[48:49] op_sel_hi:[1,0,1]
	v_pk_fma_f32 v[50:51], v[88:89], v[146:147], v[50:51] op_sel_hi:[1,0,1]
	v_pk_fma_f32 v[52:53], v[86:87], v[146:147], v[52:53] op_sel:[0,1,0]
	v_pk_fma_f32 v[54:55], v[88:89], v[146:147], v[54:55] op_sel:[0,1,0]
	v_pk_fma_f32 v[56:57], v[86:87], v[148:149], v[56:57] op_sel_hi:[1,0,1]
	v_pk_fma_f32 v[58:59], v[88:89], v[148:149], v[58:59] op_sel_hi:[1,0,1]
	v_pk_fma_f32 v[60:61], v[86:87], v[148:149], v[60:61] op_sel:[0,1,0]
	v_pk_fma_f32 v[62:63], v[88:89], v[148:149], v[62:63] op_sel:[0,1,0]
	ds_read_b128 v[142:145], v109 offset:384
	s_waitcnt vmcnt(10)
	s_waitcnt lgkmcnt(4)
	v_pk_fma_f32 v[0:1], v[90:91], v[150:151], v[0:1] op_sel_hi:[1,0,1]
	v_pk_fma_f32 v[2:3], v[92:93], v[150:151], v[2:3] op_sel_hi:[1,0,1]
	v_pk_fma_f32 v[4:5], v[90:91], v[150:151], v[4:5] op_sel:[0,1,0]
	v_pk_fma_f32 v[6:7], v[92:93], v[150:151], v[6:7] op_sel:[0,1,0]
	v_pk_fma_f32 v[8:9], v[90:91], v[152:153], v[8:9] op_sel_hi:[1,0,1]
	v_pk_fma_f32 v[10:11], v[92:93], v[152:153], v[10:11] op_sel_hi:[1,0,1]
	v_pk_fma_f32 v[12:13], v[90:91], v[152:153], v[12:13] op_sel:[0,1,0]
	v_pk_fma_f32 v[14:15], v[92:93], v[152:153], v[14:15] op_sel:[0,1,0]
	ds_read_b128 v[146:149], v109 offset:400
	s_waitcnt lgkmcnt(4)
	v_pk_fma_f32 v[16:17], v[90:91], v[154:155], v[16:17] op_sel_hi:[1,0,1]
	v_pk_fma_f32 v[18:19], v[92:93], v[154:155], v[18:19] op_sel_hi:[1,0,1]
	v_pk_fma_f32 v[20:21], v[90:91], v[154:155], v[20:21] op_sel:[0,1,0]
	v_pk_fma_f32 v[22:23], v[92:93], v[154:155], v[22:23] op_sel:[0,1,0]
	v_pk_fma_f32 v[24:25], v[90:91], v[156:157], v[24:25] op_sel_hi:[1,0,1]
	v_pk_fma_f32 v[26:27], v[92:93], v[156:157], v[26:27] op_sel_hi:[1,0,1]
	v_pk_fma_f32 v[28:29], v[90:91], v[156:157], v[28:29] op_sel:[0,1,0]
	v_pk_fma_f32 v[30:31], v[92:93], v[156:157], v[30:31] op_sel:[0,1,0]
	ds_read_b128 v[150:153], v109 offset:416
	s_waitcnt lgkmcnt(4)
	v_pk_fma_f32 v[32:33], v[90:91], v[160:161], v[32:33] op_sel_hi:[1,0,1]
	v_pk_fma_f32 v[34:35], v[92:93], v[160:161], v[34:35] op_sel_hi:[1,0,1]
	v_pk_fma_f32 v[36:37], v[90:91], v[160:161], v[36:37] op_sel:[0,1,0]
	v_pk_fma_f32 v[38:39], v[92:93], v[160:161], v[38:39] op_sel:[0,1,0]
	v_pk_fma_f32 v[40:41], v[90:91], v[162:163], v[40:41] op_sel_hi:[1,0,1]
	v_pk_fma_f32 v[42:43], v[92:93], v[162:163], v[42:43] op_sel_hi:[1,0,1]
	v_pk_fma_f32 v[44:45], v[90:91], v[162:163], v[44:45] op_sel:[0,1,0]
	v_pk_fma_f32 v[46:47], v[92:93], v[162:163], v[46:47] op_sel:[0,1,0]
	ds_read_b128 v[154:157], v109 offset:432
	s_waitcnt lgkmcnt(4)
	v_pk_fma_f32 v[48:49], v[90:91], v[164:165], v[48:49] op_sel_hi:[1,0,1]
	v_pk_fma_f32 v[50:51], v[92:93], v[164:165], v[50:51] op_sel_hi:[1,0,1]
	v_pk_fma_f32 v[52:53], v[90:91], v[164:165], v[52:53] op_sel:[0,1,0]
	v_pk_fma_f32 v[54:55], v[92:93], v[164:165], v[54:55] op_sel:[0,1,0]
	v_pk_fma_f32 v[56:57], v[90:91], v[166:167], v[56:57] op_sel_hi:[1,0,1]
	v_pk_fma_f32 v[58:59], v[92:93], v[166:167], v[58:59] op_sel_hi:[1,0,1]
	v_pk_fma_f32 v[60:61], v[90:91], v[166:167], v[60:61] op_sel:[0,1,0]
	v_pk_fma_f32 v[62:63], v[92:93], v[166:167], v[62:63] op_sel:[0,1,0]
	ds_read_b128 v[160:163], v109 offset:448
	s_waitcnt vmcnt(9)
	s_waitcnt lgkmcnt(4)
	v_pk_fma_f32 v[0:1], v[94:95], v[142:143], v[0:1] op_sel_hi:[1,0,1]
	v_pk_fma_f32 v[2:3], v[96:97], v[142:143], v[2:3] op_sel_hi:[1,0,1]
	v_pk_fma_f32 v[4:5], v[94:95], v[142:143], v[4:5] op_sel:[0,1,0]
	v_pk_fma_f32 v[6:7], v[96:97], v[142:143], v[6:7] op_sel:[0,1,0]
	v_pk_fma_f32 v[8:9], v[94:95], v[144:145], v[8:9] op_sel_hi:[1,0,1]
	v_pk_fma_f32 v[10:11], v[96:97], v[144:145], v[10:11] op_sel_hi:[1,0,1]
	v_pk_fma_f32 v[12:13], v[94:95], v[144:145], v[12:13] op_sel:[0,1,0]
	v_pk_fma_f32 v[14:15], v[96:97], v[144:145], v[14:15] op_sel:[0,1,0]
	ds_read_b128 v[164:167], v109 offset:464
	s_waitcnt lgkmcnt(4)
; DI void ada_item(const KP& p, int item, float* lds) {
;     ...
;     for (int u = 0; u < 16; ++u) { const f32x4 w = wv[u]; const f32x4* sp = (const f32x4*)(lds + (d0 + dd0 + u) * 16);
; #pragma unroll
;       for (int q = 0; q < 4; ++q) { const f32x4 s = sp[q];
;         acc[4 * q + 0] += w * s[0]; acc[4 * q + 1] += w * s[1]; acc[4 * q + 2] += w * s[2]; acc[4 * q + 3] += w * s[3]; } } }
	v_pk_fma_f32 v[16:17], v[94:95], v[146:147], v[16:17] op_sel_hi:[1,0,1]
	v_pk_fma_f32 v[18:19], v[96:97], v[146:147], v[18:19] op_sel_hi:[1,0,1]
	v_pk_fma_f32 v[20:21], v[94:95], v[146:147], v[20:21] op_sel:[0,1,0]
	v_pk_fma_f32 v[22:23], v[96:97], v[146:147], v[22:23] op_sel:[0,1,0]
	v_pk_fma_f32 v[24:25], v[94:95], v[148:149], v[24:25] op_sel_hi:[1,0,1]
	v_pk_fma_f32 v[26:27], v[96:97], v[148:149], v[26:27] op_sel_hi:[1,0,1]
	v_pk_fma_f32 v[28:29], v[94:95], v[148:149], v[28:29] op_sel:[0,1,0]
	v_pk_fma_f32 v[30:31], v[96:97], v[148:149], v[30:31] op_sel:[0,1,0]
	ds_read_b128 v[142:145], v109 offset:480
	s_waitcnt lgkmcnt(4)
	v_pk_fma_f32 v[32:33], v[94:95], v[150:151], v[32:33] op_sel_hi:[1,0,1]
	v_pk_fma_f32 v[34:35], v[96:97], v[150:151], v[34:35] op_sel_hi:[1,0,1]
	v_pk_fma_f32 v[36:37], v[94:95], v[150:151], v[36:37] op_sel:[0,1,0]
	v_pk_fma_f32 v[38:39], v[96:97], v[150:151], v[38:39] op_sel:[0,1,0]
	v_pk_fma_f32 v[40:41], v[94:95], v[152:153], v[40:41] op_sel_hi:[1,0,1]
	v_pk_fma_f32 v[42:43], v[96:97], v[152:153], v[42:43] op_sel_hi:[1,0,1]
	v_pk_fma_f32 v[44:45], v[94:95], v[152:153], v[44:45] op_sel:[0,1,0]
	v_pk_fma_f32 v[46:47], v[96:97], v[152:153], v[46:47] op_sel:[0,1,0]
	ds_read_b128 v[146:149], v109 offset:496
	s_waitcnt lgkmcnt(4)
	v_pk_fma_f32 v[48:49], v[94:95], v[154:155], v[48:49] op_sel_hi:[1,0,1]
	v_pk_fma_f32 v[50:51], v[96:97], v[154:155], v[50:51] op_sel_hi:[1,0,1]
	v_pk_fma_f32 v[52:53], v[94:95], v[154:155], v[52:53] op_sel:[0,1,0]
	v_pk_fma_f32 v[54:55], v[96:97], v[154:155], v[54:55] op_sel:[0,1,0]
	v_pk_fma_f32 v[56:57], v[94:95], v[156:157], v[56:57] op_sel_hi:[1,0,1]
	v_pk_fma_f32 v[58:59], v[96:97], v[156:157], v[58:59] op_sel_hi:[1,0,1]
	v_pk_fma_f32 v[60:61], v[94:95], v[156:157], v[60:61] op_sel:[0,1,0]
	v_pk_fma_f32 v[62:63], v[96:97], v[156:157], v[62:63] op_sel:[0,1,0]
	s_waitcnt vmcnt(8)
	s_waitcnt lgkmcnt(3)
	v_pk_fma_f32 v[0:1], v[98:99], v[160:161], v[0:1] op_sel_hi:[1,0,1]
	v_pk_fma_f32 v[2:3], v[100:101], v[160:161], v[2:3] op_sel_hi:[1,0,1]
	v_pk_fma_f32 v[4:5], v[98:99], v[160:161], v[4:5] op_sel:[0,1,0]
	v_pk_fma_f32 v[6:7], v[100:101], v[160:161], v[6:7] op_sel:[0,1,0]
	v_pk_fma_f32 v[8:9], v[98:99], v[162:163], v[8:9] op_sel_hi:[1,0,1]
	v_pk_fma_f32 v[10:11], v[100:101], v[162:163], v[10:11] op_sel_hi:[1,0,1]
	v_pk_fma_f32 v[12:13], v[98:99], v[162:163], v[12:13] op_sel:[0,1,0]
	v_pk_fma_f32 v[14:15], v[100:101], v[162:163], v[14:15] op_sel:[0,1,0]
	s_waitcnt lgkmcnt(2)
	v_pk_fma_f32 v[16:17], v[98:99], v[164:165], v[16:17] op_sel_hi:[1,0,1]
	v_pk_fma_f32 v[18:19], v[100:101], v[164:165], v[18:19] op_sel_hi:[1,0,1]
	v_pk_fma_f32 v[20:21], v[98:99], v[164:165], v[20:21] op_sel:[0,1,0]
	v_pk_fma_f32 v[22:23], v[100:101], v[164:165], v[22:23] op_sel:[0,1,0]
	v_pk_fma_f32 v[24:25], v[98:99], v[166:167], v[24:25] op_sel_hi:[1,0,1]
	v_pk_fma_f32 v[26:27], v[100:101], v[166:167], v[26:27] op_sel_hi:[1,0,1]
	v_pk_fma_f32 v[28:29], v[98:99], v[166:167], v[28:29] op_sel:[0,1,0]
	v_pk_fma_f32 v[30:31], v[100:101], v[166:167], v[30:31] op_sel:[0,1,0]
	s_waitcnt lgkmcnt(1)
	v_pk_fma_f32 v[32:33], v[98:99], v[142:143], v[32:33] op_sel_hi:[1,0,1]
	v_pk_fma_f32 v[34:35], v[100:101], v[142:143], v[34:35] op_sel_hi:[1,0,1]
	v_pk_fma_f32 v[36:37], v[98:99], v[142:143], v[36:37] op_sel:[0,1,0]
	v_pk_fma_f32 v[38:39], v[100:101], v[142:143], v[38:39] op_sel:[0,1,0]
	v_pk_fma_f32 v[40:41], v[98:99], v[144:145], v[40:41] op_sel_hi:[1,0,1]
	v_pk_fma_f32 v[42:43], v[100:101], v[144:145], v[42:43] op_sel_hi:[1,0,1]
	v_pk_fma_f32 v[44:45], v[98:99], v[144:145], v[44:45] op_sel:[0,1,0]
	v_pk_fma_f32 v[46:47], v[100:101], v[144:145], v[46:47] op_sel:[0,1,0]
	s_waitcnt lgkmcnt(0)
	v_pk_fma_f32 v[48:49], v[98:99], v[146:147], v[48:49] op_sel_hi:[1,0,1]
	v_pk_fma_f32 v[50:51], v[100:101], v[146:147], v[50:51] op_sel_hi:[1,0,1]
	v_pk_fma_f32 v[52:53], v[98:99], v[146:147], v[52:53] op_sel:[0,1,0]
	v_pk_fma_f32 v[54:55], v[100:101], v[146:147], v[54:55] op_sel:[0,1,0]
	v_pk_fma_f32 v[56:57], v[98:99], v[148:149], v[56:57] op_sel_hi:[1,0,1]
	v_pk_fma_f32 v[58:59], v[100:101], v[148:149], v[58:59] op_sel_hi:[1,0,1]
	v_pk_fma_f32 v[60:61], v[98:99], v[148:149], v[60:61] op_sel:[0,1,0]
	v_pk_fma_f32 v[62:63], v[100:101], v[148:149], v[62:63] op_sel:[0,1,0]
	global_load_dwordx4 v[70:73], v[158:159], off
	v_lshl_add_u64 v[64:65], v[158:159], 0, s[20:21]
	global_load_dwordx4 v[74:77], v[64:65], off
	v_lshl_add_u64 v[66:67], v[64:65], 0, s[20:21]
	global_load_dwordx4 v[78:81], v[66:67], off
	v_lshl_add_u64 v[64:65], v[66:67], 0, s[20:21]
	global_load_dwordx4 v[82:85], v[64:65], off
	v_lshl_add_u64 v[66:67], v[64:65], 0, s[20:21]
	global_load_dwordx4 v[86:89], v[66:67], off
	v_lshl_add_u64 v[64:65], v[66:67], 0, s[20:21]
	global_load_dwordx4 v[90:93], v[64:65], off
	v_lshl_add_u64 v[66:67], v[64:65], 0, s[20:21]
	global_load_dwordx4 v[94:97], v[66:67], off
	v_lshl_add_u64 v[64:65], v[66:67], 0, s[20:21]
	global_load_dwordx4 v[98:101], v[64:65], off
	v_lshl_add_u64 v[158:159], v[64:65], 0, s[20:21]
	ds_read_b128 v[142:145], v109 offset:512
	ds_read_b128 v[146:149], v109 offset:528
	ds_read_b128 v[150:153], v109 offset:544
	ds_read_b128 v[154:157], v109 offset:560
	ds_read_b128 v[160:163], v109 offset:576
	s_waitcnt vmcnt(15)
	s_waitcnt lgkmcnt(4)
	v_pk_fma_f32 v[0:1], v[110:111], v[142:143], v[0:1] op_sel_hi:[1,0,1]
	v_pk_fma_f32 v[2:3], v[112:113], v[142:143], v[2:3] op_sel_hi:[1,0,1]
	v_pk_fma_f32 v[4:5], v[110:111], v[142:143], v[4:5] op_sel:[0,1,0]
	v_pk_fma_f32 v[6:7], v[112:113], v[142:143], v[6:7] op_sel:[0,1,0]
	v_pk_fma_f32 v[8:9], v[110:111], v[144:145], v[8:9] op_sel_hi:[1,0,1]
	v_pk_fma_f32 v[10:11], v[112:113], v[144:145], v[10:11] op_sel_hi:[1,0,1]
	v_pk_fma_f32 v[12:13], v[110:111], v[144:145], v[12:13] op_sel:[0,1,0]
	v_pk_fma_f32 v[14:15], v[112:113], v[144:145], v[14:15] op_sel:[0,1,0]
	ds_read_b128 v[164:167], v109 offset:592
	s_waitcnt lgkmcnt(4)
; DI void ada_item(const KP& p, int item, float* lds) {
;     ...
;     for (int u = 0; u < 16; ++u) { const f32x4 w = wv[u]; const f32x4* sp = (const f32x4*)(lds + (d0 + dd0 + u) * 16);
; #pragma unroll
;       for (int q = 0; q < 4; ++q) { const f32x4 s = sp[q];
;         acc[4 * q + 0] += w * s[0]; acc[4 * q + 1] += w * s[1]; acc[4 * q + 2] += w * s[2]; acc[4 * q + 3] += w * s[3]; } } }
	v_pk_fma_f32 v[16:17], v[110:111], v[146:147], v[16:17] op_sel_hi:[1,0,1]
	v_pk_fma_f32 v[18:19], v[112:113], v[146:147], v[18:19] op_sel_hi:[1,0,1]
	v_pk_fma_f32 v[20:21], v[110:111], v[146:147], v[20:21] op_sel:[0,1,0]
	v_pk_fma_f32 v[22:23], v[112:113], v[146:147], v[22:23] op_sel:[0,1,0]
	v_pk_fma_f32 v[24:25], v[110:111], v[148:149], v[24:25] op_sel_hi:[1,0,1]
	v_pk_fma_f32 v[26:27], v[112:113], v[148:149], v[26:27] op_sel_hi:[1,0,1]
	v_pk_fma_f32 v[28:29], v[110:111], v[148:149], v[28:29] op_sel:[0,1,0]
	v_pk_fma_f32 v[30:31], v[112:113], v[148:149], v[30:31] op_sel:[0,1,0]
	ds_read_b128 v[142:145], v109 offset:608
	s_waitcnt lgkmcnt(4)
	v_pk_fma_f32 v[32:33], v[110:111], v[150:151], v[32:33] op_sel_hi:[1,0,1]
	v_pk_fma_f32 v[34:35], v[112:113], v[150:151], v[34:35] op_sel_hi:[1,0,1]
	v_pk_fma_f32 v[36:37], v[110:111], v[150:151], v[36:37] op_sel:[0,1,0]
	v_pk_fma_f32 v[38:39], v[112:113], v[150:151], v[38:39] op_sel:[0,1,0]
	v_pk_fma_f32 v[40:41], v[110:111], v[152:153], v[40:41] op_sel_hi:[1,0,1]
	v_pk_fma_f32 v[42:43], v[112:113], v[152:153], v[42:43] op_sel_hi:[1,0,1]
	v_pk_fma_f32 v[44:45], v[110:111], v[152:153], v[44:45] op_sel:[0,1,0]
	v_pk_fma_f32 v[46:47], v[112:113], v[152:153], v[46:47] op_sel:[0,1,0]
	ds_read_b128 v[146:149], v109 offset:624
	s_waitcnt lgkmcnt(4)
	v_pk_fma_f32 v[48:49], v[110:111], v[154:155], v[48:49] op_sel_hi:[1,0,1]
	v_pk_fma_f32 v[50:51], v[112:113], v[154:155], v[50:51] op_sel_hi:[1,0,1]
	v_pk_fma_f32 v[52:53], v[110:111], v[154:155], v[52:53] op_sel:[0,1,0]
	v_pk_fma_f32 v[54:55], v[112:113], v[154:155], v[54:55] op_sel:[0,1,0]
	v_pk_fma_f32 v[56:57], v[110:111], v[156:157], v[56:57] op_sel_hi:[1,0,1]
	v_pk_fma_f32 v[58:59], v[112:113], v[156:157], v[58:59] op_sel_hi:[1,0,1]
	v_pk_fma_f32 v[60:61], v[110:111], v[156:157], v[60:61] op_sel:[0,1,0]
	v_pk_fma_f32 v[62:63], v[112:113], v[156:157], v[62:63] op_sel:[0,1,0]
	ds_read_b128 v[150:153], v109 offset:640
	s_waitcnt vmcnt(14)
	s_waitcnt lgkmcnt(4)
	v_pk_fma_f32 v[0:1], v[114:115], v[160:161], v[0:1] op_sel_hi:[1,0,1]
	v_pk_fma_f32 v[2:3], v[116:117], v[160:161], v[2:3] op_sel_hi:[1,0,1]
	v_pk_fma_f32 v[4:5], v[114:115], v[160:161], v[4:5] op_sel:[0,1,0]
	v_pk_fma_f32 v[6:7], v[116:117], v[160:161], v[6:7] op_sel:[0,1,0]
	v_pk_fma_f32 v[8:9], v[114:115], v[162:163], v[8:9] op_sel_hi:[1,0,1]
	v_pk_fma_f32 v[10:11], v[116:117], v[162:163], v[10:11] op_sel_hi:[1,0,1]
	v_pk_fma_f32 v[12:13], v[114:115], v[162:163], v[12:13] op_sel:[0,1,0]
	v_pk_fma_f32 v[14:15], v[116:117], v[162:163], v[14:15] op_sel:[0,1,0]
	ds_read_b128 v[154:157], v109 offset:656
	s_waitcnt lgkmcnt(4)
	v_pk_fma_f32 v[16:17], v[114:115], v[164:165], v[16:17] op_sel_hi:[1,0,1]
	v_pk_fma_f32 v[18:19], v[116:117], v[164:165], v[18:19] op_sel_hi:[1,0,1]
	v_pk_fma_f32 v[20:21], v[114:115], v[164:165], v[20:21] op_sel:[0,1,0]
	v_pk_fma_f32 v[22:23], v[116:117], v[164:165], v[22:23] op_sel:[0,1,0]
	v_pk_fma_f32 v[24:25], v[114:115], v[166:167], v[24:25] op_sel_hi:[1,0,1]
	v_pk_fma_f32 v[26:27], v[116:117], v[166:167], v[26:27] op_sel_hi:[1,0,1]
	v_pk_fma_f32 v[28:29], v[114:115], v[166:167], v[28:29] op_sel:[0,1,0]
	v_pk_fma_f32 v[30:31], v[116:117], v[166:167], v[30:31] op_sel:[0,1,0]
	ds_read_b128 v[160:163], v109 offset:672
	s_waitcnt lgkmcnt(4)
	v_pk_fma_f32 v[32:33], v[114:115], v[142:143], v[32:33] op_sel_hi:[1,0,1]
	v_pk_fma_f32 v[34:35], v[116:117], v[142:143], v[34:35] op_sel_hi:[1,0,1]
	v_pk_fma_f32 v[36:37], v[114:115], v[142:143], v[36:37] op_sel:[0,1,0]
	v_pk_fma_f32 v[38:39], v[116:117], v[142:143], v[38:39] op_sel:[0,1,0]
	v_pk_fma_f32 v[40:41], v[114:115], v[144:145], v[40:41] op_sel_hi:[1,0,1]
	v_pk_fma_f32 v[42:43], v[116:117], v[144:145], v[42:43] op_sel_hi:[1,0,1]
	v_pk_fma_f32 v[44:45], v[114:115], v[144:145], v[44:45] op_sel:[0,1,0]
	v_pk_fma_f32 v[46:47], v[116:117], v[144:145], v[46:47] op_sel:[0,1,0]
	ds_read_b128 v[164:167], v109 offset:688
	s_waitcnt lgkmcnt(4)
	v_pk_fma_f32 v[48:49], v[114:115], v[146:147], v[48:49] op_sel_hi:[1,0,1]
	v_pk_fma_f32 v[50:51], v[116:117], v[146:147], v[50:51] op_sel_hi:[1,0,1]
	v_pk_fma_f32 v[52:53], v[114:115], v[146:147], v[52:53] op_sel:[0,1,0]
	v_pk_fma_f32 v[54:55], v[116:117], v[146:147], v[54:55] op_sel:[0,1,0]
	v_pk_fma_f32 v[56:57], v[114:115], v[148:149], v[56:57] op_sel_hi:[1,0,1]
	v_pk_fma_f32 v[58:59], v[116:117], v[148:149], v[58:59] op_sel_hi:[1,0,1]
	v_pk_fma_f32 v[60:61], v[114:115], v[148:149], v[60:61] op_sel:[0,1,0]
	v_pk_fma_f32 v[62:63], v[116:117], v[148:149], v[62:63] op_sel:[0,1,0]
	ds_read_b128 v[142:145], v109 offset:704
	s_waitcnt vmcnt(13)
	s_waitcnt lgkmcnt(4)
	v_pk_fma_f32 v[0:1], v[118:119], v[150:151], v[0:1] op_sel_hi:[1,0,1]
	v_pk_fma_f32 v[2:3], v[120:121], v[150:151], v[2:3] op_sel_hi:[1,0,1]
	v_pk_fma_f32 v[4:5], v[118:119], v[150:151], v[4:5] op_sel:[0,1,0]
	v_pk_fma_f32 v[6:7], v[120:121], v[150:151], v[6:7] op_sel:[0,1,0]
	v_pk_fma_f32 v[8:9], v[118:119], v[152:153], v[8:9] op_sel_hi:[1,0,1]
	v_pk_fma_f32 v[10:11], v[120:121], v[152:153], v[10:11] op_sel_hi:[1,0,1]
	v_pk_fma_f32 v[12:13], v[118:119], v[152:153], v[12:13] op_sel:[0,1,0]
	v_pk_fma_f32 v[14:15], v[120:121], v[152:153], v[14:15] op_sel:[0,1,0]
	ds_read_b128 v[146:149], v109 offset:720
	s_waitcnt lgkmcnt(4)
	v_pk_fma_f32 v[16:17], v[118:119], v[154:155], v[16:17] op_sel_hi:[1,0,1]
	v_pk_fma_f32 v[18:19], v[120:121], v[154:155], v[18:19] op_sel_hi:[1,0,1]
	v_pk_fma_f32 v[20:21], v[118:119], v[154:155], v[20:21] op_sel:[0,1,0]
	v_pk_fma_f32 v[22:23], v[120:121], v[154:155], v[22:23] op_sel:[0,1,0]
	v_pk_fma_f32 v[24:25], v[118:119], v[156:157], v[24:25] op_sel_hi:[1,0,1]
	v_pk_fma_f32 v[26:27], v[120:121], v[156:157], v[26:27] op_sel_hi:[1,0,1]
	v_pk_fma_f32 v[28:29], v[118:119], v[156:157], v[28:29] op_sel:[0,1,0]
	v_pk_fma_f32 v[30:31], v[120:121], v[156:157], v[30:31] op_sel:[0,1,0]
	ds_read_b128 v[150:153], v109 offset:736
	s_waitcnt lgkmcnt(4)
; DI void ada_item(const KP& p, int item, float* lds) {
;     ...
;     for (int u = 0; u < 16; ++u) { const f32x4 w = wv[u]; const f32x4* sp = (const f32x4*)(lds + (d0 + dd0 + u) * 16);
; #pragma unroll
;       for (int q = 0; q < 4; ++q) { const f32x4 s = sp[q];
;         acc[4 * q + 0] += w * s[0]; acc[4 * q + 1] += w * s[1]; acc[4 * q + 2] += w * s[2]; acc[4 * q + 3] += w * s[3]; } } }
	v_pk_fma_f32 v[32:33], v[118:119], v[160:161], v[32:33] op_sel_hi:[1,0,1]
	v_pk_fma_f32 v[34:35], v[120:121], v[160:161], v[34:35] op_sel_hi:[1,0,1]
	v_pk_fma_f32 v[36:37], v[118:119], v[160:161], v[36:37] op_sel:[0,1,0]
	v_pk_fma_f32 v[38:39], v[120:121], v[160:161], v[38:39] op_sel:[0,1,0]
	v_pk_fma_f32 v[40:41], v[118:119], v[162:163], v[40:41] op_sel_hi:[1,0,1]
	v_pk_fma_f32 v[42:43], v[120:121], v[162:163], v[42:43] op_sel_hi:[1,0,1]
	v_pk_fma_f32 v[44:45], v[118:119], v[162:163], v[44:45] op_sel:[0,1,0]
	v_pk_fma_f32 v[46:47], v[120:121], v[162:163], v[46:47] op_sel:[0,1,0]
	ds_read_b128 v[154:157], v109 offset:752
	s_waitcnt lgkmcnt(4)
	v_pk_fma_f32 v[48:49], v[118:119], v[164:165], v[48:49] op_sel_hi:[1,0,1]
	v_pk_fma_f32 v[50:51], v[120:121], v[164:165], v[50:51] op_sel_hi:[1,0,1]
	v_pk_fma_f32 v[52:53], v[118:119], v[164:165], v[52:53] op_sel:[0,1,0]
	v_pk_fma_f32 v[54:55], v[120:121], v[164:165], v[54:55] op_sel:[0,1,0]
	v_pk_fma_f32 v[56:57], v[118:119], v[166:167], v[56:57] op_sel_hi:[1,0,1]
	v_pk_fma_f32 v[58:59], v[120:121], v[166:167], v[58:59] op_sel_hi:[1,0,1]
	v_pk_fma_f32 v[60:61], v[118:119], v[166:167], v[60:61] op_sel:[0,1,0]
	v_pk_fma_f32 v[62:63], v[120:121], v[166:167], v[62:63] op_sel:[0,1,0]
	ds_read_b128 v[160:163], v109 offset:768
	s_waitcnt vmcnt(12)
	s_waitcnt lgkmcnt(4)
	v_pk_fma_f32 v[0:1], v[122:123], v[142:143], v[0:1] op_sel_hi:[1,0,1]
	v_pk_fma_f32 v[2:3], v[124:125], v[142:143], v[2:3] op_sel_hi:[1,0,1]
	v_pk_fma_f32 v[4:5], v[122:123], v[142:143], v[4:5] op_sel:[0,1,0]
	v_pk_fma_f32 v[6:7], v[124:125], v[142:143], v[6:7] op_sel:[0,1,0]
	v_pk_fma_f32 v[8:9], v[122:123], v[144:145], v[8:9] op_sel_hi:[1,0,1]
	v_pk_fma_f32 v[10:11], v[124:125], v[144:145], v[10:11] op_sel_hi:[1,0,1]
	v_pk_fma_f32 v[12:13], v[122:123], v[144:145], v[12:13] op_sel:[0,1,0]
	v_pk_fma_f32 v[14:15], v[124:125], v[144:145], v[14:15] op_sel:[0,1,0]
	ds_read_b128 v[164:167], v109 offset:784
	s_waitcnt lgkmcnt(4)
	v_pk_fma_f32 v[16:17], v[122:123], v[146:147], v[16:17] op_sel_hi:[1,0,1]
	v_pk_fma_f32 v[18:19], v[124:125], v[146:147], v[18:19] op_sel_hi:[1,0,1]
	v_pk_fma_f32 v[20:21], v[122:123], v[146:147], v[20:21] op_sel:[0,1,0]
	v_pk_fma_f32 v[22:23], v[124:125], v[146:147], v[22:23] op_sel:[0,1,0]
	v_pk_fma_f32 v[24:25], v[122:123], v[148:149], v[24:25] op_sel_hi:[1,0,1]
	v_pk_fma_f32 v[26:27], v[124:125], v[148:149], v[26:27] op_sel_hi:[1,0,1]
	v_pk_fma_f32 v[28:29], v[122:123], v[148:149], v[28:29] op_sel:[0,1,0]
	v_pk_fma_f32 v[30:31], v[124:125], v[148:149], v[30:31] op_sel:[0,1,0]
	ds_read_b128 v[142:145], v109 offset:800
	s_waitcnt lgkmcnt(4)
	v_pk_fma_f32 v[32:33], v[122:123], v[150:151], v[32:33] op_sel_hi:[1,0,1]
	v_pk_fma_f32 v[34:35], v[124:125], v[150:151], v[34:35] op_sel_hi:[1,0,1]
	v_pk_fma_f32 v[36:37], v[122:123], v[150:151], v[36:37] op_sel:[0,1,0]
	v_pk_fma_f32 v[38:39], v[124:125], v[150:151], v[38:39] op_sel:[0,1,0]
	v_pk_fma_f32 v[40:41], v[122:123], v[152:153], v[40:41] op_sel_hi:[1,0,1]
	v_pk_fma_f32 v[42:43], v[124:125], v[152:153], v[42:43] op_sel_hi:[1,0,1]
	v_pk_fma_f32 v[44:45], v[122:123], v[152:153], v[44:45] op_sel:[0,1,0]
	v_pk_fma_f32 v[46:47], v[124:125], v[152:153], v[46:47] op_sel:[0,1,0]
	ds_read_b128 v[146:149], v109 offset:816
	s_waitcnt lgkmcnt(4)
	v_pk_fma_f32 v[48:49], v[122:123], v[154:155], v[48:49] op_sel_hi:[1,0,1]
	v_pk_fma_f32 v[50:51], v[124:125], v[154:155], v[50:51] op_sel_hi:[1,0,1]
	v_pk_fma_f32 v[52:53], v[122:123], v[154:155], v[52:53] op_sel:[0,1,0]
	v_pk_fma_f32 v[54:55], v[124:125], v[154:155], v[54:55] op_sel:[0,1,0]
	v_pk_fma_f32 v[56:57], v[122:123], v[156:157], v[56:57] op_sel_hi:[1,0,1]
	v_pk_fma_f32 v[58:59], v[124:125], v[156:157], v[58:59] op_sel_hi:[1,0,1]
	v_pk_fma_f32 v[60:61], v[122:123], v[156:157], v[60:61] op_sel:[0,1,0]
	v_pk_fma_f32 v[62:63], v[124:125], v[156:157], v[62:63] op_sel:[0,1,0]
	ds_read_b128 v[150:153], v109 offset:832
	s_waitcnt vmcnt(11)
	s_waitcnt lgkmcnt(4)
	v_pk_fma_f32 v[0:1], v[126:127], v[160:161], v[0:1] op_sel_hi:[1,0,1]
	v_pk_fma_f32 v[2:3], v[128:129], v[160:161], v[2:3] op_sel_hi:[1,0,1]
	v_pk_fma_f32 v[4:5], v[126:127], v[160:161], v[4:5] op_sel:[0,1,0]
	v_pk_fma_f32 v[6:7], v[128:129], v[160:161], v[6:7] op_sel:[0,1,0]
	v_pk_fma_f32 v[8:9], v[126:127], v[162:163], v[8:9] op_sel_hi:[1,0,1]
	v_pk_fma_f32 v[10:11], v[128:129], v[162:163], v[10:11] op_sel_hi:[1,0,1]
	v_pk_fma_f32 v[12:13], v[126:127], v[162:163], v[12:13] op_sel:[0,1,0]
	v_pk_fma_f32 v[14:15], v[128:129], v[162:163], v[14:15] op_sel:[0,1,0]
	ds_read_b128 v[154:157], v109 offset:848
	s_waitcnt lgkmcnt(4)
	v_pk_fma_f32 v[16:17], v[126:127], v[164:165], v[16:17] op_sel_hi:[1,0,1]
	v_pk_fma_f32 v[18:19], v[128:129], v[164:165], v[18:19] op_sel_hi:[1,0,1]
	v_pk_fma_f32 v[20:21], v[126:127], v[164:165], v[20:21] op_sel:[0,1,0]
	v_pk_fma_f32 v[22:23], v[128:129], v[164:165], v[22:23] op_sel:[0,1,0]
	v_pk_fma_f32 v[24:25], v[126:127], v[166:167], v[24:25] op_sel_hi:[1,0,1]
	v_pk_fma_f32 v[26:27], v[128:129], v[166:167], v[26:27] op_sel_hi:[1,0,1]
	v_pk_fma_f32 v[28:29], v[126:127], v[166:167], v[28:29] op_sel:[0,1,0]
	v_pk_fma_f32 v[30:31], v[128:129], v[166:167], v[30:31] op_sel:[0,1,0]
	ds_read_b128 v[160:163], v109 offset:864
	s_waitcnt lgkmcnt(4)
	v_pk_fma_f32 v[32:33], v[126:127], v[142:143], v[32:33] op_sel_hi:[1,0,1]
	v_pk_fma_f32 v[34:35], v[128:129], v[142:143], v[34:35] op_sel_hi:[1,0,1]
	v_pk_fma_f32 v[36:37], v[126:127], v[142:143], v[36:37] op_sel:[0,1,0]
	v_pk_fma_f32 v[38:39], v[128:129], v[142:143], v[38:39] op_sel:[0,1,0]
	v_pk_fma_f32 v[40:41], v[126:127], v[144:145], v[40:41] op_sel_hi:[1,0,1]
	v_pk_fma_f32 v[42:43], v[128:129], v[144:145], v[42:43] op_sel_hi:[1,0,1]
	v_pk_fma_f32 v[44:45], v[126:127], v[144:145], v[44:45] op_sel:[0,1,0]
	v_pk_fma_f32 v[46:47], v[128:129], v[144:145], v[46:47] op_sel:[0,1,0]
	ds_read_b128 v[164:167], v109 offset:880
	s_waitcnt lgkmcnt(4)
; DI void ada_item(const KP& p, int item, float* lds) {
;     ...
;     for (int u = 0; u < 16; ++u) { const f32x4 w = wv[u]; const f32x4* sp = (const f32x4*)(lds + (d0 + dd0 + u) * 16);
; #pragma unroll
;       for (int q = 0; q < 4; ++q) { const f32x4 s = sp[q];
;         acc[4 * q + 0] += w * s[0]; acc[4 * q + 1] += w * s[1]; acc[4 * q + 2] += w * s[2]; acc[4 * q + 3] += w * s[3]; } } }
	v_pk_fma_f32 v[48:49], v[126:127], v[146:147], v[48:49] op_sel_hi:[1,0,1]
	v_pk_fma_f32 v[50:51], v[128:129], v[146:147], v[50:51] op_sel_hi:[1,0,1]
	v_pk_fma_f32 v[52:53], v[126:127], v[146:147], v[52:53] op_sel:[0,1,0]
	v_pk_fma_f32 v[54:55], v[128:129], v[146:147], v[54:55] op_sel:[0,1,0]
	v_pk_fma_f32 v[56:57], v[126:127], v[148:149], v[56:57] op_sel_hi:[1,0,1]
	v_pk_fma_f32 v[58:59], v[128:129], v[148:149], v[58:59] op_sel_hi:[1,0,1]
	v_pk_fma_f32 v[60:61], v[126:127], v[148:149], v[60:61] op_sel:[0,1,0]
	v_pk_fma_f32 v[62:63], v[128:129], v[148:149], v[62:63] op_sel:[0,1,0]
	ds_read_b128 v[142:145], v109 offset:896
	s_waitcnt vmcnt(10)
	s_waitcnt lgkmcnt(4)
	v_pk_fma_f32 v[0:1], v[130:131], v[150:151], v[0:1] op_sel_hi:[1,0,1]
	v_pk_fma_f32 v[2:3], v[132:133], v[150:151], v[2:3] op_sel_hi:[1,0,1]
	v_pk_fma_f32 v[4:5], v[130:131], v[150:151], v[4:5] op_sel:[0,1,0]
	v_pk_fma_f32 v[6:7], v[132:133], v[150:151], v[6:7] op_sel:[0,1,0]
	v_pk_fma_f32 v[8:9], v[130:131], v[152:153], v[8:9] op_sel_hi:[1,0,1]
	v_pk_fma_f32 v[10:11], v[132:133], v[152:153], v[10:11] op_sel_hi:[1,0,1]
	v_pk_fma_f32 v[12:13], v[130:131], v[152:153], v[12:13] op_sel:[0,1,0]
	v_pk_fma_f32 v[14:15], v[132:133], v[152:153], v[14:15] op_sel:[0,1,0]
	ds_read_b128 v[146:149], v109 offset:912
	s_waitcnt lgkmcnt(4)
	v_pk_fma_f32 v[16:17], v[130:131], v[154:155], v[16:17] op_sel_hi:[1,0,1]
	v_pk_fma_f32 v[18:19], v[132:133], v[154:155], v[18:19] op_sel_hi:[1,0,1]
	v_pk_fma_f32 v[20:21], v[130:131], v[154:155], v[20:21] op_sel:[0,1,0]
	v_pk_fma_f32 v[22:23], v[132:133], v[154:155], v[22:23] op_sel:[0,1,0]
	v_pk_fma_f32 v[24:25], v[130:131], v[156:157], v[24:25] op_sel_hi:[1,0,1]
	v_pk_fma_f32 v[26:27], v[132:133], v[156:157], v[26:27] op_sel_hi:[1,0,1]
	v_pk_fma_f32 v[28:29], v[130:131], v[156:157], v[28:29] op_sel:[0,1,0]
	v_pk_fma_f32 v[30:31], v[132:133], v[156:157], v[30:31] op_sel:[0,1,0]
	ds_read_b128 v[150:153], v109 offset:928
	s_waitcnt lgkmcnt(4)
	v_pk_fma_f32 v[32:33], v[130:131], v[160:161], v[32:33] op_sel_hi:[1,0,1]
	v_pk_fma_f32 v[34:35], v[132:133], v[160:161], v[34:35] op_sel_hi:[1,0,1]
	v_pk_fma_f32 v[36:37], v[130:131], v[160:161], v[36:37] op_sel:[0,1,0]
	v_pk_fma_f32 v[38:39], v[132:133], v[160:161], v[38:39] op_sel:[0,1,0]
	v_pk_fma_f32 v[40:41], v[130:131], v[162:163], v[40:41] op_sel_hi:[1,0,1]
	v_pk_fma_f32 v[42:43], v[132:133], v[162:163], v[42:43] op_sel_hi:[1,0,1]
	v_pk_fma_f32 v[44:45], v[130:131], v[162:163], v[44:45] op_sel:[0,1,0]
	v_pk_fma_f32 v[46:47], v[132:133], v[162:163], v[46:47] op_sel:[0,1,0]
	ds_read_b128 v[154:157], v109 offset:944
	s_waitcnt lgkmcnt(4)
	v_pk_fma_f32 v[48:49], v[130:131], v[164:165], v[48:49] op_sel_hi:[1,0,1]
	v_pk_fma_f32 v[50:51], v[132:133], v[164:165], v[50:51] op_sel_hi:[1,0,1]
	v_pk_fma_f32 v[52:53], v[130:131], v[164:165], v[52:53] op_sel:[0,1,0]
	v_pk_fma_f32 v[54:55], v[132:133], v[164:165], v[54:55] op_sel:[0,1,0]
	v_pk_fma_f32 v[56:57], v[130:131], v[166:167], v[56:57] op_sel_hi:[1,0,1]
	v_pk_fma_f32 v[58:59], v[132:133], v[166:167], v[58:59] op_sel_hi:[1,0,1]
	v_pk_fma_f32 v[60:61], v[130:131], v[166:167], v[60:61] op_sel:[0,1,0]
	v_pk_fma_f32 v[62:63], v[132:133], v[166:167], v[62:63] op_sel:[0,1,0]
	ds_read_b128 v[160:163], v109 offset:960
	s_waitcnt vmcnt(9)
	s_waitcnt lgkmcnt(4)
	v_pk_fma_f32 v[0:1], v[134:135], v[142:143], v[0:1] op_sel_hi:[1,0,1]
	v_pk_fma_f32 v[2:3], v[136:137], v[142:143], v[2:3] op_sel_hi:[1,0,1]
	v_pk_fma_f32 v[4:5], v[134:135], v[142:143], v[4:5] op_sel:[0,1,0]
	v_pk_fma_f32 v[6:7], v[136:137], v[142:143], v[6:7] op_sel:[0,1,0]
	v_pk_fma_f32 v[8:9], v[134:135], v[144:145], v[8:9] op_sel_hi:[1,0,1]
	v_pk_fma_f32 v[10:11], v[136:137], v[144:145], v[10:11] op_sel_hi:[1,0,1]
	v_pk_fma_f32 v[12:13], v[134:135], v[144:145], v[12:13] op_sel:[0,1,0]
	v_pk_fma_f32 v[14:15], v[136:137], v[144:145], v[14:15] op_sel:[0,1,0]
	ds_read_b128 v[164:167], v109 offset:976
	s_waitcnt lgkmcnt(4)
	v_pk_fma_f32 v[16:17], v[134:135], v[146:147], v[16:17] op_sel_hi:[1,0,1]
	v_pk_fma_f32 v[18:19], v[136:137], v[146:147], v[18:19] op_sel_hi:[1,0,1]
	v_pk_fma_f32 v[20:21], v[134:135], v[146:147], v[20:21] op_sel:[0,1,0]
	v_pk_fma_f32 v[22:23], v[136:137], v[146:147], v[22:23] op_sel:[0,1,0]
	v_pk_fma_f32 v[24:25], v[134:135], v[148:149], v[24:25] op_sel_hi:[1,0,1]
	v_pk_fma_f32 v[26:27], v[136:137], v[148:149], v[26:27] op_sel_hi:[1,0,1]
	v_pk_fma_f32 v[28:29], v[134:135], v[148:149], v[28:29] op_sel:[0,1,0]
	v_pk_fma_f32 v[30:31], v[136:137], v[148:149], v[30:31] op_sel:[0,1,0]
	ds_read_b128 v[142:145], v109 offset:992
	s_waitcnt lgkmcnt(4)
	v_pk_fma_f32 v[32:33], v[134:135], v[150:151], v[32:33] op_sel_hi:[1,0,1]
	v_pk_fma_f32 v[34:35], v[136:137], v[150:151], v[34:35] op_sel_hi:[1,0,1]
	v_pk_fma_f32 v[36:37], v[134:135], v[150:151], v[36:37] op_sel:[0,1,0]
	v_pk_fma_f32 v[38:39], v[136:137], v[150:151], v[38:39] op_sel:[0,1,0]
	v_pk_fma_f32 v[40:41], v[134:135], v[152:153], v[40:41] op_sel_hi:[1,0,1]
	v_pk_fma_f32 v[42:43], v[136:137], v[152:153], v[42:43] op_sel_hi:[1,0,1]
	v_pk_fma_f32 v[44:45], v[134:135], v[152:153], v[44:45] op_sel:[0,1,0]
	v_pk_fma_f32 v[46:47], v[136:137], v[152:153], v[46:47] op_sel:[0,1,0]
	ds_read_b128 v[146:149], v109 offset:1008
	s_waitcnt lgkmcnt(4)
	v_pk_fma_f32 v[48:49], v[134:135], v[154:155], v[48:49] op_sel_hi:[1,0,1]
	v_pk_fma_f32 v[50:51], v[136:137], v[154:155], v[50:51] op_sel_hi:[1,0,1]
	v_pk_fma_f32 v[52:53], v[134:135], v[154:155], v[52:53] op_sel:[0,1,0]
	v_pk_fma_f32 v[54:55], v[136:137], v[154:155], v[54:55] op_sel:[0,1,0]
	v_pk_fma_f32 v[56:57], v[134:135], v[156:157], v[56:57] op_sel_hi:[1,0,1]
	v_pk_fma_f32 v[58:59], v[136:137], v[156:157], v[58:59] op_sel_hi:[1,0,1]
	v_pk_fma_f32 v[60:61], v[134:135], v[156:157], v[60:61] op_sel:[0,1,0]
	v_pk_fma_f32 v[62:63], v[136:137], v[156:157], v[62:63] op_sel:[0,1,0]
	s_waitcnt vmcnt(8)
; DI void ada_item(const KP& p, int item, float* lds) {
;     ...
;     for (int u = 0; u < 16; ++u) { const f32x4 w = wv[u]; const f32x4* sp = (const f32x4*)(lds + (d0 + dd0 + u) * 16);
; #pragma unroll
;       for (int q = 0; q < 4; ++q) { const f32x4 s = sp[q];
;         acc[4 * q + 0] += w * s[0]; acc[4 * q + 1] += w * s[1]; acc[4 * q + 2] += w * s[2]; acc[4 * q + 3] += w * s[3]; } } }
	s_waitcnt lgkmcnt(3)
	v_pk_fma_f32 v[0:1], v[138:139], v[160:161], v[0:1] op_sel_hi:[1,0,1]
	v_pk_fma_f32 v[2:3], v[140:141], v[160:161], v[2:3] op_sel_hi:[1,0,1]
	v_pk_fma_f32 v[4:5], v[138:139], v[160:161], v[4:5] op_sel:[0,1,0]
	v_pk_fma_f32 v[6:7], v[140:141], v[160:161], v[6:7] op_sel:[0,1,0]
	v_pk_fma_f32 v[8:9], v[138:139], v[162:163], v[8:9] op_sel_hi:[1,0,1]
	v_pk_fma_f32 v[10:11], v[140:141], v[162:163], v[10:11] op_sel_hi:[1,0,1]
	v_pk_fma_f32 v[12:13], v[138:139], v[162:163], v[12:13] op_sel:[0,1,0]
	v_pk_fma_f32 v[14:15], v[140:141], v[162:163], v[14:15] op_sel:[0,1,0]
	s_waitcnt lgkmcnt(2)
	v_pk_fma_f32 v[16:17], v[138:139], v[164:165], v[16:17] op_sel_hi:[1,0,1]
	v_pk_fma_f32 v[18:19], v[140:141], v[164:165], v[18:19] op_sel_hi:[1,0,1]
	v_pk_fma_f32 v[20:21], v[138:139], v[164:165], v[20:21] op_sel:[0,1,0]
	v_pk_fma_f32 v[22:23], v[140:141], v[164:165], v[22:23] op_sel:[0,1,0]
	v_pk_fma_f32 v[24:25], v[138:139], v[166:167], v[24:25] op_sel_hi:[1,0,1]
	v_pk_fma_f32 v[26:27], v[140:141], v[166:167], v[26:27] op_sel_hi:[1,0,1]
	v_pk_fma_f32 v[28:29], v[138:139], v[166:167], v[28:29] op_sel:[0,1,0]
	v_pk_fma_f32 v[30:31], v[140:141], v[166:167], v[30:31] op_sel:[0,1,0]
	s_waitcnt lgkmcnt(1)
	v_pk_fma_f32 v[32:33], v[138:139], v[142:143], v[32:33] op_sel_hi:[1,0,1]
	v_pk_fma_f32 v[34:35], v[140:141], v[142:143], v[34:35] op_sel_hi:[1,0,1]
	v_pk_fma_f32 v[36:37], v[138:139], v[142:143], v[36:37] op_sel:[0,1,0]
	v_pk_fma_f32 v[38:39], v[140:141], v[142:143], v[38:39] op_sel:[0,1,0]
	v_pk_fma_f32 v[40:41], v[138:139], v[144:145], v[40:41] op_sel_hi:[1,0,1]
	v_pk_fma_f32 v[42:43], v[140:141], v[144:145], v[42:43] op_sel_hi:[1,0,1]
	v_pk_fma_f32 v[44:45], v[138:139], v[144:145], v[44:45] op_sel:[0,1,0]
	v_pk_fma_f32 v[46:47], v[140:141], v[144:145], v[46:47] op_sel:[0,1,0]
	s_waitcnt lgkmcnt(0)
	v_pk_fma_f32 v[48:49], v[138:139], v[146:147], v[48:49] op_sel_hi:[1,0,1]
	v_pk_fma_f32 v[50:51], v[140:141], v[146:147], v[50:51] op_sel_hi:[1,0,1]
	v_pk_fma_f32 v[52:53], v[138:139], v[146:147], v[52:53] op_sel:[0,1,0]
	v_pk_fma_f32 v[54:55], v[140:141], v[146:147], v[54:55] op_sel:[0,1,0]
	v_pk_fma_f32 v[56:57], v[138:139], v[148:149], v[56:57] op_sel_hi:[1,0,1]
	v_pk_fma_f32 v[58:59], v[140:141], v[148:149], v[58:59] op_sel_hi:[1,0,1]
	v_pk_fma_f32 v[60:61], v[138:139], v[148:149], v[60:61] op_sel:[0,1,0]
	v_pk_fma_f32 v[62:63], v[140:141], v[148:149], v[62:63] op_sel:[0,1,0]
	v_add_u32_e32 v109, 0x400, v109
	s_add_i32 s4, s4, 1
	s_cmp_lt_u32 s4, 3
	s_cbranch_scc1 .Lada_loop
	global_load_dwordx4 v[110:113], v[158:159], off
	v_lshl_add_u64 v[64:65], v[158:159], 0, s[20:21]
	global_load_dwordx4 v[114:117], v[64:65], off
	v_lshl_add_u64 v[66:67], v[64:65], 0, s[20:21]
	global_load_dwordx4 v[118:121], v[66:67], off
	v_lshl_add_u64 v[64:65], v[66:67], 0, s[20:21]
	global_load_dwordx4 v[122:125], v[64:65], off
	v_lshl_add_u64 v[66:67], v[64:65], 0, s[20:21]
	global_load_dwordx4 v[126:129], v[66:67], off
	v_lshl_add_u64 v[64:65], v[66:67], 0, s[20:21]
	global_load_dwordx4 v[130:133], v[64:65], off
	v_lshl_add_u64 v[66:67], v[64:65], 0, s[20:21]
	global_load_dwordx4 v[134:137], v[66:67], off
	v_lshl_add_u64 v[64:65], v[66:67], 0, s[20:21]
	global_load_dwordx4 v[138:141], v[64:65], off
	v_lshl_add_u64 v[158:159], v[64:65], 0, s[20:21]
	ds_read_b128 v[142:145], v109 offset:0
	ds_read_b128 v[146:149], v109 offset:16
	ds_read_b128 v[150:153], v109 offset:32
	ds_read_b128 v[154:157], v109 offset:48
	ds_read_b128 v[160:163], v109 offset:64
	s_waitcnt vmcnt(15)
	s_waitcnt lgkmcnt(4)
	v_pk_fma_f32 v[0:1], v[70:71], v[142:143], v[0:1] op_sel_hi:[1,0,1]
	v_pk_fma_f32 v[2:3], v[72:73], v[142:143], v[2:3] op_sel_hi:[1,0,1]
	v_pk_fma_f32 v[4:5], v[70:71], v[142:143], v[4:5] op_sel:[0,1,0]
	v_pk_fma_f32 v[6:7], v[72:73], v[142:143], v[6:7] op_sel:[0,1,0]
	v_pk_fma_f32 v[8:9], v[70:71], v[144:145], v[8:9] op_sel_hi:[1,0,1]
	v_pk_fma_f32 v[10:11], v[72:73], v[144:145], v[10:11] op_sel_hi:[1,0,1]
	v_pk_fma_f32 v[12:13], v[70:71], v[144:145], v[12:13] op_sel:[0,1,0]
	v_pk_fma_f32 v[14:15], v[72:73], v[144:145], v[14:15] op_sel:[0,1,0]
	ds_read_b128 v[164:167], v109 offset:80
	s_waitcnt lgkmcnt(4)
	v_pk_fma_f32 v[16:17], v[70:71], v[146:147], v[16:17] op_sel_hi:[1,0,1]
	v_pk_fma_f32 v[18:19], v[72:73], v[146:147], v[18:19] op_sel_hi:[1,0,1]
	v_pk_fma_f32 v[20:21], v[70:71], v[146:147], v[20:21] op_sel:[0,1,0]
	v_pk_fma_f32 v[22:23], v[72:73], v[146:147], v[22:23] op_sel:[0,1,0]
	v_pk_fma_f32 v[24:25], v[70:71], v[148:149], v[24:25] op_sel_hi:[1,0,1]
	v_pk_fma_f32 v[26:27], v[72:73], v[148:149], v[26:27] op_sel_hi:[1,0,1]
	v_pk_fma_f32 v[28:29], v[70:71], v[148:149], v[28:29] op_sel:[0,1,0]
	v_pk_fma_f32 v[30:31], v[72:73], v[148:149], v[30:31] op_sel:[0,1,0]
	ds_read_b128 v[142:145], v109 offset:96
	s_waitcnt lgkmcnt(4)
	v_pk_fma_f32 v[32:33], v[70:71], v[150:151], v[32:33] op_sel_hi:[1,0,1]
	v_pk_fma_f32 v[34:35], v[72:73], v[150:151], v[34:35] op_sel_hi:[1,0,1]
	v_pk_fma_f32 v[36:37], v[70:71], v[150:151], v[36:37] op_sel:[0,1,0]
	v_pk_fma_f32 v[38:39], v[72:73], v[150:151], v[38:39] op_sel:[0,1,0]
	v_pk_fma_f32 v[40:41], v[70:71], v[152:153], v[40:41] op_sel_hi:[1,0,1]
	v_pk_fma_f32 v[42:43], v[72:73], v[152:153], v[42:43] op_sel_hi:[1,0,1]
	v_pk_fma_f32 v[44:45], v[70:71], v[152:153], v[44:45] op_sel:[0,1,0]
	v_pk_fma_f32 v[46:47], v[72:73], v[152:153], v[46:47] op_sel:[0,1,0]
	ds_read_b128 v[146:149], v109 offset:112
	s_waitcnt lgkmcnt(4)
; DI void ada_item(const KP& p, int item, float* lds) {
;     ...
;     for (int u = 0; u < 16; ++u) { const f32x4 w = wv[u]; const f32x4* sp = (const f32x4*)(lds + (d0 + dd0 + u) * 16);
; #pragma unroll
;       for (int q = 0; q < 4; ++q) { const f32x4 s = sp[q];
;         acc[4 * q + 0] += w * s[0]; acc[4 * q + 1] += w * s[1]; acc[4 * q + 2] += w * s[2]; acc[4 * q + 3] += w * s[3]; } } }
	v_pk_fma_f32 v[48:49], v[70:71], v[154:155], v[48:49] op_sel_hi:[1,0,1]
	v_pk_fma_f32 v[50:51], v[72:73], v[154:155], v[50:51] op_sel_hi:[1,0,1]
	v_pk_fma_f32 v[52:53], v[70:71], v[154:155], v[52:53] op_sel:[0,1,0]
	v_pk_fma_f32 v[54:55], v[72:73], v[154:155], v[54:55] op_sel:[0,1,0]
	v_pk_fma_f32 v[56:57], v[70:71], v[156:157], v[56:57] op_sel_hi:[1,0,1]
	v_pk_fma_f32 v[58:59], v[72:73], v[156:157], v[58:59] op_sel_hi:[1,0,1]
	v_pk_fma_f32 v[60:61], v[70:71], v[156:157], v[60:61] op_sel:[0,1,0]
	v_pk_fma_f32 v[62:63], v[72:73], v[156:157], v[62:63] op_sel:[0,1,0]
	ds_read_b128 v[150:153], v109 offset:128
	s_waitcnt vmcnt(14)
	s_waitcnt lgkmcnt(4)
	v_pk_fma_f32 v[0:1], v[74:75], v[160:161], v[0:1] op_sel_hi:[1,0,1]
	v_pk_fma_f32 v[2:3], v[76:77], v[160:161], v[2:3] op_sel_hi:[1,0,1]
	v_pk_fma_f32 v[4:5], v[74:75], v[160:161], v[4:5] op_sel:[0,1,0]
	v_pk_fma_f32 v[6:7], v[76:77], v[160:161], v[6:7] op_sel:[0,1,0]
	v_pk_fma_f32 v[8:9], v[74:75], v[162:163], v[8:9] op_sel_hi:[1,0,1]
	v_pk_fma_f32 v[10:11], v[76:77], v[162:163], v[10:11] op_sel_hi:[1,0,1]
	v_pk_fma_f32 v[12:13], v[74:75], v[162:163], v[12:13] op_sel:[0,1,0]
	v_pk_fma_f32 v[14:15], v[76:77], v[162:163], v[14:15] op_sel:[0,1,0]
	ds_read_b128 v[154:157], v109 offset:144
	s_waitcnt lgkmcnt(4)
	v_pk_fma_f32 v[16:17], v[74:75], v[164:165], v[16:17] op_sel_hi:[1,0,1]
	v_pk_fma_f32 v[18:19], v[76:77], v[164:165], v[18:19] op_sel_hi:[1,0,1]
	v_pk_fma_f32 v[20:21], v[74:75], v[164:165], v[20:21] op_sel:[0,1,0]
	v_pk_fma_f32 v[22:23], v[76:77], v[164:165], v[22:23] op_sel:[0,1,0]
	v_pk_fma_f32 v[24:25], v[74:75], v[166:167], v[24:25] op_sel_hi:[1,0,1]
	v_pk_fma_f32 v[26:27], v[76:77], v[166:167], v[26:27] op_sel_hi:[1,0,1]
	v_pk_fma_f32 v[28:29], v[74:75], v[166:167], v[28:29] op_sel:[0,1,0]
	v_pk_fma_f32 v[30:31], v[76:77], v[166:167], v[30:31] op_sel:[0,1,0]
	ds_read_b128 v[160:163], v109 offset:160
	s_waitcnt lgkmcnt(4)
	v_pk_fma_f32 v[32:33], v[74:75], v[142:143], v[32:33] op_sel_hi:[1,0,1]
	v_pk_fma_f32 v[34:35], v[76:77], v[142:143], v[34:35] op_sel_hi:[1,0,1]
	v_pk_fma_f32 v[36:37], v[74:75], v[142:143], v[36:37] op_sel:[0,1,0]
	v_pk_fma_f32 v[38:39], v[76:77], v[142:143], v[38:39] op_sel:[0,1,0]
	v_pk_fma_f32 v[40:41], v[74:75], v[144:145], v[40:41] op_sel_hi:[1,0,1]
	v_pk_fma_f32 v[42:43], v[76:77], v[144:145], v[42:43] op_sel_hi:[1,0,1]
	v_pk_fma_f32 v[44:45], v[74:75], v[144:145], v[44:45] op_sel:[0,1,0]
	v_pk_fma_f32 v[46:47], v[76:77], v[144:145], v[46:47] op_sel:[0,1,0]
	ds_read_b128 v[164:167], v109 offset:176
	s_waitcnt lgkmcnt(4)
	v_pk_fma_f32 v[48:49], v[74:75], v[146:147], v[48:49] op_sel_hi:[1,0,1]
	v_pk_fma_f32 v[50:51], v[76:77], v[146:147], v[50:51] op_sel_hi:[1,0,1]
	v_pk_fma_f32 v[52:53], v[74:75], v[146:147], v[52:53] op_sel:[0,1,0]
	v_pk_fma_f32 v[54:55], v[76:77], v[146:147], v[54:55] op_sel:[0,1,0]
	v_pk_fma_f32 v[56:57], v[74:75], v[148:149], v[56:57] op_sel_hi:[1,0,1]
	v_pk_fma_f32 v[58:59], v[76:77], v[148:149], v[58:59] op_sel_hi:[1,0,1]
	v_pk_fma_f32 v[60:61], v[74:75], v[148:149], v[60:61] op_sel:[0,1,0]
	v_pk_fma_f32 v[62:63], v[76:77], v[148:149], v[62:63] op_sel:[0,1,0]
	ds_read_b128 v[142:145], v109 offset:192
	s_waitcnt vmcnt(13)
	s_waitcnt lgkmcnt(4)
	v_pk_fma_f32 v[0:1], v[78:79], v[150:151], v[0:1] op_sel_hi:[1,0,1]
	v_pk_fma_f32 v[2:3], v[80:81], v[150:151], v[2:3] op_sel_hi:[1,0,1]
	v_pk_fma_f32 v[4:5], v[78:79], v[150:151], v[4:5] op_sel:[0,1,0]
	v_pk_fma_f32 v[6:7], v[80:81], v[150:151], v[6:7] op_sel:[0,1,0]
	v_pk_fma_f32 v[8:9], v[78:79], v[152:153], v[8:9] op_sel_hi:[1,0,1]
	v_pk_fma_f32 v[10:11], v[80:81], v[152:153], v[10:11] op_sel_hi:[1,0,1]
	v_pk_fma_f32 v[12:13], v[78:79], v[152:153], v[12:13] op_sel:[0,1,0]
	v_pk_fma_f32 v[14:15], v[80:81], v[152:153], v[14:15] op_sel:[0,1,0]
	ds_read_b128 v[146:149], v109 offset:208
	s_waitcnt lgkmcnt(4)
	v_pk_fma_f32 v[16:17], v[78:79], v[154:155], v[16:17] op_sel_hi:[1,0,1]
	v_pk_fma_f32 v[18:19], v[80:81], v[154:155], v[18:19] op_sel_hi:[1,0,1]
	v_pk_fma_f32 v[20:21], v[78:79], v[154:155], v[20:21] op_sel:[0,1,0]
	v_pk_fma_f32 v[22:23], v[80:81], v[154:155], v[22:23] op_sel:[0,1,0]
	v_pk_fma_f32 v[24:25], v[78:79], v[156:157], v[24:25] op_sel_hi:[1,0,1]
	v_pk_fma_f32 v[26:27], v[80:81], v[156:157], v[26:27] op_sel_hi:[1,0,1]
	v_pk_fma_f32 v[28:29], v[78:79], v[156:157], v[28:29] op_sel:[0,1,0]
	v_pk_fma_f32 v[30:31], v[80:81], v[156:157], v[30:31] op_sel:[0,1,0]
	ds_read_b128 v[150:153], v109 offset:224
	s_waitcnt lgkmcnt(4)
	v_pk_fma_f32 v[32:33], v[78:79], v[160:161], v[32:33] op_sel_hi:[1,0,1]
	v_pk_fma_f32 v[34:35], v[80:81], v[160:161], v[34:35] op_sel_hi:[1,0,1]
	v_pk_fma_f32 v[36:37], v[78:79], v[160:161], v[36:37] op_sel:[0,1,0]
	v_pk_fma_f32 v[38:39], v[80:81], v[160:161], v[38:39] op_sel:[0,1,0]
	v_pk_fma_f32 v[40:41], v[78:79], v[162:163], v[40:41] op_sel_hi:[1,0,1]
	v_pk_fma_f32 v[42:43], v[80:81], v[162:163], v[42:43] op_sel_hi:[1,0,1]
	v_pk_fma_f32 v[44:45], v[78:79], v[162:163], v[44:45] op_sel:[0,1,0]
	v_pk_fma_f32 v[46:47], v[80:81], v[162:163], v[46:47] op_sel:[0,1,0]
	ds_read_b128 v[154:157], v109 offset:240
	s_waitcnt lgkmcnt(4)
	v_pk_fma_f32 v[48:49], v[78:79], v[164:165], v[48:49] op_sel_hi:[1,0,1]
	v_pk_fma_f32 v[50:51], v[80:81], v[164:165], v[50:51] op_sel_hi:[1,0,1]
	v_pk_fma_f32 v[52:53], v[78:79], v[164:165], v[52:53] op_sel:[0,1,0]
	v_pk_fma_f32 v[54:55], v[80:81], v[164:165], v[54:55] op_sel:[0,1,0]
	v_pk_fma_f32 v[56:57], v[78:79], v[166:167], v[56:57] op_sel_hi:[1,0,1]
	v_pk_fma_f32 v[58:59], v[80:81], v[166:167], v[58:59] op_sel_hi:[1,0,1]
	v_pk_fma_f32 v[60:61], v[78:79], v[166:167], v[60:61] op_sel:[0,1,0]
	v_pk_fma_f32 v[62:63], v[80:81], v[166:167], v[62:63] op_sel:[0,1,0]
	ds_read_b128 v[160:163], v109 offset:256
	s_waitcnt vmcnt(12)
; DI void ada_item(const KP& p, int item, float* lds) {
;     ...
;     for (int u = 0; u < 16; ++u) { const f32x4 w = wv[u]; const f32x4* sp = (const f32x4*)(lds + (d0 + dd0 + u) * 16);
; #pragma unroll
;       for (int q = 0; q < 4; ++q) { const f32x4 s = sp[q];
;         acc[4 * q + 0] += w * s[0]; acc[4 * q + 1] += w * s[1]; acc[4 * q + 2] += w * s[2]; acc[4 * q + 3] += w * s[3]; } } }
	s_waitcnt lgkmcnt(4)
	v_pk_fma_f32 v[0:1], v[82:83], v[142:143], v[0:1] op_sel_hi:[1,0,1]
	v_pk_fma_f32 v[2:3], v[84:85], v[142:143], v[2:3] op_sel_hi:[1,0,1]
	v_pk_fma_f32 v[4:5], v[82:83], v[142:143], v[4:5] op_sel:[0,1,0]
	v_pk_fma_f32 v[6:7], v[84:85], v[142:143], v[6:7] op_sel:[0,1,0]
	v_pk_fma_f32 v[8:9], v[82:83], v[144:145], v[8:9] op_sel_hi:[1,0,1]
	v_pk_fma_f32 v[10:11], v[84:85], v[144:145], v[10:11] op_sel_hi:[1,0,1]
	v_pk_fma_f32 v[12:13], v[82:83], v[144:145], v[12:13] op_sel:[0,1,0]
	v_pk_fma_f32 v[14:15], v[84:85], v[144:145], v[14:15] op_sel:[0,1,0]
	ds_read_b128 v[164:167], v109 offset:272
	s_waitcnt lgkmcnt(4)
	v_pk_fma_f32 v[16:17], v[82:83], v[146:147], v[16:17] op_sel_hi:[1,0,1]
	v_pk_fma_f32 v[18:19], v[84:85], v[146:147], v[18:19] op_sel_hi:[1,0,1]
	v_pk_fma_f32 v[20:21], v[82:83], v[146:147], v[20:21] op_sel:[0,1,0]
	v_pk_fma_f32 v[22:23], v[84:85], v[146:147], v[22:23] op_sel:[0,1,0]
	v_pk_fma_f32 v[24:25], v[82:83], v[148:149], v[24:25] op_sel_hi:[1,0,1]
	v_pk_fma_f32 v[26:27], v[84:85], v[148:149], v[26:27] op_sel_hi:[1,0,1]
	v_pk_fma_f32 v[28:29], v[82:83], v[148:149], v[28:29] op_sel:[0,1,0]
	v_pk_fma_f32 v[30:31], v[84:85], v[148:149], v[30:31] op_sel:[0,1,0]
	ds_read_b128 v[142:145], v109 offset:288
	s_waitcnt lgkmcnt(4)
	v_pk_fma_f32 v[32:33], v[82:83], v[150:151], v[32:33] op_sel_hi:[1,0,1]
	v_pk_fma_f32 v[34:35], v[84:85], v[150:151], v[34:35] op_sel_hi:[1,0,1]
	v_pk_fma_f32 v[36:37], v[82:83], v[150:151], v[36:37] op_sel:[0,1,0]
	v_pk_fma_f32 v[38:39], v[84:85], v[150:151], v[38:39] op_sel:[0,1,0]
	v_pk_fma_f32 v[40:41], v[82:83], v[152:153], v[40:41] op_sel_hi:[1,0,1]
	v_pk_fma_f32 v[42:43], v[84:85], v[152:153], v[42:43] op_sel_hi:[1,0,1]
	v_pk_fma_f32 v[44:45], v[82:83], v[152:153], v[44:45] op_sel:[0,1,0]
	v_pk_fma_f32 v[46:47], v[84:85], v[152:153], v[46:47] op_sel:[0,1,0]
	ds_read_b128 v[146:149], v109 offset:304
	s_waitcnt lgkmcnt(4)
	v_pk_fma_f32 v[48:49], v[82:83], v[154:155], v[48:49] op_sel_hi:[1,0,1]
	v_pk_fma_f32 v[50:51], v[84:85], v[154:155], v[50:51] op_sel_hi:[1,0,1]
	v_pk_fma_f32 v[52:53], v[82:83], v[154:155], v[52:53] op_sel:[0,1,0]
	v_pk_fma_f32 v[54:55], v[84:85], v[154:155], v[54:55] op_sel:[0,1,0]
	v_pk_fma_f32 v[56:57], v[82:83], v[156:157], v[56:57] op_sel_hi:[1,0,1]
	v_pk_fma_f32 v[58:59], v[84:85], v[156:157], v[58:59] op_sel_hi:[1,0,1]
	v_pk_fma_f32 v[60:61], v[82:83], v[156:157], v[60:61] op_sel:[0,1,0]
	v_pk_fma_f32 v[62:63], v[84:85], v[156:157], v[62:63] op_sel:[0,1,0]
	ds_read_b128 v[150:153], v109 offset:320
	s_waitcnt vmcnt(11)
	s_waitcnt lgkmcnt(4)
	v_pk_fma_f32 v[0:1], v[86:87], v[160:161], v[0:1] op_sel_hi:[1,0,1]
	v_pk_fma_f32 v[2:3], v[88:89], v[160:161], v[2:3] op_sel_hi:[1,0,1]
	v_pk_fma_f32 v[4:5], v[86:87], v[160:161], v[4:5] op_sel:[0,1,0]
	v_pk_fma_f32 v[6:7], v[88:89], v[160:161], v[6:7] op_sel:[0,1,0]
	v_pk_fma_f32 v[8:9], v[86:87], v[162:163], v[8:9] op_sel_hi:[1,0,1]
	v_pk_fma_f32 v[10:11], v[88:89], v[162:163], v[10:11] op_sel_hi:[1,0,1]
	v_pk_fma_f32 v[12:13], v[86:87], v[162:163], v[12:13] op_sel:[0,1,0]
	v_pk_fma_f32 v[14:15], v[88:89], v[162:163], v[14:15] op_sel:[0,1,0]
	ds_read_b128 v[154:157], v109 offset:336
	s_waitcnt lgkmcnt(4)
	v_pk_fma_f32 v[16:17], v[86:87], v[164:165], v[16:17] op_sel_hi:[1,0,1]
	v_pk_fma_f32 v[18:19], v[88:89], v[164:165], v[18:19] op_sel_hi:[1,0,1]
	v_pk_fma_f32 v[20:21], v[86:87], v[164:165], v[20:21] op_sel:[0,1,0]
	v_pk_fma_f32 v[22:23], v[88:89], v[164:165], v[22:23] op_sel:[0,1,0]
	v_pk_fma_f32 v[24:25], v[86:87], v[166:167], v[24:25] op_sel_hi:[1,0,1]
	v_pk_fma_f32 v[26:27], v[88:89], v[166:167], v[26:27] op_sel_hi:[1,0,1]
	v_pk_fma_f32 v[28:29], v[86:87], v[166:167], v[28:29] op_sel:[0,1,0]
	v_pk_fma_f32 v[30:31], v[88:89], v[166:167], v[30:31] op_sel:[0,1,0]
	ds_read_b128 v[160:163], v109 offset:352
	s_waitcnt lgkmcnt(4)
	v_pk_fma_f32 v[32:33], v[86:87], v[142:143], v[32:33] op_sel_hi:[1,0,1]
	v_pk_fma_f32 v[34:35], v[88:89], v[142:143], v[34:35] op_sel_hi:[1,0,1]
	v_pk_fma_f32 v[36:37], v[86:87], v[142:143], v[36:37] op_sel:[0,1,0]
	v_pk_fma_f32 v[38:39], v[88:89], v[142:143], v[38:39] op_sel:[0,1,0]
	v_pk_fma_f32 v[40:41], v[86:87], v[144:145], v[40:41] op_sel_hi:[1,0,1]
	v_pk_fma_f32 v[42:43], v[88:89], v[144:145], v[42:43] op_sel_hi:[1,0,1]
	v_pk_fma_f32 v[44:45], v[86:87], v[144:145], v[44:45] op_sel:[0,1,0]
	v_pk_fma_f32 v[46:47], v[88:89], v[144:145], v[46:47] op_sel:[0,1,0]
	ds_read_b128 v[164:167], v109 offset:368
	s_waitcnt lgkmcnt(4)
	v_pk_fma_f32 v[48:49], v[86:87], v[146:147], v[48:49] op_sel_hi:[1,0,1]
	v_pk_fma_f32 v[50:51], v[88:89], v[146:147], v[50:51] op_sel_hi:[1,0,1]
	v_pk_fma_f32 v[52:53], v[86:87], v[146:147], v[52:53] op_sel:[0,1,0]
	v_pk_fma_f32 v[54:55], v[88:89], v[146:147], v[54:55] op_sel:[0,1,0]
	v_pk_fma_f32 v[56:57], v[86:87], v[148:149], v[56:57] op_sel_hi:[1,0,1]
	v_pk_fma_f32 v[58:59], v[88:89], v[148:149], v[58:59] op_sel_hi:[1,0,1]
	v_pk_fma_f32 v[60:61], v[86:87], v[148:149], v[60:61] op_sel:[0,1,0]
	v_pk_fma_f32 v[62:63], v[88:89], v[148:149], v[62:63] op_sel:[0,1,0]
	ds_read_b128 v[142:145], v109 offset:384
	s_waitcnt vmcnt(10)
	s_waitcnt lgkmcnt(4)
	v_pk_fma_f32 v[0:1], v[90:91], v[150:151], v[0:1] op_sel_hi:[1,0,1]
	v_pk_fma_f32 v[2:3], v[92:93], v[150:151], v[2:3] op_sel_hi:[1,0,1]
	v_pk_fma_f32 v[4:5], v[90:91], v[150:151], v[4:5] op_sel:[0,1,0]
	v_pk_fma_f32 v[6:7], v[92:93], v[150:151], v[6:7] op_sel:[0,1,0]
	v_pk_fma_f32 v[8:9], v[90:91], v[152:153], v[8:9] op_sel_hi:[1,0,1]
	v_pk_fma_f32 v[10:11], v[92:93], v[152:153], v[10:11] op_sel_hi:[1,0,1]
	v_pk_fma_f32 v[12:13], v[90:91], v[152:153], v[12:13] op_sel:[0,1,0]
	v_pk_fma_f32 v[14:15], v[92:93], v[152:153], v[14:15] op_sel:[0,1,0]
	ds_read_b128 v[146:149], v109 offset:400
	s_waitcnt lgkmcnt(4)
; DI void ada_item(const KP& p, int item, float* lds) {
;     ...
;     for (int u = 0; u < 16; ++u) { const f32x4 w = wv[u]; const f32x4* sp = (const f32x4*)(lds + (d0 + dd0 + u) * 16);
; #pragma unroll
;       for (int q = 0; q < 4; ++q) { const f32x4 s = sp[q];
;         acc[4 * q + 0] += w * s[0]; acc[4 * q + 1] += w * s[1]; acc[4 * q + 2] += w * s[2]; acc[4 * q + 3] += w * s[3]; } } }
	v_pk_fma_f32 v[16:17], v[90:91], v[154:155], v[16:17] op_sel_hi:[1,0,1]
	v_pk_fma_f32 v[18:19], v[92:93], v[154:155], v[18:19] op_sel_hi:[1,0,1]
	v_pk_fma_f32 v[20:21], v[90:91], v[154:155], v[20:21] op_sel:[0,1,0]
	v_pk_fma_f32 v[22:23], v[92:93], v[154:155], v[22:23] op_sel:[0,1,0]
	v_pk_fma_f32 v[24:25], v[90:91], v[156:157], v[24:25] op_sel_hi:[1,0,1]
	v_pk_fma_f32 v[26:27], v[92:93], v[156:157], v[26:27] op_sel_hi:[1,0,1]
	v_pk_fma_f32 v[28:29], v[90:91], v[156:157], v[28:29] op_sel:[0,1,0]
	v_pk_fma_f32 v[30:31], v[92:93], v[156:157], v[30:31] op_sel:[0,1,0]
	ds_read_b128 v[150:153], v109 offset:416
	s_waitcnt lgkmcnt(4)
	v_pk_fma_f32 v[32:33], v[90:91], v[160:161], v[32:33] op_sel_hi:[1,0,1]
	v_pk_fma_f32 v[34:35], v[92:93], v[160:161], v[34:35] op_sel_hi:[1,0,1]
	v_pk_fma_f32 v[36:37], v[90:91], v[160:161], v[36:37] op_sel:[0,1,0]
	v_pk_fma_f32 v[38:39], v[92:93], v[160:161], v[38:39] op_sel:[0,1,0]
	v_pk_fma_f32 v[40:41], v[90:91], v[162:163], v[40:41] op_sel_hi:[1,0,1]
	v_pk_fma_f32 v[42:43], v[92:93], v[162:163], v[42:43] op_sel_hi:[1,0,1]
	v_pk_fma_f32 v[44:45], v[90:91], v[162:163], v[44:45] op_sel:[0,1,0]
	v_pk_fma_f32 v[46:47], v[92:93], v[162:163], v[46:47] op_sel:[0,1,0]
	ds_read_b128 v[154:157], v109 offset:432
	s_waitcnt lgkmcnt(4)
	v_pk_fma_f32 v[48:49], v[90:91], v[164:165], v[48:49] op_sel_hi:[1,0,1]
	v_pk_fma_f32 v[50:51], v[92:93], v[164:165], v[50:51] op_sel_hi:[1,0,1]
	v_pk_fma_f32 v[52:53], v[90:91], v[164:165], v[52:53] op_sel:[0,1,0]
	v_pk_fma_f32 v[54:55], v[92:93], v[164:165], v[54:55] op_sel:[0,1,0]
	v_pk_fma_f32 v[56:57], v[90:91], v[166:167], v[56:57] op_sel_hi:[1,0,1]
	v_pk_fma_f32 v[58:59], v[92:93], v[166:167], v[58:59] op_sel_hi:[1,0,1]
	v_pk_fma_f32 v[60:61], v[90:91], v[166:167], v[60:61] op_sel:[0,1,0]
	v_pk_fma_f32 v[62:63], v[92:93], v[166:167], v[62:63] op_sel:[0,1,0]
	ds_read_b128 v[160:163], v109 offset:448
	s_waitcnt vmcnt(9)
	s_waitcnt lgkmcnt(4)
	v_pk_fma_f32 v[0:1], v[94:95], v[142:143], v[0:1] op_sel_hi:[1,0,1]
	v_pk_fma_f32 v[2:3], v[96:97], v[142:143], v[2:3] op_sel_hi:[1,0,1]
	v_pk_fma_f32 v[4:5], v[94:95], v[142:143], v[4:5] op_sel:[0,1,0]
	v_pk_fma_f32 v[6:7], v[96:97], v[142:143], v[6:7] op_sel:[0,1,0]
	v_pk_fma_f32 v[8:9], v[94:95], v[144:145], v[8:9] op_sel_hi:[1,0,1]
	v_pk_fma_f32 v[10:11], v[96:97], v[144:145], v[10:11] op_sel_hi:[1,0,1]
	v_pk_fma_f32 v[12:13], v[94:95], v[144:145], v[12:13] op_sel:[0,1,0]
	v_pk_fma_f32 v[14:15], v[96:97], v[144:145], v[14:15] op_sel:[0,1,0]
	ds_read_b128 v[164:167], v109 offset:464
	s_waitcnt lgkmcnt(4)
	v_pk_fma_f32 v[16:17], v[94:95], v[146:147], v[16:17] op_sel_hi:[1,0,1]
	v_pk_fma_f32 v[18:19], v[96:97], v[146:147], v[18:19] op_sel_hi:[1,0,1]
	v_pk_fma_f32 v[20:21], v[94:95], v[146:147], v[20:21] op_sel:[0,1,0]
	v_pk_fma_f32 v[22:23], v[96:97], v[146:147], v[22:23] op_sel:[0,1,0]
	v_pk_fma_f32 v[24:25], v[94:95], v[148:149], v[24:25] op_sel_hi:[1,0,1]
	v_pk_fma_f32 v[26:27], v[96:97], v[148:149], v[26:27] op_sel_hi:[1,0,1]
	v_pk_fma_f32 v[28:29], v[94:95], v[148:149], v[28:29] op_sel:[0,1,0]
	v_pk_fma_f32 v[30:31], v[96:97], v[148:149], v[30:31] op_sel:[0,1,0]
	ds_read_b128 v[142:145], v109 offset:480
	s_waitcnt lgkmcnt(4)
	v_pk_fma_f32 v[32:33], v[94:95], v[150:151], v[32:33] op_sel_hi:[1,0,1]
	v_pk_fma_f32 v[34:35], v[96:97], v[150:151], v[34:35] op_sel_hi:[1,0,1]
	v_pk_fma_f32 v[36:37], v[94:95], v[150:151], v[36:37] op_sel:[0,1,0]
	v_pk_fma_f32 v[38:39], v[96:97], v[150:151], v[38:39] op_sel:[0,1,0]
	v_pk_fma_f32 v[40:41], v[94:95], v[152:153], v[40:41] op_sel_hi:[1,0,1]
	v_pk_fma_f32 v[42:43], v[96:97], v[152:153], v[42:43] op_sel_hi:[1,0,1]
	v_pk_fma_f32 v[44:45], v[94:95], v[152:153], v[44:45] op_sel:[0,1,0]
	v_pk_fma_f32 v[46:47], v[96:97], v[152:153], v[46:47] op_sel:[0,1,0]
	ds_read_b128 v[146:149], v109 offset:496
	s_waitcnt lgkmcnt(4)
	v_pk_fma_f32 v[48:49], v[94:95], v[154:155], v[48:49] op_sel_hi:[1,0,1]
	v_pk_fma_f32 v[50:51], v[96:97], v[154:155], v[50:51] op_sel_hi:[1,0,1]
	v_pk_fma_f32 v[52:53], v[94:95], v[154:155], v[52:53] op_sel:[0,1,0]
	v_pk_fma_f32 v[54:55], v[96:97], v[154:155], v[54:55] op_sel:[0,1,0]
	v_pk_fma_f32 v[56:57], v[94:95], v[156:157], v[56:57] op_sel_hi:[1,0,1]
	v_pk_fma_f32 v[58:59], v[96:97], v[156:157], v[58:59] op_sel_hi:[1,0,1]
	v_pk_fma_f32 v[60:61], v[94:95], v[156:157], v[60:61] op_sel:[0,1,0]
	v_pk_fma_f32 v[62:63], v[96:97], v[156:157], v[62:63] op_sel:[0,1,0]
	s_waitcnt vmcnt(8)
	s_waitcnt lgkmcnt(3)
	v_pk_fma_f32 v[0:1], v[98:99], v[160:161], v[0:1] op_sel_hi:[1,0,1]
	v_pk_fma_f32 v[2:3], v[100:101], v[160:161], v[2:3] op_sel_hi:[1,0,1]
	v_pk_fma_f32 v[4:5], v[98:99], v[160:161], v[4:5] op_sel:[0,1,0]
	v_pk_fma_f32 v[6:7], v[100:101], v[160:161], v[6:7] op_sel:[0,1,0]
	v_pk_fma_f32 v[8:9], v[98:99], v[162:163], v[8:9] op_sel_hi:[1,0,1]
	v_pk_fma_f32 v[10:11], v[100:101], v[162:163], v[10:11] op_sel_hi:[1,0,1]
	v_pk_fma_f32 v[12:13], v[98:99], v[162:163], v[12:13] op_sel:[0,1,0]
	v_pk_fma_f32 v[14:15], v[100:101], v[162:163], v[14:15] op_sel:[0,1,0]
	s_waitcnt lgkmcnt(2)
	v_pk_fma_f32 v[16:17], v[98:99], v[164:165], v[16:17] op_sel_hi:[1,0,1]
	v_pk_fma_f32 v[18:19], v[100:101], v[164:165], v[18:19] op_sel_hi:[1,0,1]
	v_pk_fma_f32 v[20:21], v[98:99], v[164:165], v[20:21] op_sel:[0,1,0]
	v_pk_fma_f32 v[22:23], v[100:101], v[164:165], v[22:23] op_sel:[0,1,0]
	v_pk_fma_f32 v[24:25], v[98:99], v[166:167], v[24:25] op_sel_hi:[1,0,1]
	v_pk_fma_f32 v[26:27], v[100:101], v[166:167], v[26:27] op_sel_hi:[1,0,1]
	v_pk_fma_f32 v[28:29], v[98:99], v[166:167], v[28:29] op_sel:[0,1,0]
	v_pk_fma_f32 v[30:31], v[100:101], v[166:167], v[30:31] op_sel:[0,1,0]
	s_waitcnt lgkmcnt(1)
; DI void ada_item(const KP& p, int item, float* lds) {
;     ...
;     for (int u = 0; u < 16; ++u) { const f32x4 w = wv[u]; const f32x4* sp = (const f32x4*)(lds + (d0 + dd0 + u) * 16);
; #pragma unroll
;       for (int q = 0; q < 4; ++q) { const f32x4 s = sp[q];
;         acc[4 * q + 0] += w * s[0]; acc[4 * q + 1] += w * s[1]; acc[4 * q + 2] += w * s[2]; acc[4 * q + 3] += w * s[3]; } } }
	v_pk_fma_f32 v[32:33], v[98:99], v[142:143], v[32:33] op_sel_hi:[1,0,1]
	v_pk_fma_f32 v[34:35], v[100:101], v[142:143], v[34:35] op_sel_hi:[1,0,1]
	v_pk_fma_f32 v[36:37], v[98:99], v[142:143], v[36:37] op_sel:[0,1,0]
	v_pk_fma_f32 v[38:39], v[100:101], v[142:143], v[38:39] op_sel:[0,1,0]
	v_pk_fma_f32 v[40:41], v[98:99], v[144:145], v[40:41] op_sel_hi:[1,0,1]
	v_pk_fma_f32 v[42:43], v[100:101], v[144:145], v[42:43] op_sel_hi:[1,0,1]
	v_pk_fma_f32 v[44:45], v[98:99], v[144:145], v[44:45] op_sel:[0,1,0]
	v_pk_fma_f32 v[46:47], v[100:101], v[144:145], v[46:47] op_sel:[0,1,0]
	s_waitcnt lgkmcnt(0)
	v_pk_fma_f32 v[48:49], v[98:99], v[146:147], v[48:49] op_sel_hi:[1,0,1]
	v_pk_fma_f32 v[50:51], v[100:101], v[146:147], v[50:51] op_sel_hi:[1,0,1]
	v_pk_fma_f32 v[52:53], v[98:99], v[146:147], v[52:53] op_sel:[0,1,0]
	v_pk_fma_f32 v[54:55], v[100:101], v[146:147], v[54:55] op_sel:[0,1,0]
	v_pk_fma_f32 v[56:57], v[98:99], v[148:149], v[56:57] op_sel_hi:[1,0,1]
	v_pk_fma_f32 v[58:59], v[100:101], v[148:149], v[58:59] op_sel_hi:[1,0,1]
	v_pk_fma_f32 v[60:61], v[98:99], v[148:149], v[60:61] op_sel:[0,1,0]
	v_pk_fma_f32 v[62:63], v[100:101], v[148:149], v[62:63] op_sel:[0,1,0]
	ds_read_b128 v[142:145], v109 offset:512
	ds_read_b128 v[146:149], v109 offset:528
	ds_read_b128 v[150:153], v109 offset:544
	ds_read_b128 v[154:157], v109 offset:560
	ds_read_b128 v[160:163], v109 offset:576
	s_waitcnt vmcnt(7)
	s_waitcnt lgkmcnt(4)
	v_pk_fma_f32 v[0:1], v[110:111], v[142:143], v[0:1] op_sel_hi:[1,0,1]
	v_pk_fma_f32 v[2:3], v[112:113], v[142:143], v[2:3] op_sel_hi:[1,0,1]
	v_pk_fma_f32 v[4:5], v[110:111], v[142:143], v[4:5] op_sel:[0,1,0]
	v_pk_fma_f32 v[6:7], v[112:113], v[142:143], v[6:7] op_sel:[0,1,0]
	v_pk_fma_f32 v[8:9], v[110:111], v[144:145], v[8:9] op_sel_hi:[1,0,1]
	v_pk_fma_f32 v[10:11], v[112:113], v[144:145], v[10:11] op_sel_hi:[1,0,1]
	v_pk_fma_f32 v[12:13], v[110:111], v[144:145], v[12:13] op_sel:[0,1,0]
	v_pk_fma_f32 v[14:15], v[112:113], v[144:145], v[14:15] op_sel:[0,1,0]
	ds_read_b128 v[164:167], v109 offset:592
	s_waitcnt lgkmcnt(4)
	v_pk_fma_f32 v[16:17], v[110:111], v[146:147], v[16:17] op_sel_hi:[1,0,1]
	v_pk_fma_f32 v[18:19], v[112:113], v[146:147], v[18:19] op_sel_hi:[1,0,1]
	v_pk_fma_f32 v[20:21], v[110:111], v[146:147], v[20:21] op_sel:[0,1,0]
	v_pk_fma_f32 v[22:23], v[112:113], v[146:147], v[22:23] op_sel:[0,1,0]
	v_pk_fma_f32 v[24:25], v[110:111], v[148:149], v[24:25] op_sel_hi:[1,0,1]
	v_pk_fma_f32 v[26:27], v[112:113], v[148:149], v[26:27] op_sel_hi:[1,0,1]
	v_pk_fma_f32 v[28:29], v[110:111], v[148:149], v[28:29] op_sel:[0,1,0]
	v_pk_fma_f32 v[30:31], v[112:113], v[148:149], v[30:31] op_sel:[0,1,0]
	ds_read_b128 v[142:145], v109 offset:608
	s_waitcnt lgkmcnt(4)
	v_pk_fma_f32 v[32:33], v[110:111], v[150:151], v[32:33] op_sel_hi:[1,0,1]
	v_pk_fma_f32 v[34:35], v[112:113], v[150:151], v[34:35] op_sel_hi:[1,0,1]
	v_pk_fma_f32 v[36:37], v[110:111], v[150:151], v[36:37] op_sel:[0,1,0]
	v_pk_fma_f32 v[38:39], v[112:113], v[150:151], v[38:39] op_sel:[0,1,0]
	v_pk_fma_f32 v[40:41], v[110:111], v[152:153], v[40:41] op_sel_hi:[1,0,1]
	v_pk_fma_f32 v[42:43], v[112:113], v[152:153], v[42:43] op_sel_hi:[1,0,1]
	v_pk_fma_f32 v[44:45], v[110:111], v[152:153], v[44:45] op_sel:[0,1,0]
	v_pk_fma_f32 v[46:47], v[112:113], v[152:153], v[46:47] op_sel:[0,1,0]
	ds_read_b128 v[146:149], v109 offset:624
	s_waitcnt lgkmcnt(4)
	v_pk_fma_f32 v[48:49], v[110:111], v[154:155], v[48:49] op_sel_hi:[1,0,1]
	v_pk_fma_f32 v[50:51], v[112:113], v[154:155], v[50:51] op_sel_hi:[1,0,1]
	v_pk_fma_f32 v[52:53], v[110:111], v[154:155], v[52:53] op_sel:[0,1,0]
	v_pk_fma_f32 v[54:55], v[112:113], v[154:155], v[54:55] op_sel:[0,1,0]
	v_pk_fma_f32 v[56:57], v[110:111], v[156:157], v[56:57] op_sel_hi:[1,0,1]
	v_pk_fma_f32 v[58:59], v[112:113], v[156:157], v[58:59] op_sel_hi:[1,0,1]
	v_pk_fma_f32 v[60:61], v[110:111], v[156:157], v[60:61] op_sel:[0,1,0]
	v_pk_fma_f32 v[62:63], v[112:113], v[156:157], v[62:63] op_sel:[0,1,0]
	ds_read_b128 v[150:153], v109 offset:640
	s_waitcnt vmcnt(6)
	s_waitcnt lgkmcnt(4)
	v_pk_fma_f32 v[0:1], v[114:115], v[160:161], v[0:1] op_sel_hi:[1,0,1]
	v_pk_fma_f32 v[2:3], v[116:117], v[160:161], v[2:3] op_sel_hi:[1,0,1]
	v_pk_fma_f32 v[4:5], v[114:115], v[160:161], v[4:5] op_sel:[0,1,0]
	v_pk_fma_f32 v[6:7], v[116:117], v[160:161], v[6:7] op_sel:[0,1,0]
	v_pk_fma_f32 v[8:9], v[114:115], v[162:163], v[8:9] op_sel_hi:[1,0,1]
	v_pk_fma_f32 v[10:11], v[116:117], v[162:163], v[10:11] op_sel_hi:[1,0,1]
	v_pk_fma_f32 v[12:13], v[114:115], v[162:163], v[12:13] op_sel:[0,1,0]
	v_pk_fma_f32 v[14:15], v[116:117], v[162:163], v[14:15] op_sel:[0,1,0]
	ds_read_b128 v[154:157], v109 offset:656
	s_waitcnt lgkmcnt(4)
	v_pk_fma_f32 v[16:17], v[114:115], v[164:165], v[16:17] op_sel_hi:[1,0,1]
	v_pk_fma_f32 v[18:19], v[116:117], v[164:165], v[18:19] op_sel_hi:[1,0,1]
	v_pk_fma_f32 v[20:21], v[114:115], v[164:165], v[20:21] op_sel:[0,1,0]
	v_pk_fma_f32 v[22:23], v[116:117], v[164:165], v[22:23] op_sel:[0,1,0]
	v_pk_fma_f32 v[24:25], v[114:115], v[166:167], v[24:25] op_sel_hi:[1,0,1]
	v_pk_fma_f32 v[26:27], v[116:117], v[166:167], v[26:27] op_sel_hi:[1,0,1]
	v_pk_fma_f32 v[28:29], v[114:115], v[166:167], v[28:29] op_sel:[0,1,0]
	v_pk_fma_f32 v[30:31], v[116:117], v[166:167], v[30:31] op_sel:[0,1,0]
	ds_read_b128 v[160:163], v109 offset:672
	s_waitcnt lgkmcnt(4)
; DI void ada_item(const KP& p, int item, float* lds) {
;     ...
;     for (int u = 0; u < 16; ++u) { const f32x4 w = wv[u]; const f32x4* sp = (const f32x4*)(lds + (d0 + dd0 + u) * 16);
; #pragma unroll
;       for (int q = 0; q < 4; ++q) { const f32x4 s = sp[q];
;         acc[4 * q + 0] += w * s[0]; acc[4 * q + 1] += w * s[1]; acc[4 * q + 2] += w * s[2]; acc[4 * q + 3] += w * s[3]; } } }
	v_pk_fma_f32 v[32:33], v[114:115], v[142:143], v[32:33] op_sel_hi:[1,0,1]
	v_pk_fma_f32 v[34:35], v[116:117], v[142:143], v[34:35] op_sel_hi:[1,0,1]
	v_pk_fma_f32 v[36:37], v[114:115], v[142:143], v[36:37] op_sel:[0,1,0]
	v_pk_fma_f32 v[38:39], v[116:117], v[142:143], v[38:39] op_sel:[0,1,0]
	v_pk_fma_f32 v[40:41], v[114:115], v[144:145], v[40:41] op_sel_hi:[1,0,1]
	v_pk_fma_f32 v[42:43], v[116:117], v[144:145], v[42:43] op_sel_hi:[1,0,1]
	v_pk_fma_f32 v[44:45], v[114:115], v[144:145], v[44:45] op_sel:[0,1,0]
	v_pk_fma_f32 v[46:47], v[116:117], v[144:145], v[46:47] op_sel:[0,1,0]
	ds_read_b128 v[164:167], v109 offset:688
	s_waitcnt lgkmcnt(4)
	v_pk_fma_f32 v[48:49], v[114:115], v[146:147], v[48:49] op_sel_hi:[1,0,1]
	v_pk_fma_f32 v[50:51], v[116:117], v[146:147], v[50:51] op_sel_hi:[1,0,1]
	v_pk_fma_f32 v[52:53], v[114:115], v[146:147], v[52:53] op_sel:[0,1,0]
	v_pk_fma_f32 v[54:55], v[116:117], v[146:147], v[54:55] op_sel:[0,1,0]
	v_pk_fma_f32 v[56:57], v[114:115], v[148:149], v[56:57] op_sel_hi:[1,0,1]
	v_pk_fma_f32 v[58:59], v[116:117], v[148:149], v[58:59] op_sel_hi:[1,0,1]
	v_pk_fma_f32 v[60:61], v[114:115], v[148:149], v[60:61] op_sel:[0,1,0]
	v_pk_fma_f32 v[62:63], v[116:117], v[148:149], v[62:63] op_sel:[0,1,0]
	ds_read_b128 v[142:145], v109 offset:704
	s_waitcnt vmcnt(5)
	s_waitcnt lgkmcnt(4)
	v_pk_fma_f32 v[0:1], v[118:119], v[150:151], v[0:1] op_sel_hi:[1,0,1]
	v_pk_fma_f32 v[2:3], v[120:121], v[150:151], v[2:3] op_sel_hi:[1,0,1]
	v_pk_fma_f32 v[4:5], v[118:119], v[150:151], v[4:5] op_sel:[0,1,0]
	v_pk_fma_f32 v[6:7], v[120:121], v[150:151], v[6:7] op_sel:[0,1,0]
	v_pk_fma_f32 v[8:9], v[118:119], v[152:153], v[8:9] op_sel_hi:[1,0,1]
	v_pk_fma_f32 v[10:11], v[120:121], v[152:153], v[10:11] op_sel_hi:[1,0,1]
	v_pk_fma_f32 v[12:13], v[118:119], v[152:153], v[12:13] op_sel:[0,1,0]
	v_pk_fma_f32 v[14:15], v[120:121], v[152:153], v[14:15] op_sel:[0,1,0]
	ds_read_b128 v[146:149], v109 offset:720
	s_waitcnt lgkmcnt(4)
	v_pk_fma_f32 v[16:17], v[118:119], v[154:155], v[16:17] op_sel_hi:[1,0,1]
	v_pk_fma_f32 v[18:19], v[120:121], v[154:155], v[18:19] op_sel_hi:[1,0,1]
	v_pk_fma_f32 v[20:21], v[118:119], v[154:155], v[20:21] op_sel:[0,1,0]
	v_pk_fma_f32 v[22:23], v[120:121], v[154:155], v[22:23] op_sel:[0,1,0]
	v_pk_fma_f32 v[24:25], v[118:119], v[156:157], v[24:25] op_sel_hi:[1,0,1]
	v_pk_fma_f32 v[26:27], v[120:121], v[156:157], v[26:27] op_sel_hi:[1,0,1]
	v_pk_fma_f32 v[28:29], v[118:119], v[156:157], v[28:29] op_sel:[0,1,0]
	v_pk_fma_f32 v[30:31], v[120:121], v[156:157], v[30:31] op_sel:[0,1,0]
	ds_read_b128 v[150:153], v109 offset:736
	s_waitcnt lgkmcnt(4)
	v_pk_fma_f32 v[32:33], v[118:119], v[160:161], v[32:33] op_sel_hi:[1,0,1]
	v_pk_fma_f32 v[34:35], v[120:121], v[160:161], v[34:35] op_sel_hi:[1,0,1]
	v_pk_fma_f32 v[36:37], v[118:119], v[160:161], v[36:37] op_sel:[0,1,0]
	v_pk_fma_f32 v[38:39], v[120:121], v[160:161], v[38:39] op_sel:[0,1,0]
	v_pk_fma_f32 v[40:41], v[118:119], v[162:163], v[40:41] op_sel_hi:[1,0,1]
	v_pk_fma_f32 v[42:43], v[120:121], v[162:163], v[42:43] op_sel_hi:[1,0,1]
	v_pk_fma_f32 v[44:45], v[118:119], v[162:163], v[44:45] op_sel:[0,1,0]
	v_pk_fma_f32 v[46:47], v[120:121], v[162:163], v[46:47] op_sel:[0,1,0]
	ds_read_b128 v[154:157], v109 offset:752
	s_waitcnt lgkmcnt(4)
	v_pk_fma_f32 v[48:49], v[118:119], v[164:165], v[48:49] op_sel_hi:[1,0,1]
	v_pk_fma_f32 v[50:51], v[120:121], v[164:165], v[50:51] op_sel_hi:[1,0,1]
	v_pk_fma_f32 v[52:53], v[118:119], v[164:165], v[52:53] op_sel:[0,1,0]
	v_pk_fma_f32 v[54:55], v[120:121], v[164:165], v[54:55] op_sel:[0,1,0]
	v_pk_fma_f32 v[56:57], v[118:119], v[166:167], v[56:57] op_sel_hi:[1,0,1]
	v_pk_fma_f32 v[58:59], v[120:121], v[166:167], v[58:59] op_sel_hi:[1,0,1]
	v_pk_fma_f32 v[60:61], v[118:119], v[166:167], v[60:61] op_sel:[0,1,0]
	v_pk_fma_f32 v[62:63], v[120:121], v[166:167], v[62:63] op_sel:[0,1,0]
	ds_read_b128 v[160:163], v109 offset:768
	s_waitcnt vmcnt(4)
	s_waitcnt lgkmcnt(4)
	v_pk_fma_f32 v[0:1], v[122:123], v[142:143], v[0:1] op_sel_hi:[1,0,1]
	v_pk_fma_f32 v[2:3], v[124:125], v[142:143], v[2:3] op_sel_hi:[1,0,1]
	v_pk_fma_f32 v[4:5], v[122:123], v[142:143], v[4:5] op_sel:[0,1,0]
	v_pk_fma_f32 v[6:7], v[124:125], v[142:143], v[6:7] op_sel:[0,1,0]
	v_pk_fma_f32 v[8:9], v[122:123], v[144:145], v[8:9] op_sel_hi:[1,0,1]
	v_pk_fma_f32 v[10:11], v[124:125], v[144:145], v[10:11] op_sel_hi:[1,0,1]
	v_pk_fma_f32 v[12:13], v[122:123], v[144:145], v[12:13] op_sel:[0,1,0]
	v_pk_fma_f32 v[14:15], v[124:125], v[144:145], v[14:15] op_sel:[0,1,0]
	ds_read_b128 v[164:167], v109 offset:784
	s_waitcnt lgkmcnt(4)
	v_pk_fma_f32 v[16:17], v[122:123], v[146:147], v[16:17] op_sel_hi:[1,0,1]
	v_pk_fma_f32 v[18:19], v[124:125], v[146:147], v[18:19] op_sel_hi:[1,0,1]
	v_pk_fma_f32 v[20:21], v[122:123], v[146:147], v[20:21] op_sel:[0,1,0]
	v_pk_fma_f32 v[22:23], v[124:125], v[146:147], v[22:23] op_sel:[0,1,0]
	v_pk_fma_f32 v[24:25], v[122:123], v[148:149], v[24:25] op_sel_hi:[1,0,1]
	v_pk_fma_f32 v[26:27], v[124:125], v[148:149], v[26:27] op_sel_hi:[1,0,1]
	v_pk_fma_f32 v[28:29], v[122:123], v[148:149], v[28:29] op_sel:[0,1,0]
	v_pk_fma_f32 v[30:31], v[124:125], v[148:149], v[30:31] op_sel:[0,1,0]
	ds_read_b128 v[142:145], v109 offset:800
	s_waitcnt lgkmcnt(4)
	v_pk_fma_f32 v[32:33], v[122:123], v[150:151], v[32:33] op_sel_hi:[1,0,1]
	v_pk_fma_f32 v[34:35], v[124:125], v[150:151], v[34:35] op_sel_hi:[1,0,1]
	v_pk_fma_f32 v[36:37], v[122:123], v[150:151], v[36:37] op_sel:[0,1,0]
	v_pk_fma_f32 v[38:39], v[124:125], v[150:151], v[38:39] op_sel:[0,1,0]
	v_pk_fma_f32 v[40:41], v[122:123], v[152:153], v[40:41] op_sel_hi:[1,0,1]
	v_pk_fma_f32 v[42:43], v[124:125], v[152:153], v[42:43] op_sel_hi:[1,0,1]
	v_pk_fma_f32 v[44:45], v[122:123], v[152:153], v[44:45] op_sel:[0,1,0]
	v_pk_fma_f32 v[46:47], v[124:125], v[152:153], v[46:47] op_sel:[0,1,0]
	ds_read_b128 v[146:149], v109 offset:816
	s_waitcnt lgkmcnt(4)
; DI void ada_item(const KP& p, int item, float* lds) {
;     ...
;   for (int dd0 = 0; dd0 < 64; dd0 += 16) {
;     f32x4 wv[16];
; #pragma unroll
;     for (int u = 0; u < 16; ++u) wv[u] = *(const f32x4*)(W + (size_t)(d0 + dd0 + u) * 6144 + e0 + cq * 4);
; #pragma unroll
;     for (int u = 0; u < 16; ++u) { const f32x4 w = wv[u]; const f32x4* sp = (const f32x4*)(lds + (d0 + dd0 + u) * 16);
; #pragma unroll
;       for (int q = 0; q < 4; ++q) { const f32x4 s = sp[q];
;         acc[4 * q + 0] += w * s[0]; acc[4 * q + 1] += w * s[1]; acc[4 * q + 2] += w * s[2]; acc[4 * q + 3] += w * s[3]; } } }
	v_pk_fma_f32 v[48:49], v[122:123], v[154:155], v[48:49] op_sel_hi:[1,0,1]
	v_pk_fma_f32 v[50:51], v[124:125], v[154:155], v[50:51] op_sel_hi:[1,0,1]
	v_pk_fma_f32 v[52:53], v[122:123], v[154:155], v[52:53] op_sel:[0,1,0]
	v_pk_fma_f32 v[54:55], v[124:125], v[154:155], v[54:55] op_sel:[0,1,0]
	v_pk_fma_f32 v[56:57], v[122:123], v[156:157], v[56:57] op_sel_hi:[1,0,1]
	v_pk_fma_f32 v[58:59], v[124:125], v[156:157], v[58:59] op_sel_hi:[1,0,1]
	v_pk_fma_f32 v[60:61], v[122:123], v[156:157], v[60:61] op_sel:[0,1,0]
	v_pk_fma_f32 v[62:63], v[124:125], v[156:157], v[62:63] op_sel:[0,1,0]
	ds_read_b128 v[150:153], v109 offset:832
	s_waitcnt vmcnt(3)
	s_waitcnt lgkmcnt(4)
	v_pk_fma_f32 v[0:1], v[126:127], v[160:161], v[0:1] op_sel_hi:[1,0,1]
	v_pk_fma_f32 v[2:3], v[128:129], v[160:161], v[2:3] op_sel_hi:[1,0,1]
	v_pk_fma_f32 v[4:5], v[126:127], v[160:161], v[4:5] op_sel:[0,1,0]
	v_pk_fma_f32 v[6:7], v[128:129], v[160:161], v[6:7] op_sel:[0,1,0]
	v_pk_fma_f32 v[8:9], v[126:127], v[162:163], v[8:9] op_sel_hi:[1,0,1]
	v_pk_fma_f32 v[10:11], v[128:129], v[162:163], v[10:11] op_sel_hi:[1,0,1]
	v_pk_fma_f32 v[12:13], v[126:127], v[162:163], v[12:13] op_sel:[0,1,0]
	v_pk_fma_f32 v[14:15], v[128:129], v[162:163], v[14:15] op_sel:[0,1,0]
	ds_read_b128 v[154:157], v109 offset:848
	s_waitcnt lgkmcnt(4)
	v_pk_fma_f32 v[16:17], v[126:127], v[164:165], v[16:17] op_sel_hi:[1,0,1]
	v_pk_fma_f32 v[18:19], v[128:129], v[164:165], v[18:19] op_sel_hi:[1,0,1]
	v_pk_fma_f32 v[20:21], v[126:127], v[164:165], v[20:21] op_sel:[0,1,0]
	v_pk_fma_f32 v[22:23], v[128:129], v[164:165], v[22:23] op_sel:[0,1,0]
	v_pk_fma_f32 v[24:25], v[126:127], v[166:167], v[24:25] op_sel_hi:[1,0,1]
	v_pk_fma_f32 v[26:27], v[128:129], v[166:167], v[26:27] op_sel_hi:[1,0,1]
	v_pk_fma_f32 v[28:29], v[126:127], v[166:167], v[28:29] op_sel:[0,1,0]
	v_pk_fma_f32 v[30:31], v[128:129], v[166:167], v[30:31] op_sel:[0,1,0]
	ds_read_b128 v[160:163], v109 offset:864
	s_waitcnt lgkmcnt(4)
	v_pk_fma_f32 v[32:33], v[126:127], v[142:143], v[32:33] op_sel_hi:[1,0,1]
	v_pk_fma_f32 v[34:35], v[128:129], v[142:143], v[34:35] op_sel_hi:[1,0,1]
	v_pk_fma_f32 v[36:37], v[126:127], v[142:143], v[36:37] op_sel:[0,1,0]
	v_pk_fma_f32 v[38:39], v[128:129], v[142:143], v[38:39] op_sel:[0,1,0]
	v_pk_fma_f32 v[40:41], v[126:127], v[144:145], v[40:41] op_sel_hi:[1,0,1]
	v_pk_fma_f32 v[42:43], v[128:129], v[144:145], v[42:43] op_sel_hi:[1,0,1]
	v_pk_fma_f32 v[44:45], v[126:127], v[144:145], v[44:45] op_sel:[0,1,0]
	v_pk_fma_f32 v[46:47], v[128:129], v[144:145], v[46:47] op_sel:[0,1,0]
	ds_read_b128 v[164:167], v109 offset:880
	s_waitcnt lgkmcnt(4)
	v_pk_fma_f32 v[48:49], v[126:127], v[146:147], v[48:49] op_sel_hi:[1,0,1]
	v_pk_fma_f32 v[50:51], v[128:129], v[146:147], v[50:51] op_sel_hi:[1,0,1]
	v_pk_fma_f32 v[52:53], v[126:127], v[146:147], v[52:53] op_sel:[0,1,0]
	v_pk_fma_f32 v[54:55], v[128:129], v[146:147], v[54:55] op_sel:[0,1,0]
	v_pk_fma_f32 v[56:57], v[126:127], v[148:149], v[56:57] op_sel_hi:[1,0,1]
	v_pk_fma_f32 v[58:59], v[128:129], v[148:149], v[58:59] op_sel_hi:[1,0,1]
	v_pk_fma_f32 v[60:61], v[126:127], v[148:149], v[60:61] op_sel:[0,1,0]
	v_pk_fma_f32 v[62:63], v[128:129], v[148:149], v[62:63] op_sel:[0,1,0]
	ds_read_b128 v[142:145], v109 offset:896
	s_waitcnt vmcnt(2)
	s_waitcnt lgkmcnt(4)
	v_pk_fma_f32 v[0:1], v[130:131], v[150:151], v[0:1] op_sel_hi:[1,0,1]
	v_pk_fma_f32 v[2:3], v[132:133], v[150:151], v[2:3] op_sel_hi:[1,0,1]
	v_pk_fma_f32 v[4:5], v[130:131], v[150:151], v[4:5] op_sel:[0,1,0]
	v_pk_fma_f32 v[6:7], v[132:133], v[150:151], v[6:7] op_sel:[0,1,0]
	v_pk_fma_f32 v[8:9], v[130:131], v[152:153], v[8:9] op_sel_hi:[1,0,1]
	v_pk_fma_f32 v[10:11], v[132:133], v[152:153], v[10:11] op_sel_hi:[1,0,1]
	v_pk_fma_f32 v[12:13], v[130:131], v[152:153], v[12:13] op_sel:[0,1,0]
	v_pk_fma_f32 v[14:15], v[132:133], v[152:153], v[14:15] op_sel:[0,1,0]
	ds_read_b128 v[146:149], v109 offset:912
	s_waitcnt lgkmcnt(4)
	v_pk_fma_f32 v[16:17], v[130:131], v[154:155], v[16:17] op_sel_hi:[1,0,1]
	v_pk_fma_f32 v[18:19], v[132:133], v[154:155], v[18:19] op_sel_hi:[1,0,1]
	v_pk_fma_f32 v[20:21], v[130:131], v[154:155], v[20:21] op_sel:[0,1,0]
	v_pk_fma_f32 v[22:23], v[132:133], v[154:155], v[22:23] op_sel:[0,1,0]
	v_pk_fma_f32 v[24:25], v[130:131], v[156:157], v[24:25] op_sel_hi:[1,0,1]
	v_pk_fma_f32 v[26:27], v[132:133], v[156:157], v[26:27] op_sel_hi:[1,0,1]
	v_pk_fma_f32 v[28:29], v[130:131], v[156:157], v[28:29] op_sel:[0,1,0]
	v_pk_fma_f32 v[30:31], v[132:133], v[156:157], v[30:31] op_sel:[0,1,0]
	ds_read_b128 v[150:153], v109 offset:928
	s_waitcnt lgkmcnt(4)
	v_pk_fma_f32 v[32:33], v[130:131], v[160:161], v[32:33] op_sel_hi:[1,0,1]
	v_pk_fma_f32 v[34:35], v[132:133], v[160:161], v[34:35] op_sel_hi:[1,0,1]
	v_pk_fma_f32 v[36:37], v[130:131], v[160:161], v[36:37] op_sel:[0,1,0]
	v_pk_fma_f32 v[38:39], v[132:133], v[160:161], v[38:39] op_sel:[0,1,0]
	v_pk_fma_f32 v[40:41], v[130:131], v[162:163], v[40:41] op_sel_hi:[1,0,1]
	v_pk_fma_f32 v[42:43], v[132:133], v[162:163], v[42:43] op_sel_hi:[1,0,1]
	v_pk_fma_f32 v[44:45], v[130:131], v[162:163], v[44:45] op_sel:[0,1,0]
	v_pk_fma_f32 v[46:47], v[132:133], v[162:163], v[46:47] op_sel:[0,1,0]
	ds_read_b128 v[154:157], v109 offset:944
	s_waitcnt lgkmcnt(4)
	v_pk_fma_f32 v[48:49], v[130:131], v[164:165], v[48:49] op_sel_hi:[1,0,1]
	v_pk_fma_f32 v[50:51], v[132:133], v[164:165], v[50:51] op_sel_hi:[1,0,1]
	v_pk_fma_f32 v[52:53], v[130:131], v[164:165], v[52:53] op_sel:[0,1,0]
	v_pk_fma_f32 v[54:55], v[132:133], v[164:165], v[54:55] op_sel:[0,1,0]
	v_pk_fma_f32 v[56:57], v[130:131], v[166:167], v[56:57] op_sel_hi:[1,0,1]
	v_pk_fma_f32 v[58:59], v[132:133], v[166:167], v[58:59] op_sel_hi:[1,0,1]
	v_pk_fma_f32 v[60:61], v[130:131], v[166:167], v[60:61] op_sel:[0,1,0]
	v_pk_fma_f32 v[62:63], v[132:133], v[166:167], v[62:63] op_sel:[0,1,0]
	ds_read_b128 v[160:163], v109 offset:960
	s_waitcnt vmcnt(1)
; DI void ada_item(const KP& p, int item, float* lds) {
;     ...
;   for (int dd0 = 0; dd0 < 64; dd0 += 16) {
;     f32x4 wv[16];
; #pragma unroll
;     for (int u = 0; u < 16; ++u) wv[u] = *(const f32x4*)(W + (size_t)(d0 + dd0 + u) * 6144 + e0 + cq * 4);
; #pragma unroll
;     for (int u = 0; u < 16; ++u) { const f32x4 w = wv[u]; const f32x4* sp = (const f32x4*)(lds + (d0 + dd0 + u) * 16);
; #pragma unroll
;       for (int q = 0; q < 4; ++q) { const f32x4 s = sp[q];
;         acc[4 * q + 0] += w * s[0]; acc[4 * q + 1] += w * s[1]; acc[4 * q + 2] += w * s[2]; acc[4 * q + 3] += w * s[3]; } } }
;   __syncthreads();
; #pragma unroll
;   for (int b = 0; b < 16; ++b) *(f32x4*)(lds + (dg * 16 + b) * 64 + cq * 4) = acc[b];
;   __syncthreads();
;   for (int o = tid; o < 1024; o += 512) { const int b = o >> 6, col = o & 63; float s = 0.f;
;     for (int g = 0; g < 32; ++g) s += lds[(g * 16 + b) * 64 + col];
;     mods[(size_t)b * 6144 + e0 + col] = s + bias[e0 + col]; }
	s_waitcnt lgkmcnt(4)
	v_pk_fma_f32 v[0:1], v[134:135], v[142:143], v[0:1] op_sel_hi:[1,0,1]
	v_pk_fma_f32 v[2:3], v[136:137], v[142:143], v[2:3] op_sel_hi:[1,0,1]
	v_pk_fma_f32 v[4:5], v[134:135], v[142:143], v[4:5] op_sel:[0,1,0]
	v_pk_fma_f32 v[6:7], v[136:137], v[142:143], v[6:7] op_sel:[0,1,0]
	v_pk_fma_f32 v[8:9], v[134:135], v[144:145], v[8:9] op_sel_hi:[1,0,1]
	v_pk_fma_f32 v[10:11], v[136:137], v[144:145], v[10:11] op_sel_hi:[1,0,1]
	v_pk_fma_f32 v[12:13], v[134:135], v[144:145], v[12:13] op_sel:[0,1,0]
	v_pk_fma_f32 v[14:15], v[136:137], v[144:145], v[14:15] op_sel:[0,1,0]
	ds_read_b128 v[164:167], v109 offset:976
	s_waitcnt lgkmcnt(4)
	v_pk_fma_f32 v[16:17], v[134:135], v[146:147], v[16:17] op_sel_hi:[1,0,1]
	v_pk_fma_f32 v[18:19], v[136:137], v[146:147], v[18:19] op_sel_hi:[1,0,1]
	v_pk_fma_f32 v[20:21], v[134:135], v[146:147], v[20:21] op_sel:[0,1,0]
	v_pk_fma_f32 v[22:23], v[136:137], v[146:147], v[22:23] op_sel:[0,1,0]
	v_pk_fma_f32 v[24:25], v[134:135], v[148:149], v[24:25] op_sel_hi:[1,0,1]
	v_pk_fma_f32 v[26:27], v[136:137], v[148:149], v[26:27] op_sel_hi:[1,0,1]
	v_pk_fma_f32 v[28:29], v[134:135], v[148:149], v[28:29] op_sel:[0,1,0]
	v_pk_fma_f32 v[30:31], v[136:137], v[148:149], v[30:31] op_sel:[0,1,0]
	ds_read_b128 v[142:145], v109 offset:992
	s_waitcnt lgkmcnt(4)
	v_pk_fma_f32 v[32:33], v[134:135], v[150:151], v[32:33] op_sel_hi:[1,0,1]
	v_pk_fma_f32 v[34:35], v[136:137], v[150:151], v[34:35] op_sel_hi:[1,0,1]
	v_pk_fma_f32 v[36:37], v[134:135], v[150:151], v[36:37] op_sel:[0,1,0]
	v_pk_fma_f32 v[38:39], v[136:137], v[150:151], v[38:39] op_sel:[0,1,0]
	v_pk_fma_f32 v[40:41], v[134:135], v[152:153], v[40:41] op_sel_hi:[1,0,1]
	v_pk_fma_f32 v[42:43], v[136:137], v[152:153], v[42:43] op_sel_hi:[1,0,1]
	v_pk_fma_f32 v[44:45], v[134:135], v[152:153], v[44:45] op_sel:[0,1,0]
	v_pk_fma_f32 v[46:47], v[136:137], v[152:153], v[46:47] op_sel:[0,1,0]
	ds_read_b128 v[146:149], v109 offset:1008
	s_waitcnt lgkmcnt(4)
	v_pk_fma_f32 v[48:49], v[134:135], v[154:155], v[48:49] op_sel_hi:[1,0,1]
	v_pk_fma_f32 v[50:51], v[136:137], v[154:155], v[50:51] op_sel_hi:[1,0,1]
	v_pk_fma_f32 v[52:53], v[134:135], v[154:155], v[52:53] op_sel:[0,1,0]
	v_pk_fma_f32 v[54:55], v[136:137], v[154:155], v[54:55] op_sel:[0,1,0]
	v_pk_fma_f32 v[56:57], v[134:135], v[156:157], v[56:57] op_sel_hi:[1,0,1]
	v_pk_fma_f32 v[58:59], v[136:137], v[156:157], v[58:59] op_sel_hi:[1,0,1]
	v_pk_fma_f32 v[60:61], v[134:135], v[156:157], v[60:61] op_sel:[0,1,0]
	v_pk_fma_f32 v[62:63], v[136:137], v[156:157], v[62:63] op_sel:[0,1,0]
	s_waitcnt vmcnt(0)
	s_waitcnt lgkmcnt(3)
	v_pk_fma_f32 v[0:1], v[138:139], v[160:161], v[0:1] op_sel_hi:[1,0,1]
	v_pk_fma_f32 v[2:3], v[140:141], v[160:161], v[2:3] op_sel_hi:[1,0,1]
	v_pk_fma_f32 v[4:5], v[138:139], v[160:161], v[4:5] op_sel:[0,1,0]
	v_pk_fma_f32 v[6:7], v[140:141], v[160:161], v[6:7] op_sel:[0,1,0]
	v_pk_fma_f32 v[8:9], v[138:139], v[162:163], v[8:9] op_sel_hi:[1,0,1]
	v_pk_fma_f32 v[10:11], v[140:141], v[162:163], v[10:11] op_sel_hi:[1,0,1]
	v_pk_fma_f32 v[12:13], v[138:139], v[162:163], v[12:13] op_sel:[0,1,0]
	v_pk_fma_f32 v[14:15], v[140:141], v[162:163], v[14:15] op_sel:[0,1,0]
	s_waitcnt lgkmcnt(2)
	v_pk_fma_f32 v[16:17], v[138:139], v[164:165], v[16:17] op_sel_hi:[1,0,1]
	v_pk_fma_f32 v[18:19], v[140:141], v[164:165], v[18:19] op_sel_hi:[1,0,1]
	v_pk_fma_f32 v[20:21], v[138:139], v[164:165], v[20:21] op_sel:[0,1,0]
	v_pk_fma_f32 v[22:23], v[140:141], v[164:165], v[22:23] op_sel:[0,1,0]
	v_pk_fma_f32 v[24:25], v[138:139], v[166:167], v[24:25] op_sel_hi:[1,0,1]
	v_pk_fma_f32 v[26:27], v[140:141], v[166:167], v[26:27] op_sel_hi:[1,0,1]
	v_pk_fma_f32 v[28:29], v[138:139], v[166:167], v[28:29] op_sel:[0,1,0]
	v_pk_fma_f32 v[30:31], v[140:141], v[166:167], v[30:31] op_sel:[0,1,0]
	s_waitcnt lgkmcnt(1)
	v_pk_fma_f32 v[32:33], v[138:139], v[142:143], v[32:33] op_sel_hi:[1,0,1]
	v_pk_fma_f32 v[34:35], v[140:141], v[142:143], v[34:35] op_sel_hi:[1,0,1]
	v_pk_fma_f32 v[36:37], v[138:139], v[142:143], v[36:37] op_sel:[0,1,0]
	v_pk_fma_f32 v[38:39], v[140:141], v[142:143], v[38:39] op_sel:[0,1,0]
	v_pk_fma_f32 v[40:41], v[138:139], v[144:145], v[40:41] op_sel_hi:[1,0,1]
	v_pk_fma_f32 v[42:43], v[140:141], v[144:145], v[42:43] op_sel_hi:[1,0,1]
	v_pk_fma_f32 v[44:45], v[138:139], v[144:145], v[44:45] op_sel:[0,1,0]
	v_pk_fma_f32 v[46:47], v[140:141], v[144:145], v[46:47] op_sel:[0,1,0]
	s_waitcnt lgkmcnt(0)
	v_pk_fma_f32 v[48:49], v[138:139], v[146:147], v[48:49] op_sel_hi:[1,0,1]
	v_pk_fma_f32 v[50:51], v[140:141], v[146:147], v[50:51] op_sel_hi:[1,0,1]
	v_pk_fma_f32 v[52:53], v[138:139], v[146:147], v[52:53] op_sel:[0,1,0]
	v_pk_fma_f32 v[54:55], v[140:141], v[146:147], v[54:55] op_sel:[0,1,0]
	v_pk_fma_f32 v[56:57], v[138:139], v[148:149], v[56:57] op_sel_hi:[1,0,1]
	v_pk_fma_f32 v[58:59], v[140:141], v[148:149], v[58:59] op_sel_hi:[1,0,1]
	v_pk_fma_f32 v[60:61], v[138:139], v[148:149], v[60:61] op_sel:[0,1,0]
	v_pk_fma_f32 v[62:63], v[140:141], v[148:149], v[62:63] op_sel:[0,1,0]
	v_lshl_add_u32 v64, v108, 4, 32
	v_add_u32_e32 v65, v64, v107
	s_barrier
	ds_write_b128 v65, v[0:3]
	ds_write_b128 v65, v[4:7] offset:256
	ds_write_b128 v65, v[8:11] offset:512
	ds_write_b128 v65, v[12:15] offset:768
	ds_write_b128 v65, v[16:19] offset:1024
	ds_write_b128 v65, v[20:23] offset:1280
	ds_write_b128 v65, v[24:27] offset:1536
	ds_write_b128 v65, v[28:31] offset:1792
	ds_write_b128 v65, v[32:35] offset:2048
	ds_write_b128 v65, v[36:39] offset:2304
	ds_write_b128 v65, v[40:43] offset:2560
	ds_write_b128 v65, v[44:47] offset:2816
	ds_write_b128 v65, v[48:51] offset:3072
	ds_write_b128 v65, v[52:55] offset:3328
	ds_write_b128 v65, v[56:59] offset:3584
	v_or_b32_e32 v66, 0xf00, v106
	s_movk_i32 s4, 0x400
	v_add_u32_e32 v66, v64, v66
	v_cmp_gt_i32_e32 vcc, s4, v105
	ds_write_b128 v66, v[60:63]
	s_waitcnt lgkmcnt(0)
	s_barrier
	s_and_saveexec_b64 s[4:5], vcc
	s_movk_i32 s22, 0x6000
	s_movk_i32 s23, 0x1ff
	s_cbranch_execz .LBB0_12
	s_mul_hi_i32 s11, s19, 0x6000
	s_mulk_i32 s19, 0x6000
	s_add_u32 s8, s8, s19
	s_addc_u32 s9, s9, s11
	s_mul_hi_i32 s11, s18, 0x60000
	s_mul_i32 s18, s18, 0x60000
	s_add_u32 s18, s16, s18
	s_addc_u32 s11, s17, s11
	v_and_b32_e32 v0, 63, v105
	s_add_u32 s12, s18, s12
	v_lshlrev_b32_e32 v168, 2, v0
	v_or_b32_e32 v0, s10, v0
	s_addc_u32 s13, s11, s13
	v_ashrrev_i32_e32 v1, 31, v0
	v_add_u32_e32 v4, 32, v168
	v_lshl_add_u64 v[0:1], v[0:1], 2, s[8:9]
	v_lshl_add_u64 v[2:3], s[12:13], 0, v[168:169]
	s_mov_b64 s[8:9], 0

; __global__ void __launch_bounds__(512, 2) fwd_mega(Params p_unused) {
;     ...
;   for (int step = 0; step < 8; ++step) {
.Ltramp_lb8:
	s_branch .LBB0_8
